# finalize phase rewritten: per-wave register double buffer (rows of the next iteration in flight during the reductions), wave sums by permlane32_swap + ds_swizzle, same fp32 math
# speedup vs baseline: 1.3323x; 1.0100x over previous
.LBB0_35:
	s_add_i32 s82, s18, -2
	s_ashr_i32 s80, s82, 2
	s_and_b32 s4, s82, 3
	s_cmp_lt_i32 s4, 2
	s_mov_b64 s[0:1], -1
	s_cbranch_scc1 .LBB0_91
	s_cmp_gt_i32 s4, 2
	s_cbranch_scc0 .LBB0_49
	v_readlane_b32 s0, v253, 32
	v_readlane_b32 s1, v253, 33
	s_andn2_b64 vcc, exec, s[0:1]
	s_cbranch_vccnz .LBB0_48
	s_cmp_eq_u32 s80, 0
	s_cbranch_scc0 .Lfin_l1
	v_and_b32_e32 v0, 63, v151
	v_lshlrev_b32_e32 v173, 5, v0
	v_lshrrev_b32_e32 v0, 6, v151
	v_readlane_b32 s5, v252, 0
	s_nop 0
	v_readfirstlane_b32 s6, v0
	s_lshl_b32 s5, s5, 3
	s_lshl_b32 s6, s6, 1
	s_add_i32 s5, s5, s6
	s_lshl_b32 s6, s5, 12
	s_lshl_b32 s7, s5, 11
	v_readlane_b32 s52, v252, 13
	v_readlane_b32 s53, v252, 14
	v_readlane_b32 s54, v252, 15
	v_readlane_b32 s55, v252, 16
	s_add_u32 s52, s52, s6
	s_addc_u32 s53, s53, 0
	s_add_u32 s54, s54, s6
	s_addc_u32 s55, s55, 0
	s_add_u32 s56, s92, s6
	s_addc_u32 s57, s93, 0
	s_add_u32 s58, s94, s7
	s_addc_u32 s59, s95, 0
	s_add_u32 s60, s94, 0xfc80000
	s_addc_u32 s61, s95, 0
	v_readlane_b32 s62, v252, 35
	v_readlane_b32 s63, v252, 36
	s_nop 4
	global_load_dwordx4 v[130:133], v173, s[62:63] offset:0
	global_load_dwordx4 v[134:137], v173, s[62:63] offset:16
	global_load_dwordx4 v[138:141], v173, s[62:63] offset:2048
	global_load_dwordx4 v[142:145], v173, s[62:63] offset:2064
	v_readlane_b32 s62, v252, 33
	v_readlane_b32 s63, v252, 34
	s_add_u32 s62, s62, 0x1000
	s_addc_u32 s63, s63, 0
	global_load_dwordx4 v[154:157], v173, s[62:63] offset:0
	global_load_dwordx4 v[158:161], v173, s[62:63] offset:16
	global_load_dwordx4 v[162:165], v173, s[62:63] offset:2048
	global_load_dwordx4 v[166:169], v173, s[62:63] offset:2064
	s_add_u32 s38, s52, 0x0
	s_addc_u32 s39, s53, 0
	s_add_u32 s40, s58, 0x3000000
	s_addc_u32 s41, s59, 0
	s_add_u32 s42, s60, 0x2000
	s_addc_u32 s43, s61, 0
	v_lshrrev_b32_e32 v0, 1, v173
	global_load_dwordx4 v[2:5], v0, s[40:41] offset:0
	global_load_dwordx4 v[6:9], v0, s[40:41] offset:1024
	global_load_dwordx4 v[10:13], v0, s[40:41] offset:2048
	global_load_dwordx4 v[14:17], v0, s[40:41] offset:3072
	global_load_dwordx4 v[18:21], v173, s[38:39] offset:0
	global_load_dwordx4 v[22:25], v173, s[38:39] offset:16
	global_load_dwordx4 v[26:29], v173, s[38:39] offset:2048
	global_load_dwordx4 v[30:33], v173, s[38:39] offset:2064
	s_add_u32 s38, s38, 0x1000
	s_addc_u32 s39, s39, 0
	global_load_dwordx4 v[34:37], v173, s[38:39] offset:0
	global_load_dwordx4 v[38:41], v173, s[38:39] offset:16
	global_load_dwordx4 v[42:45], v173, s[38:39] offset:2048
	global_load_dwordx4 v[46:49], v173, s[38:39] offset:2064
	global_load_dwordx4 v[50:53], v173, s[42:43] offset:0
	global_load_dwordx4 v[54:57], v173, s[42:43] offset:16
	global_load_dwordx4 v[58:61], v173, s[42:43] offset:2048
	global_load_dwordx4 v[62:65], v173, s[42:43] offset:2064
	s_add_u32 s0, s60, 0xf000
	s_addc_u32 s1, s61, 0
	global_load_dwordx4 v[234:237], v173, s[0:1] offset:0
	global_load_dwordx4 v[238:241], v173, s[0:1] offset:16
	global_load_dwordx4 v[242:245], v173, s[0:1] offset:2048
	global_load_dwordx4 v[246:249], v173, s[0:1] offset:2064
	s_add_u32 s0, s0, 0x1000
	s_addc_u32 s1, s1, 0
	global_load_dwordx4 v[218:221], v173, s[0:1] offset:0
	global_load_dwordx4 v[222:225], v173, s[0:1] offset:16
	global_load_dwordx4 v[226:229], v173, s[0:1] offset:2048
	global_load_dwordx4 v[230:233], v173, s[0:1] offset:2064
	s_add_u32 s38, s52, 0x1000000
	s_addc_u32 s39, s53, 0
	s_add_u32 s40, s58, 0x3800000
	s_addc_u32 s41, s59, 0
	s_add_u32 s42, s60, 0x2000
	s_addc_u32 s43, s61, 0
	v_lshrrev_b32_e32 v0, 1, v173
	global_load_dwordx4 v[66:69], v0, s[40:41] offset:0
	global_load_dwordx4 v[70:73], v0, s[40:41] offset:1024
	global_load_dwordx4 v[74:77], v0, s[40:41] offset:2048
	global_load_dwordx4 v[78:81], v0, s[40:41] offset:3072
	global_load_dwordx4 v[82:85], v173, s[38:39] offset:0
	global_load_dwordx4 v[86:89], v173, s[38:39] offset:16
	global_load_dwordx4 v[90:93], v173, s[38:39] offset:2048
	global_load_dwordx4 v[94:97], v173, s[38:39] offset:2064
	s_add_u32 s38, s38, 0x1000
	s_addc_u32 s39, s39, 0
	global_load_dwordx4 v[98:101], v173, s[38:39] offset:0
	global_load_dwordx4 v[102:105], v173, s[38:39] offset:16
	global_load_dwordx4 v[106:109], v173, s[38:39] offset:2048
	global_load_dwordx4 v[110:113], v173, s[38:39] offset:2064
	global_load_dwordx4 v[114:117], v173, s[42:43] offset:0
	global_load_dwordx4 v[118:121], v173, s[42:43] offset:16
	global_load_dwordx4 v[122:125], v173, s[42:43] offset:2048
	global_load_dwordx4 v[126:129], v173, s[42:43] offset:2064
	s_waitcnt vmcnt(24)
	v_mul_f32_e32 v50, v50, v130
	v_mul_f32_e32 v51, v51, v131
	v_mul_f32_e32 v52, v52, v132
	v_mul_f32_e32 v53, v53, v133
	v_mul_f32_e32 v54, v54, v134
	v_mul_f32_e32 v55, v55, v135
	v_mul_f32_e32 v56, v56, v136
	v_mul_f32_e32 v57, v57, v137
	v_mul_f32_e32 v58, v58, v138
	v_mul_f32_e32 v59, v59, v139
	v_mul_f32_e32 v60, v60, v140
	v_mul_f32_e32 v61, v61, v141
	v_mul_f32_e32 v62, v62, v142
	v_mul_f32_e32 v63, v63, v143
	v_mul_f32_e32 v64, v64, v144
	v_mul_f32_e32 v65, v65, v145
	v_lshlrev_b32_e32 v0, 16, v2
	v_and_b32_e32 v250, 0xffff0000, v2
	v_mul_f32_e32 v171, v0, v0
	v_fmac_f32_e32 v171, v250, v250
	v_lshlrev_b32_e32 v0, 16, v3
	v_and_b32_e32 v250, 0xffff0000, v3
	v_fmac_f32_e32 v171, v0, v0
	v_fmac_f32_e32 v171, v250, v250
	v_lshlrev_b32_e32 v0, 16, v4
	v_and_b32_e32 v250, 0xffff0000, v4
	v_fmac_f32_e32 v171, v0, v0
	v_fmac_f32_e32 v171, v250, v250
	v_lshlrev_b32_e32 v0, 16, v5
	v_and_b32_e32 v250, 0xffff0000, v5
	v_fmac_f32_e32 v171, v0, v0
	v_fmac_f32_e32 v171, v250, v250
	v_lshlrev_b32_e32 v0, 16, v6
	v_and_b32_e32 v250, 0xffff0000, v6
	v_fmac_f32_e32 v171, v0, v0
	v_fmac_f32_e32 v171, v250, v250
	v_lshlrev_b32_e32 v0, 16, v7
	v_and_b32_e32 v250, 0xffff0000, v7
	v_fmac_f32_e32 v171, v0, v0
	v_fmac_f32_e32 v171, v250, v250
	v_lshlrev_b32_e32 v0, 16, v8
	v_and_b32_e32 v250, 0xffff0000, v8
	v_fmac_f32_e32 v171, v0, v0
	v_fmac_f32_e32 v171, v250, v250
	v_lshlrev_b32_e32 v0, 16, v9
	v_and_b32_e32 v250, 0xffff0000, v9
	v_fmac_f32_e32 v171, v0, v0
	v_fmac_f32_e32 v171, v250, v250
	v_lshlrev_b32_e32 v0, 16, v10
	v_and_b32_e32 v250, 0xffff0000, v10
	v_mul_f32_e32 v172, v0, v0
	v_fmac_f32_e32 v172, v250, v250
	v_lshlrev_b32_e32 v0, 16, v11
	v_and_b32_e32 v250, 0xffff0000, v11
	v_fmac_f32_e32 v172, v0, v0
	v_fmac_f32_e32 v172, v250, v250
	v_lshlrev_b32_e32 v0, 16, v12
	v_and_b32_e32 v250, 0xffff0000, v12
	v_fmac_f32_e32 v172, v0, v0
	v_fmac_f32_e32 v172, v250, v250
	v_lshlrev_b32_e32 v0, 16, v13
	v_and_b32_e32 v250, 0xffff0000, v13
	v_fmac_f32_e32 v172, v0, v0
	v_fmac_f32_e32 v172, v250, v250
	v_lshlrev_b32_e32 v0, 16, v14
	v_and_b32_e32 v250, 0xffff0000, v14
	v_fmac_f32_e32 v172, v0, v0
	v_fmac_f32_e32 v172, v250, v250
	v_lshlrev_b32_e32 v0, 16, v15
	v_and_b32_e32 v250, 0xffff0000, v15
	v_fmac_f32_e32 v172, v0, v0
	v_fmac_f32_e32 v172, v250, v250
	v_lshlrev_b32_e32 v0, 16, v16
	v_and_b32_e32 v250, 0xffff0000, v16
	v_fmac_f32_e32 v172, v0, v0
	v_fmac_f32_e32 v172, v250, v250
	v_lshlrev_b32_e32 v0, 16, v17
	v_and_b32_e32 v250, 0xffff0000, v17
	v_fmac_f32_e32 v172, v0, v0
	v_fmac_f32_e32 v172, v250, v250
	v_mov_b32_e32 v251, v171
	v_mov_b32_e32 v170, v172
	s_nop 1
	v_permlane32_swap_b32_e32 v171, v251
	v_permlane32_swap_b32_e32 v172, v170
	v_add_f32_e32 v171, v171, v251
	v_add_f32_e32 v172, v172, v170
	ds_swizzle_b32 v251, v171 offset:0x401f
	ds_swizzle_b32 v170, v172 offset:0x401f
	s_waitcnt lgkmcnt(1)
	v_add_f32_e32 v171, v171, v251
	s_waitcnt lgkmcnt(0)
	v_add_f32_e32 v172, v172, v170
	ds_swizzle_b32 v251, v171 offset:0x201f
	ds_swizzle_b32 v170, v172 offset:0x201f
	s_waitcnt lgkmcnt(1)
	v_add_f32_e32 v171, v171, v251
	s_waitcnt lgkmcnt(0)
	v_add_f32_e32 v172, v172, v170
	ds_swizzle_b32 v251, v171 offset:0x101f
	ds_swizzle_b32 v170, v172 offset:0x101f
	s_waitcnt lgkmcnt(1)
	v_add_f32_e32 v171, v171, v251
	s_waitcnt lgkmcnt(0)
	v_add_f32_e32 v172, v172, v170
	ds_swizzle_b32 v251, v171 offset:0x81f
	ds_swizzle_b32 v170, v172 offset:0x81f
	s_waitcnt lgkmcnt(1)
	v_add_f32_e32 v171, v171, v251
	s_waitcnt lgkmcnt(0)
	v_add_f32_e32 v172, v172, v170
	ds_swizzle_b32 v251, v171 offset:0x41f
	ds_swizzle_b32 v170, v172 offset:0x41f
	s_waitcnt lgkmcnt(1)
	v_add_f32_e32 v171, v171, v251
	s_waitcnt lgkmcnt(0)
	v_add_f32_e32 v172, v172, v170
	v_fmamk_f32 v171, v171, 0x3a800000, v153
	v_fmamk_f32 v172, v172, 0x3a800000, v153
	v_rsq_f32_e32 v171, v171
	v_rsq_f32_e32 v172, v172
	s_nop 0
	s_waitcnt vmcnt(16)
	s_add_u32 s28, s56, 0x0
	s_addc_u32 s29, s57, 0
	v_lshlrev_b32_e32 v0, 16, v2
	v_and_b32_e32 v250, 0xffff0000, v2
	v_mul_f32_e32 v0, v171, v0
	v_mul_f32_e32 v250, v171, v250
	v_fmac_f32_e32 v18, v50, v0
	v_fmac_f32_e32 v19, v51, v250
	v_lshlrev_b32_e32 v0, 16, v3
	v_and_b32_e32 v250, 0xffff0000, v3
	v_mul_f32_e32 v0, v171, v0
	v_mul_f32_e32 v250, v171, v250
	v_fmac_f32_e32 v20, v52, v0
	v_fmac_f32_e32 v21, v53, v250
	v_lshlrev_b32_e32 v0, 16, v4
	v_and_b32_e32 v250, 0xffff0000, v4
	v_mul_f32_e32 v0, v171, v0
	v_mul_f32_e32 v250, v171, v250
	v_fmac_f32_e32 v22, v54, v0
	v_fmac_f32_e32 v23, v55, v250
	v_lshlrev_b32_e32 v0, 16, v5
	v_and_b32_e32 v250, 0xffff0000, v5
	v_mul_f32_e32 v0, v171, v0
	v_mul_f32_e32 v250, v171, v250
	v_fmac_f32_e32 v24, v56, v0
	v_fmac_f32_e32 v25, v57, v250
	v_lshlrev_b32_e32 v0, 16, v6
	v_and_b32_e32 v250, 0xffff0000, v6
	v_mul_f32_e32 v0, v171, v0
	v_mul_f32_e32 v250, v171, v250
	v_fmac_f32_e32 v26, v58, v0
	v_fmac_f32_e32 v27, v59, v250
	v_lshlrev_b32_e32 v0, 16, v7
	v_and_b32_e32 v250, 0xffff0000, v7
	v_mul_f32_e32 v0, v171, v0
	v_mul_f32_e32 v250, v171, v250
	v_fmac_f32_e32 v28, v60, v0
	v_fmac_f32_e32 v29, v61, v250
	v_lshlrev_b32_e32 v0, 16, v8
	v_and_b32_e32 v250, 0xffff0000, v8
	v_mul_f32_e32 v0, v171, v0
	v_mul_f32_e32 v250, v171, v250
	v_fmac_f32_e32 v30, v62, v0
	v_fmac_f32_e32 v31, v63, v250
	v_lshlrev_b32_e32 v0, 16, v9
	v_and_b32_e32 v250, 0xffff0000, v9
	v_mul_f32_e32 v0, v171, v0
	v_mul_f32_e32 v250, v171, v250
	v_fmac_f32_e32 v32, v64, v0
	v_fmac_f32_e32 v33, v65, v250
	global_store_dwordx4 v173, v[18:21], s[28:29] offset:0
	global_store_dwordx4 v173, v[22:25], s[28:29] offset:16
	global_store_dwordx4 v173, v[26:29], s[28:29] offset:2048
	global_store_dwordx4 v173, v[30:33], s[28:29] offset:2064
	v_lshlrev_b32_e32 v0, 16, v10
	v_and_b32_e32 v250, 0xffff0000, v10
	v_mul_f32_e32 v0, v172, v0
	v_mul_f32_e32 v250, v172, v250
	v_fmac_f32_e32 v34, v50, v0
	v_fmac_f32_e32 v35, v51, v250
	v_lshlrev_b32_e32 v0, 16, v11
	v_and_b32_e32 v250, 0xffff0000, v11
	v_mul_f32_e32 v0, v172, v0
	v_mul_f32_e32 v250, v172, v250
	v_fmac_f32_e32 v36, v52, v0
	v_fmac_f32_e32 v37, v53, v250
	v_lshlrev_b32_e32 v0, 16, v12
	v_and_b32_e32 v250, 0xffff0000, v12
	v_mul_f32_e32 v0, v172, v0
	v_mul_f32_e32 v250, v172, v250
	v_fmac_f32_e32 v38, v54, v0
	v_fmac_f32_e32 v39, v55, v250
	v_lshlrev_b32_e32 v0, 16, v13
	v_and_b32_e32 v250, 0xffff0000, v13
	v_mul_f32_e32 v0, v172, v0
	v_mul_f32_e32 v250, v172, v250
	v_fmac_f32_e32 v40, v56, v0
	v_fmac_f32_e32 v41, v57, v250
	v_lshlrev_b32_e32 v0, 16, v14
	v_and_b32_e32 v250, 0xffff0000, v14
	v_mul_f32_e32 v0, v172, v0
	v_mul_f32_e32 v250, v172, v250
	v_fmac_f32_e32 v42, v58, v0
	v_fmac_f32_e32 v43, v59, v250
	v_lshlrev_b32_e32 v0, 16, v15
	v_and_b32_e32 v250, 0xffff0000, v15
	v_mul_f32_e32 v0, v172, v0
	v_mul_f32_e32 v250, v172, v250
	v_fmac_f32_e32 v44, v60, v0
	v_fmac_f32_e32 v45, v61, v250
	v_lshlrev_b32_e32 v0, 16, v16
	v_and_b32_e32 v250, 0xffff0000, v16
	v_mul_f32_e32 v0, v172, v0
	v_mul_f32_e32 v250, v172, v250
	v_fmac_f32_e32 v46, v62, v0
	v_fmac_f32_e32 v47, v63, v250
	v_lshlrev_b32_e32 v0, 16, v17
	v_and_b32_e32 v250, 0xffff0000, v17
	v_mul_f32_e32 v0, v172, v0
	v_mul_f32_e32 v250, v172, v250
	v_fmac_f32_e32 v48, v64, v0
	v_fmac_f32_e32 v49, v65, v250
	s_add_u32 s28, s28, 0x1000
	s_addc_u32 s29, s29, 0
	global_store_dwordx4 v173, v[34:37], s[28:29] offset:0
	global_store_dwordx4 v173, v[38:41], s[28:29] offset:16
	global_store_dwordx4 v173, v[42:45], s[28:29] offset:2048
	global_store_dwordx4 v173, v[46:49], s[28:29] offset:2064
	v_mul_f32_e32 v171, v18, v18
	v_fmac_f32_e32 v171, v19, v19
	v_fmac_f32_e32 v171, v20, v20
	v_fmac_f32_e32 v171, v21, v21
	v_fmac_f32_e32 v171, v22, v22
	v_fmac_f32_e32 v171, v23, v23
	v_fmac_f32_e32 v171, v24, v24
	v_fmac_f32_e32 v171, v25, v25
	v_fmac_f32_e32 v171, v26, v26
	v_fmac_f32_e32 v171, v27, v27
	v_fmac_f32_e32 v171, v28, v28
	v_fmac_f32_e32 v171, v29, v29
	v_fmac_f32_e32 v171, v30, v30
	v_fmac_f32_e32 v171, v31, v31
	v_fmac_f32_e32 v171, v32, v32
	v_fmac_f32_e32 v171, v33, v33
	v_mul_f32_e32 v172, v34, v34
	v_fmac_f32_e32 v172, v35, v35
	v_fmac_f32_e32 v172, v36, v36
	v_fmac_f32_e32 v172, v37, v37
	v_fmac_f32_e32 v172, v38, v38
	v_fmac_f32_e32 v172, v39, v39
	v_fmac_f32_e32 v172, v40, v40
	v_fmac_f32_e32 v172, v41, v41
	v_fmac_f32_e32 v172, v42, v42
	v_fmac_f32_e32 v172, v43, v43
	v_fmac_f32_e32 v172, v44, v44
	v_fmac_f32_e32 v172, v45, v45
	v_fmac_f32_e32 v172, v46, v46
	v_fmac_f32_e32 v172, v47, v47
	v_fmac_f32_e32 v172, v48, v48
	v_fmac_f32_e32 v172, v49, v49
	v_mov_b32_e32 v251, v171
	v_mov_b32_e32 v170, v172
	s_nop 1
	v_permlane32_swap_b32_e32 v171, v251
	v_permlane32_swap_b32_e32 v172, v170
	v_add_f32_e32 v171, v171, v251
	v_add_f32_e32 v172, v172, v170
	ds_swizzle_b32 v251, v171 offset:0x401f
	ds_swizzle_b32 v170, v172 offset:0x401f
	s_waitcnt lgkmcnt(1)
	v_add_f32_e32 v171, v171, v251
	s_waitcnt lgkmcnt(0)
	v_add_f32_e32 v172, v172, v170
	ds_swizzle_b32 v251, v171 offset:0x201f
	ds_swizzle_b32 v170, v172 offset:0x201f
	s_waitcnt lgkmcnt(1)
	v_add_f32_e32 v171, v171, v251
	s_waitcnt lgkmcnt(0)
	v_add_f32_e32 v172, v172, v170
	ds_swizzle_b32 v251, v171 offset:0x101f
	ds_swizzle_b32 v170, v172 offset:0x101f
	s_waitcnt lgkmcnt(1)
	v_add_f32_e32 v171, v171, v251
	s_waitcnt lgkmcnt(0)
	v_add_f32_e32 v172, v172, v170
	ds_swizzle_b32 v251, v171 offset:0x81f
	ds_swizzle_b32 v170, v172 offset:0x81f
	s_waitcnt lgkmcnt(1)
	v_add_f32_e32 v171, v171, v251
	s_waitcnt lgkmcnt(0)
	v_add_f32_e32 v172, v172, v170
	ds_swizzle_b32 v251, v171 offset:0x41f
	ds_swizzle_b32 v170, v172 offset:0x41f
	s_waitcnt lgkmcnt(1)
	v_add_f32_e32 v171, v171, v251
	s_waitcnt lgkmcnt(0)
	v_add_f32_e32 v172, v172, v170
	v_fmamk_f32 v171, v171, 0x3a800000, v153
	v_fmamk_f32 v172, v172, 0x3a800000, v153
	v_rsq_f32_e32 v171, v171
	v_rsq_f32_e32 v172, v172
	s_nop 0
	v_add_f32_e32 v218, 1.0, v218
	v_add_f32_e32 v219, 1.0, v219
	v_add_f32_e32 v220, 1.0, v220
	v_add_f32_e32 v221, 1.0, v221
	v_add_f32_e32 v222, 1.0, v222
	v_add_f32_e32 v223, 1.0, v223
	v_add_f32_e32 v224, 1.0, v224
	v_add_f32_e32 v225, 1.0, v225
	v_add_f32_e32 v226, 1.0, v226
	v_add_f32_e32 v227, 1.0, v227
	v_add_f32_e32 v228, 1.0, v228
	v_add_f32_e32 v229, 1.0, v229
	v_add_f32_e32 v230, 1.0, v230
	v_add_f32_e32 v231, 1.0, v231
	v_add_f32_e32 v232, 1.0, v232
	v_add_f32_e32 v233, 1.0, v233
	s_add_u32 s8, s58, 0x0
	s_addc_u32 s9, s59, 0
	v_lshrrev_b32_e32 v251, 1, v173
	v_mul_f32_e32 v0, v18, v171
	v_mul_f32_e32 v0, v0, v154
	v_fma_f32 v0, v0, v218, v234
	v_mul_f32_e32 v250, v19, v171
	v_mul_f32_e32 v250, v250, v155
	v_fma_f32 v250, v250, v219, v235
	v_cvt_pk_bf16_f32 v174, v0, v250
	v_mul_f32_e32 v0, v20, v171
	v_mul_f32_e32 v0, v0, v156
	v_fma_f32 v0, v0, v220, v236
	v_mul_f32_e32 v250, v21, v171
	v_mul_f32_e32 v250, v250, v157
	v_fma_f32 v250, v250, v221, v237
	v_cvt_pk_bf16_f32 v175, v0, v250
	v_mul_f32_e32 v0, v22, v171
	v_mul_f32_e32 v0, v0, v158
	v_fma_f32 v0, v0, v222, v238
	v_mul_f32_e32 v250, v23, v171
	v_mul_f32_e32 v250, v250, v159
	v_fma_f32 v250, v250, v223, v239
	v_cvt_pk_bf16_f32 v176, v0, v250
	v_mul_f32_e32 v0, v24, v171
	v_mul_f32_e32 v0, v0, v160
	v_fma_f32 v0, v0, v224, v240
	v_mul_f32_e32 v250, v25, v171
	v_mul_f32_e32 v250, v250, v161
	v_fma_f32 v250, v250, v225, v241
	v_cvt_pk_bf16_f32 v177, v0, v250
	global_store_dwordx4 v251, v[174:177], s[8:9] offset:0
	s_nop 1
	v_mul_f32_e32 v0, v26, v171
	v_mul_f32_e32 v0, v0, v162
	v_fma_f32 v0, v0, v226, v242
	v_mul_f32_e32 v250, v27, v171
	v_mul_f32_e32 v250, v250, v163
	v_fma_f32 v250, v250, v227, v243
	v_cvt_pk_bf16_f32 v174, v0, v250
	v_mul_f32_e32 v0, v28, v171
	v_mul_f32_e32 v0, v0, v164
	v_fma_f32 v0, v0, v228, v244
	v_mul_f32_e32 v250, v29, v171
	v_mul_f32_e32 v250, v250, v165
	v_fma_f32 v250, v250, v229, v245
	v_cvt_pk_bf16_f32 v175, v0, v250
	v_mul_f32_e32 v0, v30, v171
	v_mul_f32_e32 v0, v0, v166
	v_fma_f32 v0, v0, v230, v246
	v_mul_f32_e32 v250, v31, v171
	v_mul_f32_e32 v250, v250, v167
	v_fma_f32 v250, v250, v231, v247
	v_cvt_pk_bf16_f32 v176, v0, v250
	v_mul_f32_e32 v0, v32, v171
	v_mul_f32_e32 v0, v0, v168
	v_fma_f32 v0, v0, v232, v248
	v_mul_f32_e32 v250, v33, v171
	v_mul_f32_e32 v250, v250, v169
	v_fma_f32 v250, v250, v233, v249
	v_cvt_pk_bf16_f32 v177, v0, v250
	global_store_dwordx4 v251, v[174:177], s[8:9] offset:1024
	s_nop 1
	v_mul_f32_e32 v0, v34, v172
	v_mul_f32_e32 v0, v0, v154
	v_fma_f32 v0, v0, v218, v234
	v_mul_f32_e32 v250, v35, v172
	v_mul_f32_e32 v250, v250, v155
	v_fma_f32 v250, v250, v219, v235
	v_cvt_pk_bf16_f32 v174, v0, v250
	v_mul_f32_e32 v0, v36, v172
	v_mul_f32_e32 v0, v0, v156
	v_fma_f32 v0, v0, v220, v236
	v_mul_f32_e32 v250, v37, v172
	v_mul_f32_e32 v250, v250, v157
	v_fma_f32 v250, v250, v221, v237
	v_cvt_pk_bf16_f32 v175, v0, v250
	v_mul_f32_e32 v0, v38, v172
	v_mul_f32_e32 v0, v0, v158
	v_fma_f32 v0, v0, v222, v238
	v_mul_f32_e32 v250, v39, v172
	v_mul_f32_e32 v250, v250, v159
	v_fma_f32 v250, v250, v223, v239
	v_cvt_pk_bf16_f32 v176, v0, v250
	v_mul_f32_e32 v0, v40, v172
	v_mul_f32_e32 v0, v0, v160
	v_fma_f32 v0, v0, v224, v240
	v_mul_f32_e32 v250, v41, v172
	v_mul_f32_e32 v250, v250, v161
	v_fma_f32 v250, v250, v225, v241
	v_cvt_pk_bf16_f32 v177, v0, v250
	global_store_dwordx4 v251, v[174:177], s[8:9] offset:2048
	s_nop 1
	v_mul_f32_e32 v0, v42, v172
	v_mul_f32_e32 v0, v0, v162
	v_fma_f32 v0, v0, v226, v242
	v_mul_f32_e32 v250, v43, v172
	v_mul_f32_e32 v250, v250, v163
	v_fma_f32 v250, v250, v227, v243
	v_cvt_pk_bf16_f32 v174, v0, v250
	v_mul_f32_e32 v0, v44, v172
	v_mul_f32_e32 v0, v0, v164
	v_fma_f32 v0, v0, v228, v244
	v_mul_f32_e32 v250, v45, v172
	v_mul_f32_e32 v250, v250, v165
	v_fma_f32 v250, v250, v229, v245
	v_cvt_pk_bf16_f32 v175, v0, v250
	v_mul_f32_e32 v0, v46, v172
	v_mul_f32_e32 v0, v0, v166
	v_fma_f32 v0, v0, v230, v246
	v_mul_f32_e32 v250, v47, v172
	v_mul_f32_e32 v250, v250, v167
	v_fma_f32 v250, v250, v231, v247
	v_cvt_pk_bf16_f32 v176, v0, v250
	v_mul_f32_e32 v0, v48, v172
	v_mul_f32_e32 v0, v0, v168
	v_fma_f32 v0, v0, v232, v248
	v_mul_f32_e32 v250, v49, v172
	v_mul_f32_e32 v250, v250, v169
	v_fma_f32 v250, v250, v233, v249
	v_cvt_pk_bf16_f32 v177, v0, v250
	global_store_dwordx4 v251, v[174:177], s[8:9] offset:3072
	s_nop 1
	s_add_u32 s0, s60, 0xf000
	s_addc_u32 s1, s61, 0
	global_load_dwordx4 v[234:237], v173, s[0:1] offset:0
	global_load_dwordx4 v[238:241], v173, s[0:1] offset:16
	global_load_dwordx4 v[242:245], v173, s[0:1] offset:2048
	global_load_dwordx4 v[246:249], v173, s[0:1] offset:2064
	s_add_u32 s0, s0, 0x1000
	s_addc_u32 s1, s1, 0
	global_load_dwordx4 v[218:221], v173, s[0:1] offset:0
	global_load_dwordx4 v[222:225], v173, s[0:1] offset:16
	global_load_dwordx4 v[226:229], v173, s[0:1] offset:2048
	global_load_dwordx4 v[230:233], v173, s[0:1] offset:2064
	s_add_u32 s38, s54, 0x0
	s_addc_u32 s39, s55, 0
	s_add_u32 s40, s58, 0x4000000
	s_addc_u32 s41, s59, 0
	s_add_u32 s42, s60, 0x5000
	s_addc_u32 s43, s61, 0
	v_lshrrev_b32_e32 v0, 1, v173
	global_load_dwordx4 v[2:5], v0, s[40:41] offset:0
	global_load_dwordx4 v[6:9], v0, s[40:41] offset:1024
	global_load_dwordx4 v[10:13], v0, s[40:41] offset:2048
	global_load_dwordx4 v[14:17], v0, s[40:41] offset:3072
	global_load_dwordx4 v[18:21], v173, s[38:39] offset:0
	global_load_dwordx4 v[22:25], v173, s[38:39] offset:16
	global_load_dwordx4 v[26:29], v173, s[38:39] offset:2048
	global_load_dwordx4 v[30:33], v173, s[38:39] offset:2064
	s_add_u32 s38, s38, 0x1000
	s_addc_u32 s39, s39, 0
	global_load_dwordx4 v[34:37], v173, s[38:39] offset:0
	global_load_dwordx4 v[38:41], v173, s[38:39] offset:16
	global_load_dwordx4 v[42:45], v173, s[38:39] offset:2048
	global_load_dwordx4 v[46:49], v173, s[38:39] offset:2064
	global_load_dwordx4 v[50:53], v173, s[42:43] offset:0
	global_load_dwordx4 v[54:57], v173, s[42:43] offset:16
	global_load_dwordx4 v[58:61], v173, s[42:43] offset:2048
	global_load_dwordx4 v[62:65], v173, s[42:43] offset:2064
	s_waitcnt vmcnt(24)
	v_mul_f32_e32 v114, v114, v130
	v_mul_f32_e32 v115, v115, v131
	v_mul_f32_e32 v116, v116, v132
	v_mul_f32_e32 v117, v117, v133
	v_mul_f32_e32 v118, v118, v134
	v_mul_f32_e32 v119, v119, v135
	v_mul_f32_e32 v120, v120, v136
	v_mul_f32_e32 v121, v121, v137
	v_mul_f32_e32 v122, v122, v138
	v_mul_f32_e32 v123, v123, v139
	v_mul_f32_e32 v124, v124, v140
	v_mul_f32_e32 v125, v125, v141
	v_mul_f32_e32 v126, v126, v142
	v_mul_f32_e32 v127, v127, v143
	v_mul_f32_e32 v128, v128, v144
	v_mul_f32_e32 v129, v129, v145
	v_lshlrev_b32_e32 v0, 16, v66
	v_and_b32_e32 v250, 0xffff0000, v66
	v_mul_f32_e32 v171, v0, v0
	v_fmac_f32_e32 v171, v250, v250
	v_lshlrev_b32_e32 v0, 16, v67
	v_and_b32_e32 v250, 0xffff0000, v67
	v_fmac_f32_e32 v171, v0, v0
	v_fmac_f32_e32 v171, v250, v250
	v_lshlrev_b32_e32 v0, 16, v68
	v_and_b32_e32 v250, 0xffff0000, v68
	v_fmac_f32_e32 v171, v0, v0
	v_fmac_f32_e32 v171, v250, v250
	v_lshlrev_b32_e32 v0, 16, v69
	v_and_b32_e32 v250, 0xffff0000, v69
	v_fmac_f32_e32 v171, v0, v0
	v_fmac_f32_e32 v171, v250, v250
	v_lshlrev_b32_e32 v0, 16, v70
	v_and_b32_e32 v250, 0xffff0000, v70
	v_fmac_f32_e32 v171, v0, v0
	v_fmac_f32_e32 v171, v250, v250
	v_lshlrev_b32_e32 v0, 16, v71
	v_and_b32_e32 v250, 0xffff0000, v71
	v_fmac_f32_e32 v171, v0, v0
	v_fmac_f32_e32 v171, v250, v250
	v_lshlrev_b32_e32 v0, 16, v72
	v_and_b32_e32 v250, 0xffff0000, v72
	v_fmac_f32_e32 v171, v0, v0
	v_fmac_f32_e32 v171, v250, v250
	v_lshlrev_b32_e32 v0, 16, v73
	v_and_b32_e32 v250, 0xffff0000, v73
	v_fmac_f32_e32 v171, v0, v0
	v_fmac_f32_e32 v171, v250, v250
	v_lshlrev_b32_e32 v0, 16, v74
	v_and_b32_e32 v250, 0xffff0000, v74
	v_mul_f32_e32 v172, v0, v0
	v_fmac_f32_e32 v172, v250, v250
	v_lshlrev_b32_e32 v0, 16, v75
	v_and_b32_e32 v250, 0xffff0000, v75
	v_fmac_f32_e32 v172, v0, v0
	v_fmac_f32_e32 v172, v250, v250
	v_lshlrev_b32_e32 v0, 16, v76
	v_and_b32_e32 v250, 0xffff0000, v76
	v_fmac_f32_e32 v172, v0, v0
	v_fmac_f32_e32 v172, v250, v250
	v_lshlrev_b32_e32 v0, 16, v77
	v_and_b32_e32 v250, 0xffff0000, v77
	v_fmac_f32_e32 v172, v0, v0
	v_fmac_f32_e32 v172, v250, v250
	v_lshlrev_b32_e32 v0, 16, v78
	v_and_b32_e32 v250, 0xffff0000, v78
	v_fmac_f32_e32 v172, v0, v0
	v_fmac_f32_e32 v172, v250, v250
	v_lshlrev_b32_e32 v0, 16, v79
	v_and_b32_e32 v250, 0xffff0000, v79
	v_fmac_f32_e32 v172, v0, v0
	v_fmac_f32_e32 v172, v250, v250
	v_lshlrev_b32_e32 v0, 16, v80
	v_and_b32_e32 v250, 0xffff0000, v80
	v_fmac_f32_e32 v172, v0, v0
	v_fmac_f32_e32 v172, v250, v250
	v_lshlrev_b32_e32 v0, 16, v81
	v_and_b32_e32 v250, 0xffff0000, v81
	v_fmac_f32_e32 v172, v0, v0
	v_fmac_f32_e32 v172, v250, v250
	v_mov_b32_e32 v251, v171
	v_mov_b32_e32 v170, v172
	s_nop 1
	v_permlane32_swap_b32_e32 v171, v251
	v_permlane32_swap_b32_e32 v172, v170
	v_add_f32_e32 v171, v171, v251
	v_add_f32_e32 v172, v172, v170
	ds_swizzle_b32 v251, v171 offset:0x401f
	ds_swizzle_b32 v170, v172 offset:0x401f
	s_waitcnt lgkmcnt(1)
	v_add_f32_e32 v171, v171, v251
	s_waitcnt lgkmcnt(0)
	v_add_f32_e32 v172, v172, v170
	ds_swizzle_b32 v251, v171 offset:0x201f
	ds_swizzle_b32 v170, v172 offset:0x201f
	s_waitcnt lgkmcnt(1)
	v_add_f32_e32 v171, v171, v251
	s_waitcnt lgkmcnt(0)
	v_add_f32_e32 v172, v172, v170
	ds_swizzle_b32 v251, v171 offset:0x101f
	ds_swizzle_b32 v170, v172 offset:0x101f
	s_waitcnt lgkmcnt(1)
	v_add_f32_e32 v171, v171, v251
	s_waitcnt lgkmcnt(0)
	v_add_f32_e32 v172, v172, v170
	ds_swizzle_b32 v251, v171 offset:0x81f
	ds_swizzle_b32 v170, v172 offset:0x81f
	s_waitcnt lgkmcnt(1)
	v_add_f32_e32 v171, v171, v251
	s_waitcnt lgkmcnt(0)
	v_add_f32_e32 v172, v172, v170
	ds_swizzle_b32 v251, v171 offset:0x41f
	ds_swizzle_b32 v170, v172 offset:0x41f
	s_waitcnt lgkmcnt(1)
	v_add_f32_e32 v171, v171, v251
	s_waitcnt lgkmcnt(0)
	v_add_f32_e32 v172, v172, v170
	v_fmamk_f32 v171, v171, 0x3a800000, v153
	v_fmamk_f32 v172, v172, 0x3a800000, v153
	v_rsq_f32_e32 v171, v171
	v_rsq_f32_e32 v172, v172
	s_nop 0
	s_waitcnt vmcnt(16)
	s_add_u32 s28, s56, 0x1000000
	s_addc_u32 s29, s57, 0
	v_lshlrev_b32_e32 v0, 16, v66
	v_and_b32_e32 v250, 0xffff0000, v66
	v_mul_f32_e32 v0, v171, v0
	v_mul_f32_e32 v250, v171, v250
	v_fmac_f32_e32 v82, v114, v0
	v_fmac_f32_e32 v83, v115, v250
	v_lshlrev_b32_e32 v0, 16, v67
	v_and_b32_e32 v250, 0xffff0000, v67
	v_mul_f32_e32 v0, v171, v0
	v_mul_f32_e32 v250, v171, v250
	v_fmac_f32_e32 v84, v116, v0
	v_fmac_f32_e32 v85, v117, v250
	v_lshlrev_b32_e32 v0, 16, v68
	v_and_b32_e32 v250, 0xffff0000, v68
	v_mul_f32_e32 v0, v171, v0
	v_mul_f32_e32 v250, v171, v250
	v_fmac_f32_e32 v86, v118, v0
	v_fmac_f32_e32 v87, v119, v250
	v_lshlrev_b32_e32 v0, 16, v69
	v_and_b32_e32 v250, 0xffff0000, v69
	v_mul_f32_e32 v0, v171, v0
	v_mul_f32_e32 v250, v171, v250
	v_fmac_f32_e32 v88, v120, v0
	v_fmac_f32_e32 v89, v121, v250
	v_lshlrev_b32_e32 v0, 16, v70
	v_and_b32_e32 v250, 0xffff0000, v70
	v_mul_f32_e32 v0, v171, v0
	v_mul_f32_e32 v250, v171, v250
	v_fmac_f32_e32 v90, v122, v0
	v_fmac_f32_e32 v91, v123, v250
	v_lshlrev_b32_e32 v0, 16, v71
	v_and_b32_e32 v250, 0xffff0000, v71
	v_mul_f32_e32 v0, v171, v0
	v_mul_f32_e32 v250, v171, v250
	v_fmac_f32_e32 v92, v124, v0
	v_fmac_f32_e32 v93, v125, v250
	v_lshlrev_b32_e32 v0, 16, v72
	v_and_b32_e32 v250, 0xffff0000, v72
	v_mul_f32_e32 v0, v171, v0
	v_mul_f32_e32 v250, v171, v250
	v_fmac_f32_e32 v94, v126, v0
	v_fmac_f32_e32 v95, v127, v250
	v_lshlrev_b32_e32 v0, 16, v73
	v_and_b32_e32 v250, 0xffff0000, v73
	v_mul_f32_e32 v0, v171, v0
	v_mul_f32_e32 v250, v171, v250
	v_fmac_f32_e32 v96, v128, v0
	v_fmac_f32_e32 v97, v129, v250
	global_store_dwordx4 v173, v[82:85], s[28:29] offset:0
	global_store_dwordx4 v173, v[86:89], s[28:29] offset:16
	global_store_dwordx4 v173, v[90:93], s[28:29] offset:2048
	global_store_dwordx4 v173, v[94:97], s[28:29] offset:2064
	v_lshlrev_b32_e32 v0, 16, v74
	v_and_b32_e32 v250, 0xffff0000, v74
	v_mul_f32_e32 v0, v172, v0
	v_mul_f32_e32 v250, v172, v250
	v_fmac_f32_e32 v98, v114, v0
	v_fmac_f32_e32 v99, v115, v250
	v_lshlrev_b32_e32 v0, 16, v75
	v_and_b32_e32 v250, 0xffff0000, v75
	v_mul_f32_e32 v0, v172, v0
	v_mul_f32_e32 v250, v172, v250
	v_fmac_f32_e32 v100, v116, v0
	v_fmac_f32_e32 v101, v117, v250
	v_lshlrev_b32_e32 v0, 16, v76
	v_and_b32_e32 v250, 0xffff0000, v76
	v_mul_f32_e32 v0, v172, v0
	v_mul_f32_e32 v250, v172, v250
	v_fmac_f32_e32 v102, v118, v0
	v_fmac_f32_e32 v103, v119, v250
	v_lshlrev_b32_e32 v0, 16, v77
	v_and_b32_e32 v250, 0xffff0000, v77
	v_mul_f32_e32 v0, v172, v0
	v_mul_f32_e32 v250, v172, v250
	v_fmac_f32_e32 v104, v120, v0
	v_fmac_f32_e32 v105, v121, v250
	v_lshlrev_b32_e32 v0, 16, v78
	v_and_b32_e32 v250, 0xffff0000, v78
	v_mul_f32_e32 v0, v172, v0
	v_mul_f32_e32 v250, v172, v250
	v_fmac_f32_e32 v106, v122, v0
	v_fmac_f32_e32 v107, v123, v250
	v_lshlrev_b32_e32 v0, 16, v79
	v_and_b32_e32 v250, 0xffff0000, v79
	v_mul_f32_e32 v0, v172, v0
	v_mul_f32_e32 v250, v172, v250
	v_fmac_f32_e32 v108, v124, v0
	v_fmac_f32_e32 v109, v125, v250
	v_lshlrev_b32_e32 v0, 16, v80
	v_and_b32_e32 v250, 0xffff0000, v80
	v_mul_f32_e32 v0, v172, v0
	v_mul_f32_e32 v250, v172, v250
	v_fmac_f32_e32 v110, v126, v0
	v_fmac_f32_e32 v111, v127, v250
	v_lshlrev_b32_e32 v0, 16, v81
	v_and_b32_e32 v250, 0xffff0000, v81
	v_mul_f32_e32 v0, v172, v0
	v_mul_f32_e32 v250, v172, v250
	v_fmac_f32_e32 v112, v128, v0
	v_fmac_f32_e32 v113, v129, v250
	s_add_u32 s28, s28, 0x1000
	s_addc_u32 s29, s29, 0
	global_store_dwordx4 v173, v[98:101], s[28:29] offset:0
	global_store_dwordx4 v173, v[102:105], s[28:29] offset:16
	global_store_dwordx4 v173, v[106:109], s[28:29] offset:2048
	global_store_dwordx4 v173, v[110:113], s[28:29] offset:2064
	v_mul_f32_e32 v171, v82, v82
	v_fmac_f32_e32 v171, v83, v83
	v_fmac_f32_e32 v171, v84, v84
	v_fmac_f32_e32 v171, v85, v85
	v_fmac_f32_e32 v171, v86, v86
	v_fmac_f32_e32 v171, v87, v87
	v_fmac_f32_e32 v171, v88, v88
	v_fmac_f32_e32 v171, v89, v89
	v_fmac_f32_e32 v171, v90, v90
	v_fmac_f32_e32 v171, v91, v91
	v_fmac_f32_e32 v171, v92, v92
	v_fmac_f32_e32 v171, v93, v93
	v_fmac_f32_e32 v171, v94, v94
	v_fmac_f32_e32 v171, v95, v95
	v_fmac_f32_e32 v171, v96, v96
	v_fmac_f32_e32 v171, v97, v97
	v_mul_f32_e32 v172, v98, v98
	v_fmac_f32_e32 v172, v99, v99
	v_fmac_f32_e32 v172, v100, v100
	v_fmac_f32_e32 v172, v101, v101
	v_fmac_f32_e32 v172, v102, v102
	v_fmac_f32_e32 v172, v103, v103
	v_fmac_f32_e32 v172, v104, v104
	v_fmac_f32_e32 v172, v105, v105
	v_fmac_f32_e32 v172, v106, v106
	v_fmac_f32_e32 v172, v107, v107
	v_fmac_f32_e32 v172, v108, v108
	v_fmac_f32_e32 v172, v109, v109
	v_fmac_f32_e32 v172, v110, v110
	v_fmac_f32_e32 v172, v111, v111
	v_fmac_f32_e32 v172, v112, v112
	v_fmac_f32_e32 v172, v113, v113
	v_mov_b32_e32 v251, v171
	v_mov_b32_e32 v170, v172
	s_nop 1
	v_permlane32_swap_b32_e32 v171, v251
	v_permlane32_swap_b32_e32 v172, v170
	v_add_f32_e32 v171, v171, v251
	v_add_f32_e32 v172, v172, v170
	ds_swizzle_b32 v251, v171 offset:0x401f
	ds_swizzle_b32 v170, v172 offset:0x401f
	s_waitcnt lgkmcnt(1)
	v_add_f32_e32 v171, v171, v251
	s_waitcnt lgkmcnt(0)
	v_add_f32_e32 v172, v172, v170
	ds_swizzle_b32 v251, v171 offset:0x201f
	ds_swizzle_b32 v170, v172 offset:0x201f
	s_waitcnt lgkmcnt(1)
	v_add_f32_e32 v171, v171, v251
	s_waitcnt lgkmcnt(0)
	v_add_f32_e32 v172, v172, v170
	ds_swizzle_b32 v251, v171 offset:0x101f
	ds_swizzle_b32 v170, v172 offset:0x101f
	s_waitcnt lgkmcnt(1)
	v_add_f32_e32 v171, v171, v251
	s_waitcnt lgkmcnt(0)
	v_add_f32_e32 v172, v172, v170
	ds_swizzle_b32 v251, v171 offset:0x81f
	ds_swizzle_b32 v170, v172 offset:0x81f
	s_waitcnt lgkmcnt(1)
	v_add_f32_e32 v171, v171, v251
	s_waitcnt lgkmcnt(0)
	v_add_f32_e32 v172, v172, v170
	ds_swizzle_b32 v251, v171 offset:0x41f
	ds_swizzle_b32 v170, v172 offset:0x41f
	s_waitcnt lgkmcnt(1)
	v_add_f32_e32 v171, v171, v251
	s_waitcnt lgkmcnt(0)
	v_add_f32_e32 v172, v172, v170
	v_fmamk_f32 v171, v171, 0x3a800000, v153
	v_fmamk_f32 v172, v172, 0x3a800000, v153
	v_rsq_f32_e32 v171, v171
	v_rsq_f32_e32 v172, v172
	s_nop 0
	v_add_f32_e32 v218, 1.0, v218
	v_add_f32_e32 v219, 1.0, v219
	v_add_f32_e32 v220, 1.0, v220
	v_add_f32_e32 v221, 1.0, v221
	v_add_f32_e32 v222, 1.0, v222
	v_add_f32_e32 v223, 1.0, v223
	v_add_f32_e32 v224, 1.0, v224
	v_add_f32_e32 v225, 1.0, v225
	v_add_f32_e32 v226, 1.0, v226
	v_add_f32_e32 v227, 1.0, v227
	v_add_f32_e32 v228, 1.0, v228
	v_add_f32_e32 v229, 1.0, v229
	v_add_f32_e32 v230, 1.0, v230
	v_add_f32_e32 v231, 1.0, v231
	v_add_f32_e32 v232, 1.0, v232
	v_add_f32_e32 v233, 1.0, v233
	s_add_u32 s8, s58, 0x800000
	s_addc_u32 s9, s59, 0
	v_lshrrev_b32_e32 v251, 1, v173
	v_mul_f32_e32 v0, v82, v171
	v_mul_f32_e32 v0, v0, v154
	v_fma_f32 v0, v0, v218, v234
	v_mul_f32_e32 v250, v83, v171
	v_mul_f32_e32 v250, v250, v155
	v_fma_f32 v250, v250, v219, v235
	v_cvt_pk_bf16_f32 v174, v0, v250
	v_mul_f32_e32 v0, v84, v171
	v_mul_f32_e32 v0, v0, v156
	v_fma_f32 v0, v0, v220, v236
	v_mul_f32_e32 v250, v85, v171
	v_mul_f32_e32 v250, v250, v157
	v_fma_f32 v250, v250, v221, v237
	v_cvt_pk_bf16_f32 v175, v0, v250
	v_mul_f32_e32 v0, v86, v171
	v_mul_f32_e32 v0, v0, v158
	v_fma_f32 v0, v0, v222, v238
	v_mul_f32_e32 v250, v87, v171
	v_mul_f32_e32 v250, v250, v159
	v_fma_f32 v250, v250, v223, v239
	v_cvt_pk_bf16_f32 v176, v0, v250
	v_mul_f32_e32 v0, v88, v171
	v_mul_f32_e32 v0, v0, v160
	v_fma_f32 v0, v0, v224, v240
	v_mul_f32_e32 v250, v89, v171
	v_mul_f32_e32 v250, v250, v161
	v_fma_f32 v250, v250, v225, v241
	v_cvt_pk_bf16_f32 v177, v0, v250
	global_store_dwordx4 v251, v[174:177], s[8:9] offset:0
	s_nop 1
	v_mul_f32_e32 v0, v90, v171
	v_mul_f32_e32 v0, v0, v162
	v_fma_f32 v0, v0, v226, v242
	v_mul_f32_e32 v250, v91, v171
	v_mul_f32_e32 v250, v250, v163
	v_fma_f32 v250, v250, v227, v243
	v_cvt_pk_bf16_f32 v174, v0, v250
	v_mul_f32_e32 v0, v92, v171
	v_mul_f32_e32 v0, v0, v164
	v_fma_f32 v0, v0, v228, v244
	v_mul_f32_e32 v250, v93, v171
	v_mul_f32_e32 v250, v250, v165
	v_fma_f32 v250, v250, v229, v245
	v_cvt_pk_bf16_f32 v175, v0, v250
	v_mul_f32_e32 v0, v94, v171
	v_mul_f32_e32 v0, v0, v166
	v_fma_f32 v0, v0, v230, v246
	v_mul_f32_e32 v250, v95, v171
	v_mul_f32_e32 v250, v250, v167
	v_fma_f32 v250, v250, v231, v247
	v_cvt_pk_bf16_f32 v176, v0, v250
	v_mul_f32_e32 v0, v96, v171
	v_mul_f32_e32 v0, v0, v168
	v_fma_f32 v0, v0, v232, v248
	v_mul_f32_e32 v250, v97, v171
	v_mul_f32_e32 v250, v250, v169
	v_fma_f32 v250, v250, v233, v249
	v_cvt_pk_bf16_f32 v177, v0, v250
	global_store_dwordx4 v251, v[174:177], s[8:9] offset:1024
	s_nop 1
	v_mul_f32_e32 v0, v98, v172
	v_mul_f32_e32 v0, v0, v154
	v_fma_f32 v0, v0, v218, v234
	v_mul_f32_e32 v250, v99, v172
	v_mul_f32_e32 v250, v250, v155
	v_fma_f32 v250, v250, v219, v235
	v_cvt_pk_bf16_f32 v174, v0, v250
	v_mul_f32_e32 v0, v100, v172
	v_mul_f32_e32 v0, v0, v156
	v_fma_f32 v0, v0, v220, v236
	v_mul_f32_e32 v250, v101, v172
	v_mul_f32_e32 v250, v250, v157
	v_fma_f32 v250, v250, v221, v237
	v_cvt_pk_bf16_f32 v175, v0, v250
	v_mul_f32_e32 v0, v102, v172
	v_mul_f32_e32 v0, v0, v158
	v_fma_f32 v0, v0, v222, v238
	v_mul_f32_e32 v250, v103, v172
	v_mul_f32_e32 v250, v250, v159
	v_fma_f32 v250, v250, v223, v239
	v_cvt_pk_bf16_f32 v176, v0, v250
	v_mul_f32_e32 v0, v104, v172
	v_mul_f32_e32 v0, v0, v160
	v_fma_f32 v0, v0, v224, v240
	v_mul_f32_e32 v250, v105, v172
	v_mul_f32_e32 v250, v250, v161
	v_fma_f32 v250, v250, v225, v241
	v_cvt_pk_bf16_f32 v177, v0, v250
	global_store_dwordx4 v251, v[174:177], s[8:9] offset:2048
	s_nop 1
	v_mul_f32_e32 v0, v106, v172
	v_mul_f32_e32 v0, v0, v162
	v_fma_f32 v0, v0, v226, v242
	v_mul_f32_e32 v250, v107, v172
	v_mul_f32_e32 v250, v250, v163
	v_fma_f32 v250, v250, v227, v243
	v_cvt_pk_bf16_f32 v174, v0, v250
	v_mul_f32_e32 v0, v108, v172
	v_mul_f32_e32 v0, v0, v164
	v_fma_f32 v0, v0, v228, v244
	v_mul_f32_e32 v250, v109, v172
	v_mul_f32_e32 v250, v250, v165
	v_fma_f32 v250, v250, v229, v245
	v_cvt_pk_bf16_f32 v175, v0, v250
	v_mul_f32_e32 v0, v110, v172
	v_mul_f32_e32 v0, v0, v166
	v_fma_f32 v0, v0, v230, v246
	v_mul_f32_e32 v250, v111, v172
	v_mul_f32_e32 v250, v250, v167
	v_fma_f32 v250, v250, v231, v247
	v_cvt_pk_bf16_f32 v176, v0, v250
	v_mul_f32_e32 v0, v112, v172
	v_mul_f32_e32 v0, v0, v168
	v_fma_f32 v0, v0, v232, v248
	v_mul_f32_e32 v250, v113, v172
	v_mul_f32_e32 v250, v250, v169
	v_fma_f32 v250, v250, v233, v249
	v_cvt_pk_bf16_f32 v177, v0, v250
	global_store_dwordx4 v251, v[174:177], s[8:9] offset:3072
	s_nop 1
	s_add_u32 s0, s60, 0x12000
	s_addc_u32 s1, s61, 0
	global_load_dwordx4 v[234:237], v173, s[0:1] offset:0
	global_load_dwordx4 v[238:241], v173, s[0:1] offset:16
	global_load_dwordx4 v[242:245], v173, s[0:1] offset:2048
	global_load_dwordx4 v[246:249], v173, s[0:1] offset:2064
	s_add_u32 s0, s0, 0x1000
	s_addc_u32 s1, s1, 0
	global_load_dwordx4 v[218:221], v173, s[0:1] offset:0
	global_load_dwordx4 v[222:225], v173, s[0:1] offset:16
	global_load_dwordx4 v[226:229], v173, s[0:1] offset:2048
	global_load_dwordx4 v[230:233], v173, s[0:1] offset:2064
	s_add_u32 s38, s54, 0x1000000
	s_addc_u32 s39, s55, 0
	s_add_u32 s40, s58, 0x4800000
	s_addc_u32 s41, s59, 0
	s_add_u32 s42, s60, 0x8000
	s_addc_u32 s43, s61, 0
	v_lshrrev_b32_e32 v0, 1, v173
	global_load_dwordx4 v[66:69], v0, s[40:41] offset:0
	global_load_dwordx4 v[70:73], v0, s[40:41] offset:1024
	global_load_dwordx4 v[74:77], v0, s[40:41] offset:2048
	global_load_dwordx4 v[78:81], v0, s[40:41] offset:3072
	global_load_dwordx4 v[82:85], v173, s[38:39] offset:0
	global_load_dwordx4 v[86:89], v173, s[38:39] offset:16
	global_load_dwordx4 v[90:93], v173, s[38:39] offset:2048
	global_load_dwordx4 v[94:97], v173, s[38:39] offset:2064
	s_add_u32 s38, s38, 0x1000
	s_addc_u32 s39, s39, 0
	global_load_dwordx4 v[98:101], v173, s[38:39] offset:0
	global_load_dwordx4 v[102:105], v173, s[38:39] offset:16
	global_load_dwordx4 v[106:109], v173, s[38:39] offset:2048
	global_load_dwordx4 v[110:113], v173, s[38:39] offset:2064
	global_load_dwordx4 v[114:117], v173, s[42:43] offset:0
	global_load_dwordx4 v[118:121], v173, s[42:43] offset:16
	global_load_dwordx4 v[122:125], v173, s[42:43] offset:2048
	global_load_dwordx4 v[126:129], v173, s[42:43] offset:2064
	s_waitcnt vmcnt(24)
	v_mul_f32_e32 v50, v50, v130
	v_mul_f32_e32 v51, v51, v131
	v_mul_f32_e32 v52, v52, v132
	v_mul_f32_e32 v53, v53, v133
	v_mul_f32_e32 v54, v54, v134
	v_mul_f32_e32 v55, v55, v135
	v_mul_f32_e32 v56, v56, v136
	v_mul_f32_e32 v57, v57, v137
	v_mul_f32_e32 v58, v58, v138
	v_mul_f32_e32 v59, v59, v139
	v_mul_f32_e32 v60, v60, v140
	v_mul_f32_e32 v61, v61, v141
	v_mul_f32_e32 v62, v62, v142
	v_mul_f32_e32 v63, v63, v143
	v_mul_f32_e32 v64, v64, v144
	v_mul_f32_e32 v65, v65, v145
	v_lshlrev_b32_e32 v0, 16, v2
	v_and_b32_e32 v250, 0xffff0000, v2
	v_mul_f32_e32 v171, v0, v0
	v_fmac_f32_e32 v171, v250, v250
	v_lshlrev_b32_e32 v0, 16, v3
	v_and_b32_e32 v250, 0xffff0000, v3
	v_fmac_f32_e32 v171, v0, v0
	v_fmac_f32_e32 v171, v250, v250
	v_lshlrev_b32_e32 v0, 16, v4
	v_and_b32_e32 v250, 0xffff0000, v4
	v_fmac_f32_e32 v171, v0, v0
	v_fmac_f32_e32 v171, v250, v250
	v_lshlrev_b32_e32 v0, 16, v5
	v_and_b32_e32 v250, 0xffff0000, v5
	v_fmac_f32_e32 v171, v0, v0
	v_fmac_f32_e32 v171, v250, v250
	v_lshlrev_b32_e32 v0, 16, v6
	v_and_b32_e32 v250, 0xffff0000, v6
	v_fmac_f32_e32 v171, v0, v0
	v_fmac_f32_e32 v171, v250, v250
	v_lshlrev_b32_e32 v0, 16, v7
	v_and_b32_e32 v250, 0xffff0000, v7
	v_fmac_f32_e32 v171, v0, v0
	v_fmac_f32_e32 v171, v250, v250
	v_lshlrev_b32_e32 v0, 16, v8
	v_and_b32_e32 v250, 0xffff0000, v8
	v_fmac_f32_e32 v171, v0, v0
	v_fmac_f32_e32 v171, v250, v250
	v_lshlrev_b32_e32 v0, 16, v9
	v_and_b32_e32 v250, 0xffff0000, v9
	v_fmac_f32_e32 v171, v0, v0
	v_fmac_f32_e32 v171, v250, v250
	v_lshlrev_b32_e32 v0, 16, v10
	v_and_b32_e32 v250, 0xffff0000, v10
	v_mul_f32_e32 v172, v0, v0
	v_fmac_f32_e32 v172, v250, v250
	v_lshlrev_b32_e32 v0, 16, v11
	v_and_b32_e32 v250, 0xffff0000, v11
	v_fmac_f32_e32 v172, v0, v0
	v_fmac_f32_e32 v172, v250, v250
	v_lshlrev_b32_e32 v0, 16, v12
	v_and_b32_e32 v250, 0xffff0000, v12
	v_fmac_f32_e32 v172, v0, v0
	v_fmac_f32_e32 v172, v250, v250
	v_lshlrev_b32_e32 v0, 16, v13
	v_and_b32_e32 v250, 0xffff0000, v13
	v_fmac_f32_e32 v172, v0, v0
	v_fmac_f32_e32 v172, v250, v250
	v_lshlrev_b32_e32 v0, 16, v14
	v_and_b32_e32 v250, 0xffff0000, v14
	v_fmac_f32_e32 v172, v0, v0
	v_fmac_f32_e32 v172, v250, v250
	v_lshlrev_b32_e32 v0, 16, v15
	v_and_b32_e32 v250, 0xffff0000, v15
	v_fmac_f32_e32 v172, v0, v0
	v_fmac_f32_e32 v172, v250, v250
	v_lshlrev_b32_e32 v0, 16, v16
	v_and_b32_e32 v250, 0xffff0000, v16
	v_fmac_f32_e32 v172, v0, v0
	v_fmac_f32_e32 v172, v250, v250
	v_lshlrev_b32_e32 v0, 16, v17
	v_and_b32_e32 v250, 0xffff0000, v17
	v_fmac_f32_e32 v172, v0, v0
	v_fmac_f32_e32 v172, v250, v250
	v_mov_b32_e32 v251, v171
	v_mov_b32_e32 v170, v172
	s_nop 1
	v_permlane32_swap_b32_e32 v171, v251
	v_permlane32_swap_b32_e32 v172, v170
	v_add_f32_e32 v171, v171, v251
	v_add_f32_e32 v172, v172, v170
	ds_swizzle_b32 v251, v171 offset:0x401f
	ds_swizzle_b32 v170, v172 offset:0x401f
	s_waitcnt lgkmcnt(1)
	v_add_f32_e32 v171, v171, v251
	s_waitcnt lgkmcnt(0)
	v_add_f32_e32 v172, v172, v170
	ds_swizzle_b32 v251, v171 offset:0x201f
	ds_swizzle_b32 v170, v172 offset:0x201f
	s_waitcnt lgkmcnt(1)
	v_add_f32_e32 v171, v171, v251
	s_waitcnt lgkmcnt(0)
	v_add_f32_e32 v172, v172, v170
	ds_swizzle_b32 v251, v171 offset:0x101f
	ds_swizzle_b32 v170, v172 offset:0x101f
	s_waitcnt lgkmcnt(1)
	v_add_f32_e32 v171, v171, v251
	s_waitcnt lgkmcnt(0)
	v_add_f32_e32 v172, v172, v170
	ds_swizzle_b32 v251, v171 offset:0x81f
	ds_swizzle_b32 v170, v172 offset:0x81f
	s_waitcnt lgkmcnt(1)
	v_add_f32_e32 v171, v171, v251
	s_waitcnt lgkmcnt(0)
	v_add_f32_e32 v172, v172, v170
	ds_swizzle_b32 v251, v171 offset:0x41f
	ds_swizzle_b32 v170, v172 offset:0x41f
	s_waitcnt lgkmcnt(1)
	v_add_f32_e32 v171, v171, v251
	s_waitcnt lgkmcnt(0)
	v_add_f32_e32 v172, v172, v170
	v_fmamk_f32 v171, v171, 0x3a800000, v153
	v_fmamk_f32 v172, v172, 0x3a800000, v153
	v_rsq_f32_e32 v171, v171
	v_rsq_f32_e32 v172, v172
	s_nop 0
	s_waitcnt vmcnt(16)
	s_add_u32 s28, s56, 0x2000000
	s_addc_u32 s29, s57, 0
	v_lshlrev_b32_e32 v0, 16, v2
	v_and_b32_e32 v250, 0xffff0000, v2
	v_mul_f32_e32 v0, v171, v0
	v_mul_f32_e32 v250, v171, v250
	v_fmac_f32_e32 v18, v50, v0
	v_fmac_f32_e32 v19, v51, v250
	v_lshlrev_b32_e32 v0, 16, v3
	v_and_b32_e32 v250, 0xffff0000, v3
	v_mul_f32_e32 v0, v171, v0
	v_mul_f32_e32 v250, v171, v250
	v_fmac_f32_e32 v20, v52, v0
	v_fmac_f32_e32 v21, v53, v250
	v_lshlrev_b32_e32 v0, 16, v4
	v_and_b32_e32 v250, 0xffff0000, v4
	v_mul_f32_e32 v0, v171, v0
	v_mul_f32_e32 v250, v171, v250
	v_fmac_f32_e32 v22, v54, v0
	v_fmac_f32_e32 v23, v55, v250
	v_lshlrev_b32_e32 v0, 16, v5
	v_and_b32_e32 v250, 0xffff0000, v5
	v_mul_f32_e32 v0, v171, v0
	v_mul_f32_e32 v250, v171, v250
	v_fmac_f32_e32 v24, v56, v0
	v_fmac_f32_e32 v25, v57, v250
	v_lshlrev_b32_e32 v0, 16, v6
	v_and_b32_e32 v250, 0xffff0000, v6
	v_mul_f32_e32 v0, v171, v0
	v_mul_f32_e32 v250, v171, v250
	v_fmac_f32_e32 v26, v58, v0
	v_fmac_f32_e32 v27, v59, v250
	v_lshlrev_b32_e32 v0, 16, v7
	v_and_b32_e32 v250, 0xffff0000, v7
	v_mul_f32_e32 v0, v171, v0
	v_mul_f32_e32 v250, v171, v250
	v_fmac_f32_e32 v28, v60, v0
	v_fmac_f32_e32 v29, v61, v250
	v_lshlrev_b32_e32 v0, 16, v8
	v_and_b32_e32 v250, 0xffff0000, v8
	v_mul_f32_e32 v0, v171, v0
	v_mul_f32_e32 v250, v171, v250
	v_fmac_f32_e32 v30, v62, v0
	v_fmac_f32_e32 v31, v63, v250
	v_lshlrev_b32_e32 v0, 16, v9
	v_and_b32_e32 v250, 0xffff0000, v9
	v_mul_f32_e32 v0, v171, v0
	v_mul_f32_e32 v250, v171, v250
	v_fmac_f32_e32 v32, v64, v0
	v_fmac_f32_e32 v33, v65, v250
	global_store_dwordx4 v173, v[18:21], s[28:29] offset:0
	global_store_dwordx4 v173, v[22:25], s[28:29] offset:16
	global_store_dwordx4 v173, v[26:29], s[28:29] offset:2048
	global_store_dwordx4 v173, v[30:33], s[28:29] offset:2064
	v_lshlrev_b32_e32 v0, 16, v10
	v_and_b32_e32 v250, 0xffff0000, v10
	v_mul_f32_e32 v0, v172, v0
	v_mul_f32_e32 v250, v172, v250
	v_fmac_f32_e32 v34, v50, v0
	v_fmac_f32_e32 v35, v51, v250
	v_lshlrev_b32_e32 v0, 16, v11
	v_and_b32_e32 v250, 0xffff0000, v11
	v_mul_f32_e32 v0, v172, v0
	v_mul_f32_e32 v250, v172, v250
	v_fmac_f32_e32 v36, v52, v0
	v_fmac_f32_e32 v37, v53, v250
	v_lshlrev_b32_e32 v0, 16, v12
	v_and_b32_e32 v250, 0xffff0000, v12
	v_mul_f32_e32 v0, v172, v0
	v_mul_f32_e32 v250, v172, v250
	v_fmac_f32_e32 v38, v54, v0
	v_fmac_f32_e32 v39, v55, v250
	v_lshlrev_b32_e32 v0, 16, v13
	v_and_b32_e32 v250, 0xffff0000, v13
	v_mul_f32_e32 v0, v172, v0
	v_mul_f32_e32 v250, v172, v250
	v_fmac_f32_e32 v40, v56, v0
	v_fmac_f32_e32 v41, v57, v250
	v_lshlrev_b32_e32 v0, 16, v14
	v_and_b32_e32 v250, 0xffff0000, v14
	v_mul_f32_e32 v0, v172, v0
	v_mul_f32_e32 v250, v172, v250
	v_fmac_f32_e32 v42, v58, v0
	v_fmac_f32_e32 v43, v59, v250
	v_lshlrev_b32_e32 v0, 16, v15
	v_and_b32_e32 v250, 0xffff0000, v15
	v_mul_f32_e32 v0, v172, v0
	v_mul_f32_e32 v250, v172, v250
	v_fmac_f32_e32 v44, v60, v0
	v_fmac_f32_e32 v45, v61, v250
	v_lshlrev_b32_e32 v0, 16, v16
	v_and_b32_e32 v250, 0xffff0000, v16
	v_mul_f32_e32 v0, v172, v0
	v_mul_f32_e32 v250, v172, v250
	v_fmac_f32_e32 v46, v62, v0
	v_fmac_f32_e32 v47, v63, v250
	v_lshlrev_b32_e32 v0, 16, v17
	v_and_b32_e32 v250, 0xffff0000, v17
	v_mul_f32_e32 v0, v172, v0
	v_mul_f32_e32 v250, v172, v250
	v_fmac_f32_e32 v48, v64, v0
	v_fmac_f32_e32 v49, v65, v250
	s_add_u32 s28, s28, 0x1000
	s_addc_u32 s29, s29, 0
	global_store_dwordx4 v173, v[34:37], s[28:29] offset:0
	global_store_dwordx4 v173, v[38:41], s[28:29] offset:16
	global_store_dwordx4 v173, v[42:45], s[28:29] offset:2048
	global_store_dwordx4 v173, v[46:49], s[28:29] offset:2064
	v_mul_f32_e32 v171, v18, v18
	v_fmac_f32_e32 v171, v19, v19
	v_fmac_f32_e32 v171, v20, v20
	v_fmac_f32_e32 v171, v21, v21
	v_fmac_f32_e32 v171, v22, v22
	v_fmac_f32_e32 v171, v23, v23
	v_fmac_f32_e32 v171, v24, v24
	v_fmac_f32_e32 v171, v25, v25
	v_fmac_f32_e32 v171, v26, v26
	v_fmac_f32_e32 v171, v27, v27
	v_fmac_f32_e32 v171, v28, v28
	v_fmac_f32_e32 v171, v29, v29
	v_fmac_f32_e32 v171, v30, v30
	v_fmac_f32_e32 v171, v31, v31
	v_fmac_f32_e32 v171, v32, v32
	v_fmac_f32_e32 v171, v33, v33
	v_mul_f32_e32 v172, v34, v34
	v_fmac_f32_e32 v172, v35, v35
	v_fmac_f32_e32 v172, v36, v36
	v_fmac_f32_e32 v172, v37, v37
	v_fmac_f32_e32 v172, v38, v38
	v_fmac_f32_e32 v172, v39, v39
	v_fmac_f32_e32 v172, v40, v40
	v_fmac_f32_e32 v172, v41, v41
	v_fmac_f32_e32 v172, v42, v42
	v_fmac_f32_e32 v172, v43, v43
	v_fmac_f32_e32 v172, v44, v44
	v_fmac_f32_e32 v172, v45, v45
	v_fmac_f32_e32 v172, v46, v46
	v_fmac_f32_e32 v172, v47, v47
	v_fmac_f32_e32 v172, v48, v48
	v_fmac_f32_e32 v172, v49, v49
	v_mov_b32_e32 v251, v171
	v_mov_b32_e32 v170, v172
	s_nop 1
	v_permlane32_swap_b32_e32 v171, v251
	v_permlane32_swap_b32_e32 v172, v170
	v_add_f32_e32 v171, v171, v251
	v_add_f32_e32 v172, v172, v170
	ds_swizzle_b32 v251, v171 offset:0x401f
	ds_swizzle_b32 v170, v172 offset:0x401f
	s_waitcnt lgkmcnt(1)
	v_add_f32_e32 v171, v171, v251
	s_waitcnt lgkmcnt(0)
	v_add_f32_e32 v172, v172, v170
	ds_swizzle_b32 v251, v171 offset:0x201f
	ds_swizzle_b32 v170, v172 offset:0x201f
	s_waitcnt lgkmcnt(1)
	v_add_f32_e32 v171, v171, v251
	s_waitcnt lgkmcnt(0)
	v_add_f32_e32 v172, v172, v170
	ds_swizzle_b32 v251, v171 offset:0x101f
	ds_swizzle_b32 v170, v172 offset:0x101f
	s_waitcnt lgkmcnt(1)
	v_add_f32_e32 v171, v171, v251
	s_waitcnt lgkmcnt(0)
	v_add_f32_e32 v172, v172, v170
	ds_swizzle_b32 v251, v171 offset:0x81f
	ds_swizzle_b32 v170, v172 offset:0x81f
	s_waitcnt lgkmcnt(1)
	v_add_f32_e32 v171, v171, v251
	s_waitcnt lgkmcnt(0)
	v_add_f32_e32 v172, v172, v170
	ds_swizzle_b32 v251, v171 offset:0x41f
	ds_swizzle_b32 v170, v172 offset:0x41f
	s_waitcnt lgkmcnt(1)
	v_add_f32_e32 v171, v171, v251
	s_waitcnt lgkmcnt(0)
	v_add_f32_e32 v172, v172, v170
	v_fmamk_f32 v171, v171, 0x3a800000, v153
	v_fmamk_f32 v172, v172, 0x3a800000, v153
	v_rsq_f32_e32 v171, v171
	v_rsq_f32_e32 v172, v172
	s_nop 0
	v_add_f32_e32 v218, 1.0, v218
	v_add_f32_e32 v219, 1.0, v219
	v_add_f32_e32 v220, 1.0, v220
	v_add_f32_e32 v221, 1.0, v221
	v_add_f32_e32 v222, 1.0, v222
	v_add_f32_e32 v223, 1.0, v223
	v_add_f32_e32 v224, 1.0, v224
	v_add_f32_e32 v225, 1.0, v225
	v_add_f32_e32 v226, 1.0, v226
	v_add_f32_e32 v227, 1.0, v227
	v_add_f32_e32 v228, 1.0, v228
	v_add_f32_e32 v229, 1.0, v229
	v_add_f32_e32 v230, 1.0, v230
	v_add_f32_e32 v231, 1.0, v231
	v_add_f32_e32 v232, 1.0, v232
	v_add_f32_e32 v233, 1.0, v233
	s_add_u32 s8, s58, 0x1000000
	s_addc_u32 s9, s59, 0
	v_lshrrev_b32_e32 v251, 1, v173
	v_mul_f32_e32 v0, v18, v171
	v_mul_f32_e32 v0, v0, v154
	v_fma_f32 v0, v0, v218, v234
	v_mul_f32_e32 v250, v19, v171
	v_mul_f32_e32 v250, v250, v155
	v_fma_f32 v250, v250, v219, v235
	v_cvt_pk_bf16_f32 v174, v0, v250
	v_mul_f32_e32 v0, v20, v171
	v_mul_f32_e32 v0, v0, v156
	v_fma_f32 v0, v0, v220, v236
	v_mul_f32_e32 v250, v21, v171
	v_mul_f32_e32 v250, v250, v157
	v_fma_f32 v250, v250, v221, v237
	v_cvt_pk_bf16_f32 v175, v0, v250
	v_mul_f32_e32 v0, v22, v171
	v_mul_f32_e32 v0, v0, v158
	v_fma_f32 v0, v0, v222, v238
	v_mul_f32_e32 v250, v23, v171
	v_mul_f32_e32 v250, v250, v159
	v_fma_f32 v250, v250, v223, v239
	v_cvt_pk_bf16_f32 v176, v0, v250
	v_mul_f32_e32 v0, v24, v171
	v_mul_f32_e32 v0, v0, v160
	v_fma_f32 v0, v0, v224, v240
	v_mul_f32_e32 v250, v25, v171
	v_mul_f32_e32 v250, v250, v161
	v_fma_f32 v250, v250, v225, v241
	v_cvt_pk_bf16_f32 v177, v0, v250
	global_store_dwordx4 v251, v[174:177], s[8:9] offset:0
	s_nop 1
	v_mul_f32_e32 v0, v26, v171
	v_mul_f32_e32 v0, v0, v162
	v_fma_f32 v0, v0, v226, v242
	v_mul_f32_e32 v250, v27, v171
	v_mul_f32_e32 v250, v250, v163
	v_fma_f32 v250, v250, v227, v243
	v_cvt_pk_bf16_f32 v174, v0, v250
	v_mul_f32_e32 v0, v28, v171
	v_mul_f32_e32 v0, v0, v164
	v_fma_f32 v0, v0, v228, v244
	v_mul_f32_e32 v250, v29, v171
	v_mul_f32_e32 v250, v250, v165
	v_fma_f32 v250, v250, v229, v245
	v_cvt_pk_bf16_f32 v175, v0, v250
	v_mul_f32_e32 v0, v30, v171
	v_mul_f32_e32 v0, v0, v166
	v_fma_f32 v0, v0, v230, v246
	v_mul_f32_e32 v250, v31, v171
	v_mul_f32_e32 v250, v250, v167
	v_fma_f32 v250, v250, v231, v247
	v_cvt_pk_bf16_f32 v176, v0, v250
	v_mul_f32_e32 v0, v32, v171
	v_mul_f32_e32 v0, v0, v168
	v_fma_f32 v0, v0, v232, v248
	v_mul_f32_e32 v250, v33, v171
	v_mul_f32_e32 v250, v250, v169
	v_fma_f32 v250, v250, v233, v249
	v_cvt_pk_bf16_f32 v177, v0, v250
	global_store_dwordx4 v251, v[174:177], s[8:9] offset:1024
	s_nop 1
	v_mul_f32_e32 v0, v34, v172
	v_mul_f32_e32 v0, v0, v154
	v_fma_f32 v0, v0, v218, v234
	v_mul_f32_e32 v250, v35, v172
	v_mul_f32_e32 v250, v250, v155
	v_fma_f32 v250, v250, v219, v235
	v_cvt_pk_bf16_f32 v174, v0, v250
	v_mul_f32_e32 v0, v36, v172
	v_mul_f32_e32 v0, v0, v156
	v_fma_f32 v0, v0, v220, v236
	v_mul_f32_e32 v250, v37, v172
	v_mul_f32_e32 v250, v250, v157
	v_fma_f32 v250, v250, v221, v237
	v_cvt_pk_bf16_f32 v175, v0, v250
	v_mul_f32_e32 v0, v38, v172
	v_mul_f32_e32 v0, v0, v158
	v_fma_f32 v0, v0, v222, v238
	v_mul_f32_e32 v250, v39, v172
	v_mul_f32_e32 v250, v250, v159
	v_fma_f32 v250, v250, v223, v239
	v_cvt_pk_bf16_f32 v176, v0, v250
	v_mul_f32_e32 v0, v40, v172
	v_mul_f32_e32 v0, v0, v160
	v_fma_f32 v0, v0, v224, v240
	v_mul_f32_e32 v250, v41, v172
	v_mul_f32_e32 v250, v250, v161
	v_fma_f32 v250, v250, v225, v241
	v_cvt_pk_bf16_f32 v177, v0, v250
	global_store_dwordx4 v251, v[174:177], s[8:9] offset:2048
	s_nop 1
	v_mul_f32_e32 v0, v42, v172
	v_mul_f32_e32 v0, v0, v162
	v_fma_f32 v0, v0, v226, v242
	v_mul_f32_e32 v250, v43, v172
	v_mul_f32_e32 v250, v250, v163
	v_fma_f32 v250, v250, v227, v243
	v_cvt_pk_bf16_f32 v174, v0, v250
	v_mul_f32_e32 v0, v44, v172
	v_mul_f32_e32 v0, v0, v164
	v_fma_f32 v0, v0, v228, v244
	v_mul_f32_e32 v250, v45, v172
	v_mul_f32_e32 v250, v250, v165
	v_fma_f32 v250, v250, v229, v245
	v_cvt_pk_bf16_f32 v175, v0, v250
	v_mul_f32_e32 v0, v46, v172
	v_mul_f32_e32 v0, v0, v166
	v_fma_f32 v0, v0, v230, v246
	v_mul_f32_e32 v250, v47, v172
	v_mul_f32_e32 v250, v250, v167
	v_fma_f32 v250, v250, v231, v247
	v_cvt_pk_bf16_f32 v176, v0, v250
	v_mul_f32_e32 v0, v48, v172
	v_mul_f32_e32 v0, v0, v168
	v_fma_f32 v0, v0, v232, v248
	v_mul_f32_e32 v250, v49, v172
	v_mul_f32_e32 v250, v250, v169
	v_fma_f32 v250, v250, v233, v249
	v_cvt_pk_bf16_f32 v177, v0, v250
	global_store_dwordx4 v251, v[174:177], s[8:9] offset:3072
	s_nop 1
	s_add_u32 s0, s60, 0x15000
	s_addc_u32 s1, s61, 0
	global_load_dwordx4 v[234:237], v173, s[0:1] offset:0
	global_load_dwordx4 v[238:241], v173, s[0:1] offset:16
	global_load_dwordx4 v[242:245], v173, s[0:1] offset:2048
	global_load_dwordx4 v[246:249], v173, s[0:1] offset:2064
	s_add_u32 s0, s0, 0x1000
	s_addc_u32 s1, s1, 0
	global_load_dwordx4 v[218:221], v173, s[0:1] offset:0
	global_load_dwordx4 v[222:225], v173, s[0:1] offset:16
	global_load_dwordx4 v[226:229], v173, s[0:1] offset:2048
	global_load_dwordx4 v[230:233], v173, s[0:1] offset:2064
	s_add_u32 s38, s54, 0x2000000
	s_addc_u32 s39, s55, 0
	s_add_u32 s40, s58, 0x5000000
	s_addc_u32 s41, s59, 0
	s_add_u32 s42, s60, 0xb000
	s_addc_u32 s43, s61, 0
	v_lshrrev_b32_e32 v0, 1, v173
	global_load_dwordx4 v[2:5], v0, s[40:41] offset:0
	global_load_dwordx4 v[6:9], v0, s[40:41] offset:1024
	global_load_dwordx4 v[10:13], v0, s[40:41] offset:2048
	global_load_dwordx4 v[14:17], v0, s[40:41] offset:3072
	global_load_dwordx4 v[18:21], v173, s[38:39] offset:0
	global_load_dwordx4 v[22:25], v173, s[38:39] offset:16
	global_load_dwordx4 v[26:29], v173, s[38:39] offset:2048
	global_load_dwordx4 v[30:33], v173, s[38:39] offset:2064
	s_add_u32 s38, s38, 0x1000
	s_addc_u32 s39, s39, 0
	global_load_dwordx4 v[34:37], v173, s[38:39] offset:0
	global_load_dwordx4 v[38:41], v173, s[38:39] offset:16
	global_load_dwordx4 v[42:45], v173, s[38:39] offset:2048
	global_load_dwordx4 v[46:49], v173, s[38:39] offset:2064
	global_load_dwordx4 v[50:53], v173, s[42:43] offset:0
	global_load_dwordx4 v[54:57], v173, s[42:43] offset:16
	global_load_dwordx4 v[58:61], v173, s[42:43] offset:2048
	global_load_dwordx4 v[62:65], v173, s[42:43] offset:2064
	s_waitcnt vmcnt(24)
	v_mul_f32_e32 v114, v114, v130
	v_mul_f32_e32 v115, v115, v131
	v_mul_f32_e32 v116, v116, v132
	v_mul_f32_e32 v117, v117, v133
	v_mul_f32_e32 v118, v118, v134
	v_mul_f32_e32 v119, v119, v135
	v_mul_f32_e32 v120, v120, v136
	v_mul_f32_e32 v121, v121, v137
	v_mul_f32_e32 v122, v122, v138
	v_mul_f32_e32 v123, v123, v139
	v_mul_f32_e32 v124, v124, v140
	v_mul_f32_e32 v125, v125, v141
	v_mul_f32_e32 v126, v126, v142
	v_mul_f32_e32 v127, v127, v143
	v_mul_f32_e32 v128, v128, v144
	v_mul_f32_e32 v129, v129, v145
	v_lshlrev_b32_e32 v0, 16, v66
	v_and_b32_e32 v250, 0xffff0000, v66
	v_mul_f32_e32 v171, v0, v0
	v_fmac_f32_e32 v171, v250, v250
	v_lshlrev_b32_e32 v0, 16, v67
	v_and_b32_e32 v250, 0xffff0000, v67
	v_fmac_f32_e32 v171, v0, v0
	v_fmac_f32_e32 v171, v250, v250
	v_lshlrev_b32_e32 v0, 16, v68
	v_and_b32_e32 v250, 0xffff0000, v68
	v_fmac_f32_e32 v171, v0, v0
	v_fmac_f32_e32 v171, v250, v250
	v_lshlrev_b32_e32 v0, 16, v69
	v_and_b32_e32 v250, 0xffff0000, v69
	v_fmac_f32_e32 v171, v0, v0
	v_fmac_f32_e32 v171, v250, v250
	v_lshlrev_b32_e32 v0, 16, v70
	v_and_b32_e32 v250, 0xffff0000, v70
	v_fmac_f32_e32 v171, v0, v0
	v_fmac_f32_e32 v171, v250, v250
	v_lshlrev_b32_e32 v0, 16, v71
	v_and_b32_e32 v250, 0xffff0000, v71
	v_fmac_f32_e32 v171, v0, v0
	v_fmac_f32_e32 v171, v250, v250
	v_lshlrev_b32_e32 v0, 16, v72
	v_and_b32_e32 v250, 0xffff0000, v72
	v_fmac_f32_e32 v171, v0, v0
	v_fmac_f32_e32 v171, v250, v250
	v_lshlrev_b32_e32 v0, 16, v73
	v_and_b32_e32 v250, 0xffff0000, v73
	v_fmac_f32_e32 v171, v0, v0
	v_fmac_f32_e32 v171, v250, v250
	v_lshlrev_b32_e32 v0, 16, v74
	v_and_b32_e32 v250, 0xffff0000, v74
	v_mul_f32_e32 v172, v0, v0
	v_fmac_f32_e32 v172, v250, v250
	v_lshlrev_b32_e32 v0, 16, v75
	v_and_b32_e32 v250, 0xffff0000, v75
	v_fmac_f32_e32 v172, v0, v0
	v_fmac_f32_e32 v172, v250, v250
	v_lshlrev_b32_e32 v0, 16, v76
	v_and_b32_e32 v250, 0xffff0000, v76
	v_fmac_f32_e32 v172, v0, v0
	v_fmac_f32_e32 v172, v250, v250
	v_lshlrev_b32_e32 v0, 16, v77
	v_and_b32_e32 v250, 0xffff0000, v77
	v_fmac_f32_e32 v172, v0, v0
	v_fmac_f32_e32 v172, v250, v250
	v_lshlrev_b32_e32 v0, 16, v78
	v_and_b32_e32 v250, 0xffff0000, v78
	v_fmac_f32_e32 v172, v0, v0
	v_fmac_f32_e32 v172, v250, v250
	v_lshlrev_b32_e32 v0, 16, v79
	v_and_b32_e32 v250, 0xffff0000, v79
	v_fmac_f32_e32 v172, v0, v0
	v_fmac_f32_e32 v172, v250, v250
	v_lshlrev_b32_e32 v0, 16, v80
	v_and_b32_e32 v250, 0xffff0000, v80
	v_fmac_f32_e32 v172, v0, v0
	v_fmac_f32_e32 v172, v250, v250
	v_lshlrev_b32_e32 v0, 16, v81
	v_and_b32_e32 v250, 0xffff0000, v81
	v_fmac_f32_e32 v172, v0, v0
	v_fmac_f32_e32 v172, v250, v250
	v_mov_b32_e32 v251, v171
	v_mov_b32_e32 v170, v172
	s_nop 1
	v_permlane32_swap_b32_e32 v171, v251
	v_permlane32_swap_b32_e32 v172, v170
	v_add_f32_e32 v171, v171, v251
	v_add_f32_e32 v172, v172, v170
	ds_swizzle_b32 v251, v171 offset:0x401f
	ds_swizzle_b32 v170, v172 offset:0x401f
	s_waitcnt lgkmcnt(1)
	v_add_f32_e32 v171, v171, v251
	s_waitcnt lgkmcnt(0)
	v_add_f32_e32 v172, v172, v170
	ds_swizzle_b32 v251, v171 offset:0x201f
	ds_swizzle_b32 v170, v172 offset:0x201f
	s_waitcnt lgkmcnt(1)
	v_add_f32_e32 v171, v171, v251
	s_waitcnt lgkmcnt(0)
	v_add_f32_e32 v172, v172, v170
	ds_swizzle_b32 v251, v171 offset:0x101f
	ds_swizzle_b32 v170, v172 offset:0x101f
	s_waitcnt lgkmcnt(1)
	v_add_f32_e32 v171, v171, v251
	s_waitcnt lgkmcnt(0)
	v_add_f32_e32 v172, v172, v170
	ds_swizzle_b32 v251, v171 offset:0x81f
	ds_swizzle_b32 v170, v172 offset:0x81f
	s_waitcnt lgkmcnt(1)
	v_add_f32_e32 v171, v171, v251
	s_waitcnt lgkmcnt(0)
	v_add_f32_e32 v172, v172, v170
	ds_swizzle_b32 v251, v171 offset:0x41f
	ds_swizzle_b32 v170, v172 offset:0x41f
	s_waitcnt lgkmcnt(1)
	v_add_f32_e32 v171, v171, v251
	s_waitcnt lgkmcnt(0)
	v_add_f32_e32 v172, v172, v170
	v_fmamk_f32 v171, v171, 0x3a800000, v153
	v_fmamk_f32 v172, v172, 0x3a800000, v153
	v_rsq_f32_e32 v171, v171
	v_rsq_f32_e32 v172, v172
	s_nop 0
	s_waitcnt vmcnt(16)
	s_add_u32 s28, s56, 0x3000000
	s_addc_u32 s29, s57, 0
	v_lshlrev_b32_e32 v0, 16, v66
	v_and_b32_e32 v250, 0xffff0000, v66
	v_mul_f32_e32 v0, v171, v0
	v_mul_f32_e32 v250, v171, v250
	v_fmac_f32_e32 v82, v114, v0
	v_fmac_f32_e32 v83, v115, v250
	v_lshlrev_b32_e32 v0, 16, v67
	v_and_b32_e32 v250, 0xffff0000, v67
	v_mul_f32_e32 v0, v171, v0
	v_mul_f32_e32 v250, v171, v250
	v_fmac_f32_e32 v84, v116, v0
	v_fmac_f32_e32 v85, v117, v250
	v_lshlrev_b32_e32 v0, 16, v68
	v_and_b32_e32 v250, 0xffff0000, v68
	v_mul_f32_e32 v0, v171, v0
	v_mul_f32_e32 v250, v171, v250
	v_fmac_f32_e32 v86, v118, v0
	v_fmac_f32_e32 v87, v119, v250
	v_lshlrev_b32_e32 v0, 16, v69
	v_and_b32_e32 v250, 0xffff0000, v69
	v_mul_f32_e32 v0, v171, v0
	v_mul_f32_e32 v250, v171, v250
	v_fmac_f32_e32 v88, v120, v0
	v_fmac_f32_e32 v89, v121, v250
	v_lshlrev_b32_e32 v0, 16, v70
	v_and_b32_e32 v250, 0xffff0000, v70
	v_mul_f32_e32 v0, v171, v0
	v_mul_f32_e32 v250, v171, v250
	v_fmac_f32_e32 v90, v122, v0
	v_fmac_f32_e32 v91, v123, v250
	v_lshlrev_b32_e32 v0, 16, v71
	v_and_b32_e32 v250, 0xffff0000, v71
	v_mul_f32_e32 v0, v171, v0
	v_mul_f32_e32 v250, v171, v250
	v_fmac_f32_e32 v92, v124, v0
	v_fmac_f32_e32 v93, v125, v250
	v_lshlrev_b32_e32 v0, 16, v72
	v_and_b32_e32 v250, 0xffff0000, v72
	v_mul_f32_e32 v0, v171, v0
	v_mul_f32_e32 v250, v171, v250
	v_fmac_f32_e32 v94, v126, v0
	v_fmac_f32_e32 v95, v127, v250
	v_lshlrev_b32_e32 v0, 16, v73
	v_and_b32_e32 v250, 0xffff0000, v73
	v_mul_f32_e32 v0, v171, v0
	v_mul_f32_e32 v250, v171, v250
	v_fmac_f32_e32 v96, v128, v0
	v_fmac_f32_e32 v97, v129, v250
	global_store_dwordx4 v173, v[82:85], s[28:29] offset:0
	global_store_dwordx4 v173, v[86:89], s[28:29] offset:16
	global_store_dwordx4 v173, v[90:93], s[28:29] offset:2048
	global_store_dwordx4 v173, v[94:97], s[28:29] offset:2064
	v_lshlrev_b32_e32 v0, 16, v74
	v_and_b32_e32 v250, 0xffff0000, v74
	v_mul_f32_e32 v0, v172, v0
	v_mul_f32_e32 v250, v172, v250
	v_fmac_f32_e32 v98, v114, v0
	v_fmac_f32_e32 v99, v115, v250
	v_lshlrev_b32_e32 v0, 16, v75
	v_and_b32_e32 v250, 0xffff0000, v75
	v_mul_f32_e32 v0, v172, v0
	v_mul_f32_e32 v250, v172, v250
	v_fmac_f32_e32 v100, v116, v0
	v_fmac_f32_e32 v101, v117, v250
	v_lshlrev_b32_e32 v0, 16, v76
	v_and_b32_e32 v250, 0xffff0000, v76
	v_mul_f32_e32 v0, v172, v0
	v_mul_f32_e32 v250, v172, v250
	v_fmac_f32_e32 v102, v118, v0
	v_fmac_f32_e32 v103, v119, v250
	v_lshlrev_b32_e32 v0, 16, v77
	v_and_b32_e32 v250, 0xffff0000, v77
	v_mul_f32_e32 v0, v172, v0
	v_mul_f32_e32 v250, v172, v250
	v_fmac_f32_e32 v104, v120, v0
	v_fmac_f32_e32 v105, v121, v250
	v_lshlrev_b32_e32 v0, 16, v78
	v_and_b32_e32 v250, 0xffff0000, v78
	v_mul_f32_e32 v0, v172, v0
	v_mul_f32_e32 v250, v172, v250
	v_fmac_f32_e32 v106, v122, v0
	v_fmac_f32_e32 v107, v123, v250
	v_lshlrev_b32_e32 v0, 16, v79
	v_and_b32_e32 v250, 0xffff0000, v79
	v_mul_f32_e32 v0, v172, v0
	v_mul_f32_e32 v250, v172, v250
	v_fmac_f32_e32 v108, v124, v0
	v_fmac_f32_e32 v109, v125, v250
	v_lshlrev_b32_e32 v0, 16, v80
	v_and_b32_e32 v250, 0xffff0000, v80
	v_mul_f32_e32 v0, v172, v0
	v_mul_f32_e32 v250, v172, v250
	v_fmac_f32_e32 v110, v126, v0
	v_fmac_f32_e32 v111, v127, v250
	v_lshlrev_b32_e32 v0, 16, v81
	v_and_b32_e32 v250, 0xffff0000, v81
	v_mul_f32_e32 v0, v172, v0
	v_mul_f32_e32 v250, v172, v250
	v_fmac_f32_e32 v112, v128, v0
	v_fmac_f32_e32 v113, v129, v250
	s_add_u32 s28, s28, 0x1000
	s_addc_u32 s29, s29, 0
	global_store_dwordx4 v173, v[98:101], s[28:29] offset:0
	global_store_dwordx4 v173, v[102:105], s[28:29] offset:16
	global_store_dwordx4 v173, v[106:109], s[28:29] offset:2048
	global_store_dwordx4 v173, v[110:113], s[28:29] offset:2064
	v_mul_f32_e32 v171, v82, v82
	v_fmac_f32_e32 v171, v83, v83
	v_fmac_f32_e32 v171, v84, v84
	v_fmac_f32_e32 v171, v85, v85
	v_fmac_f32_e32 v171, v86, v86
	v_fmac_f32_e32 v171, v87, v87
	v_fmac_f32_e32 v171, v88, v88
	v_fmac_f32_e32 v171, v89, v89
	v_fmac_f32_e32 v171, v90, v90
	v_fmac_f32_e32 v171, v91, v91
	v_fmac_f32_e32 v171, v92, v92
	v_fmac_f32_e32 v171, v93, v93
	v_fmac_f32_e32 v171, v94, v94
	v_fmac_f32_e32 v171, v95, v95
	v_fmac_f32_e32 v171, v96, v96
	v_fmac_f32_e32 v171, v97, v97
	v_mul_f32_e32 v172, v98, v98
	v_fmac_f32_e32 v172, v99, v99
	v_fmac_f32_e32 v172, v100, v100
	v_fmac_f32_e32 v172, v101, v101
	v_fmac_f32_e32 v172, v102, v102
	v_fmac_f32_e32 v172, v103, v103
	v_fmac_f32_e32 v172, v104, v104
	v_fmac_f32_e32 v172, v105, v105
	v_fmac_f32_e32 v172, v106, v106
	v_fmac_f32_e32 v172, v107, v107
	v_fmac_f32_e32 v172, v108, v108
	v_fmac_f32_e32 v172, v109, v109
	v_fmac_f32_e32 v172, v110, v110
	v_fmac_f32_e32 v172, v111, v111
	v_fmac_f32_e32 v172, v112, v112
	v_fmac_f32_e32 v172, v113, v113
	v_mov_b32_e32 v251, v171
	v_mov_b32_e32 v170, v172
	s_nop 1
	v_permlane32_swap_b32_e32 v171, v251
	v_permlane32_swap_b32_e32 v172, v170
	v_add_f32_e32 v171, v171, v251
	v_add_f32_e32 v172, v172, v170
	ds_swizzle_b32 v251, v171 offset:0x401f
	ds_swizzle_b32 v170, v172 offset:0x401f
	s_waitcnt lgkmcnt(1)
	v_add_f32_e32 v171, v171, v251
	s_waitcnt lgkmcnt(0)
	v_add_f32_e32 v172, v172, v170
	ds_swizzle_b32 v251, v171 offset:0x201f
	ds_swizzle_b32 v170, v172 offset:0x201f
	s_waitcnt lgkmcnt(1)
	v_add_f32_e32 v171, v171, v251
	s_waitcnt lgkmcnt(0)
	v_add_f32_e32 v172, v172, v170
	ds_swizzle_b32 v251, v171 offset:0x101f
	ds_swizzle_b32 v170, v172 offset:0x101f
	s_waitcnt lgkmcnt(1)
	v_add_f32_e32 v171, v171, v251
	s_waitcnt lgkmcnt(0)
	v_add_f32_e32 v172, v172, v170
	ds_swizzle_b32 v251, v171 offset:0x81f
	ds_swizzle_b32 v170, v172 offset:0x81f
	s_waitcnt lgkmcnt(1)
	v_add_f32_e32 v171, v171, v251
	s_waitcnt lgkmcnt(0)
	v_add_f32_e32 v172, v172, v170
	ds_swizzle_b32 v251, v171 offset:0x41f
	ds_swizzle_b32 v170, v172 offset:0x41f
	s_waitcnt lgkmcnt(1)
	v_add_f32_e32 v171, v171, v251
	s_waitcnt lgkmcnt(0)
	v_add_f32_e32 v172, v172, v170
	v_fmamk_f32 v171, v171, 0x3a800000, v153
	v_fmamk_f32 v172, v172, 0x3a800000, v153
	v_rsq_f32_e32 v171, v171
	v_rsq_f32_e32 v172, v172
	s_nop 0
	v_add_f32_e32 v218, 1.0, v218
	v_add_f32_e32 v219, 1.0, v219
	v_add_f32_e32 v220, 1.0, v220
	v_add_f32_e32 v221, 1.0, v221
	v_add_f32_e32 v222, 1.0, v222
	v_add_f32_e32 v223, 1.0, v223
	v_add_f32_e32 v224, 1.0, v224
	v_add_f32_e32 v225, 1.0, v225
	v_add_f32_e32 v226, 1.0, v226
	v_add_f32_e32 v227, 1.0, v227
	v_add_f32_e32 v228, 1.0, v228
	v_add_f32_e32 v229, 1.0, v229
	v_add_f32_e32 v230, 1.0, v230
	v_add_f32_e32 v231, 1.0, v231
	v_add_f32_e32 v232, 1.0, v232
	v_add_f32_e32 v233, 1.0, v233
	s_add_u32 s8, s58, 0x1800000
	s_addc_u32 s9, s59, 0
	v_lshrrev_b32_e32 v251, 1, v173
	v_mul_f32_e32 v0, v82, v171
	v_mul_f32_e32 v0, v0, v154
	v_fma_f32 v0, v0, v218, v234
	v_mul_f32_e32 v250, v83, v171
	v_mul_f32_e32 v250, v250, v155
	v_fma_f32 v250, v250, v219, v235
	v_cvt_pk_bf16_f32 v174, v0, v250
	v_mul_f32_e32 v0, v84, v171
	v_mul_f32_e32 v0, v0, v156
	v_fma_f32 v0, v0, v220, v236
	v_mul_f32_e32 v250, v85, v171
	v_mul_f32_e32 v250, v250, v157
	v_fma_f32 v250, v250, v221, v237
	v_cvt_pk_bf16_f32 v175, v0, v250
	v_mul_f32_e32 v0, v86, v171
	v_mul_f32_e32 v0, v0, v158
	v_fma_f32 v0, v0, v222, v238
	v_mul_f32_e32 v250, v87, v171
	v_mul_f32_e32 v250, v250, v159
	v_fma_f32 v250, v250, v223, v239
	v_cvt_pk_bf16_f32 v176, v0, v250
	v_mul_f32_e32 v0, v88, v171
	v_mul_f32_e32 v0, v0, v160
	v_fma_f32 v0, v0, v224, v240
	v_mul_f32_e32 v250, v89, v171
	v_mul_f32_e32 v250, v250, v161
	v_fma_f32 v250, v250, v225, v241
	v_cvt_pk_bf16_f32 v177, v0, v250
	global_store_dwordx4 v251, v[174:177], s[8:9] offset:0
	s_nop 1
	v_mul_f32_e32 v0, v90, v171
	v_mul_f32_e32 v0, v0, v162
	v_fma_f32 v0, v0, v226, v242
	v_mul_f32_e32 v250, v91, v171
	v_mul_f32_e32 v250, v250, v163
	v_fma_f32 v250, v250, v227, v243
	v_cvt_pk_bf16_f32 v174, v0, v250
	v_mul_f32_e32 v0, v92, v171
	v_mul_f32_e32 v0, v0, v164
	v_fma_f32 v0, v0, v228, v244
	v_mul_f32_e32 v250, v93, v171
	v_mul_f32_e32 v250, v250, v165
	v_fma_f32 v250, v250, v229, v245
	v_cvt_pk_bf16_f32 v175, v0, v250
	v_mul_f32_e32 v0, v94, v171
	v_mul_f32_e32 v0, v0, v166
	v_fma_f32 v0, v0, v230, v246
	v_mul_f32_e32 v250, v95, v171
	v_mul_f32_e32 v250, v250, v167
	v_fma_f32 v250, v250, v231, v247
	v_cvt_pk_bf16_f32 v176, v0, v250
	v_mul_f32_e32 v0, v96, v171
	v_mul_f32_e32 v0, v0, v168
	v_fma_f32 v0, v0, v232, v248
	v_mul_f32_e32 v250, v97, v171
	v_mul_f32_e32 v250, v250, v169
	v_fma_f32 v250, v250, v233, v249
	v_cvt_pk_bf16_f32 v177, v0, v250
	global_store_dwordx4 v251, v[174:177], s[8:9] offset:1024
	s_nop 1
	v_mul_f32_e32 v0, v98, v172
	v_mul_f32_e32 v0, v0, v154
	v_fma_f32 v0, v0, v218, v234
	v_mul_f32_e32 v250, v99, v172
	v_mul_f32_e32 v250, v250, v155
	v_fma_f32 v250, v250, v219, v235
	v_cvt_pk_bf16_f32 v174, v0, v250
	v_mul_f32_e32 v0, v100, v172
	v_mul_f32_e32 v0, v0, v156
	v_fma_f32 v0, v0, v220, v236
	v_mul_f32_e32 v250, v101, v172
	v_mul_f32_e32 v250, v250, v157
	v_fma_f32 v250, v250, v221, v237
	v_cvt_pk_bf16_f32 v175, v0, v250
	v_mul_f32_e32 v0, v102, v172
	v_mul_f32_e32 v0, v0, v158
	v_fma_f32 v0, v0, v222, v238
	v_mul_f32_e32 v250, v103, v172
	v_mul_f32_e32 v250, v250, v159
	v_fma_f32 v250, v250, v223, v239
	v_cvt_pk_bf16_f32 v176, v0, v250
	v_mul_f32_e32 v0, v104, v172
	v_mul_f32_e32 v0, v0, v160
	v_fma_f32 v0, v0, v224, v240
	v_mul_f32_e32 v250, v105, v172
	v_mul_f32_e32 v250, v250, v161
	v_fma_f32 v250, v250, v225, v241
	v_cvt_pk_bf16_f32 v177, v0, v250
	global_store_dwordx4 v251, v[174:177], s[8:9] offset:2048
	s_nop 1
	v_mul_f32_e32 v0, v106, v172
	v_mul_f32_e32 v0, v0, v162
	v_fma_f32 v0, v0, v226, v242
	v_mul_f32_e32 v250, v107, v172
	v_mul_f32_e32 v250, v250, v163
	v_fma_f32 v250, v250, v227, v243
	v_cvt_pk_bf16_f32 v174, v0, v250
	v_mul_f32_e32 v0, v108, v172
	v_mul_f32_e32 v0, v0, v164
	v_fma_f32 v0, v0, v228, v244
	v_mul_f32_e32 v250, v109, v172
	v_mul_f32_e32 v250, v250, v165
	v_fma_f32 v250, v250, v229, v245
	v_cvt_pk_bf16_f32 v175, v0, v250
	v_mul_f32_e32 v0, v110, v172
	v_mul_f32_e32 v0, v0, v166
	v_fma_f32 v0, v0, v230, v246
	v_mul_f32_e32 v250, v111, v172
	v_mul_f32_e32 v250, v250, v167
	v_fma_f32 v250, v250, v231, v247
	v_cvt_pk_bf16_f32 v176, v0, v250
	v_mul_f32_e32 v0, v112, v172
	v_mul_f32_e32 v0, v0, v168
	v_fma_f32 v0, v0, v232, v248
	v_mul_f32_e32 v250, v113, v172
	v_mul_f32_e32 v250, v250, v169
	v_fma_f32 v250, v250, v233, v249
	v_cvt_pk_bf16_f32 v177, v0, v250
	global_store_dwordx4 v251, v[174:177], s[8:9] offset:3072
	s_nop 1
	s_add_u32 s0, s60, 0x18000
	s_addc_u32 s1, s61, 0
	global_load_dwordx4 v[234:237], v173, s[0:1] offset:0
	global_load_dwordx4 v[238:241], v173, s[0:1] offset:16
	global_load_dwordx4 v[242:245], v173, s[0:1] offset:2048
	global_load_dwordx4 v[246:249], v173, s[0:1] offset:2064
	s_add_u32 s0, s0, 0x1000
	s_addc_u32 s1, s1, 0
	global_load_dwordx4 v[218:221], v173, s[0:1] offset:0
	global_load_dwordx4 v[222:225], v173, s[0:1] offset:16
	global_load_dwordx4 v[226:229], v173, s[0:1] offset:2048
	global_load_dwordx4 v[230:233], v173, s[0:1] offset:2064
	s_add_u32 s38, s54, 0x3000000
	s_addc_u32 s39, s55, 0
	s_add_u32 s40, s58, 0x5800000
	s_addc_u32 s41, s59, 0
	s_add_u32 s42, s60, 0xe000
	s_addc_u32 s43, s61, 0
	v_lshrrev_b32_e32 v0, 1, v173
	global_load_dwordx4 v[66:69], v0, s[40:41] offset:0
	global_load_dwordx4 v[70:73], v0, s[40:41] offset:1024
	global_load_dwordx4 v[74:77], v0, s[40:41] offset:2048
	global_load_dwordx4 v[78:81], v0, s[40:41] offset:3072
	global_load_dwordx4 v[82:85], v173, s[38:39] offset:0
	global_load_dwordx4 v[86:89], v173, s[38:39] offset:16
	global_load_dwordx4 v[90:93], v173, s[38:39] offset:2048
	global_load_dwordx4 v[94:97], v173, s[38:39] offset:2064
	s_add_u32 s38, s38, 0x1000
	s_addc_u32 s39, s39, 0
	global_load_dwordx4 v[98:101], v173, s[38:39] offset:0
	global_load_dwordx4 v[102:105], v173, s[38:39] offset:16
	global_load_dwordx4 v[106:109], v173, s[38:39] offset:2048
	global_load_dwordx4 v[110:113], v173, s[38:39] offset:2064
	global_load_dwordx4 v[114:117], v173, s[42:43] offset:0
	global_load_dwordx4 v[118:121], v173, s[42:43] offset:16
	global_load_dwordx4 v[122:125], v173, s[42:43] offset:2048
	global_load_dwordx4 v[126:129], v173, s[42:43] offset:2064
	s_waitcnt vmcnt(24)
	v_mul_f32_e32 v50, v50, v130
	v_mul_f32_e32 v51, v51, v131
	v_mul_f32_e32 v52, v52, v132
	v_mul_f32_e32 v53, v53, v133
	v_mul_f32_e32 v54, v54, v134
	v_mul_f32_e32 v55, v55, v135
	v_mul_f32_e32 v56, v56, v136
	v_mul_f32_e32 v57, v57, v137
	v_mul_f32_e32 v58, v58, v138
	v_mul_f32_e32 v59, v59, v139
	v_mul_f32_e32 v60, v60, v140
	v_mul_f32_e32 v61, v61, v141
	v_mul_f32_e32 v62, v62, v142
	v_mul_f32_e32 v63, v63, v143
	v_mul_f32_e32 v64, v64, v144
	v_mul_f32_e32 v65, v65, v145
	v_lshlrev_b32_e32 v0, 16, v2
	v_and_b32_e32 v250, 0xffff0000, v2
	v_mul_f32_e32 v171, v0, v0
	v_fmac_f32_e32 v171, v250, v250
	v_lshlrev_b32_e32 v0, 16, v3
	v_and_b32_e32 v250, 0xffff0000, v3
	v_fmac_f32_e32 v171, v0, v0
	v_fmac_f32_e32 v171, v250, v250
	v_lshlrev_b32_e32 v0, 16, v4
	v_and_b32_e32 v250, 0xffff0000, v4
	v_fmac_f32_e32 v171, v0, v0
	v_fmac_f32_e32 v171, v250, v250
	v_lshlrev_b32_e32 v0, 16, v5
	v_and_b32_e32 v250, 0xffff0000, v5
	v_fmac_f32_e32 v171, v0, v0
	v_fmac_f32_e32 v171, v250, v250
	v_lshlrev_b32_e32 v0, 16, v6
	v_and_b32_e32 v250, 0xffff0000, v6
	v_fmac_f32_e32 v171, v0, v0
	v_fmac_f32_e32 v171, v250, v250
	v_lshlrev_b32_e32 v0, 16, v7
	v_and_b32_e32 v250, 0xffff0000, v7
	v_fmac_f32_e32 v171, v0, v0
	v_fmac_f32_e32 v171, v250, v250
	v_lshlrev_b32_e32 v0, 16, v8
	v_and_b32_e32 v250, 0xffff0000, v8
	v_fmac_f32_e32 v171, v0, v0
	v_fmac_f32_e32 v171, v250, v250
	v_lshlrev_b32_e32 v0, 16, v9
	v_and_b32_e32 v250, 0xffff0000, v9
	v_fmac_f32_e32 v171, v0, v0
	v_fmac_f32_e32 v171, v250, v250
	v_lshlrev_b32_e32 v0, 16, v10
	v_and_b32_e32 v250, 0xffff0000, v10
	v_mul_f32_e32 v172, v0, v0
	v_fmac_f32_e32 v172, v250, v250
	v_lshlrev_b32_e32 v0, 16, v11
	v_and_b32_e32 v250, 0xffff0000, v11
	v_fmac_f32_e32 v172, v0, v0
	v_fmac_f32_e32 v172, v250, v250
	v_lshlrev_b32_e32 v0, 16, v12
	v_and_b32_e32 v250, 0xffff0000, v12
	v_fmac_f32_e32 v172, v0, v0
	v_fmac_f32_e32 v172, v250, v250
	v_lshlrev_b32_e32 v0, 16, v13
	v_and_b32_e32 v250, 0xffff0000, v13
	v_fmac_f32_e32 v172, v0, v0
	v_fmac_f32_e32 v172, v250, v250
	v_lshlrev_b32_e32 v0, 16, v14
	v_and_b32_e32 v250, 0xffff0000, v14
	v_fmac_f32_e32 v172, v0, v0
	v_fmac_f32_e32 v172, v250, v250
	v_lshlrev_b32_e32 v0, 16, v15
	v_and_b32_e32 v250, 0xffff0000, v15
	v_fmac_f32_e32 v172, v0, v0
	v_fmac_f32_e32 v172, v250, v250
	v_lshlrev_b32_e32 v0, 16, v16
	v_and_b32_e32 v250, 0xffff0000, v16
	v_fmac_f32_e32 v172, v0, v0
	v_fmac_f32_e32 v172, v250, v250
	v_lshlrev_b32_e32 v0, 16, v17
	v_and_b32_e32 v250, 0xffff0000, v17
	v_fmac_f32_e32 v172, v0, v0
	v_fmac_f32_e32 v172, v250, v250
	v_mov_b32_e32 v251, v171
	v_mov_b32_e32 v170, v172
	s_nop 1
	v_permlane32_swap_b32_e32 v171, v251
	v_permlane32_swap_b32_e32 v172, v170
	v_add_f32_e32 v171, v171, v251
	v_add_f32_e32 v172, v172, v170
	ds_swizzle_b32 v251, v171 offset:0x401f
	ds_swizzle_b32 v170, v172 offset:0x401f
	s_waitcnt lgkmcnt(1)
	v_add_f32_e32 v171, v171, v251
	s_waitcnt lgkmcnt(0)
	v_add_f32_e32 v172, v172, v170
	ds_swizzle_b32 v251, v171 offset:0x201f
	ds_swizzle_b32 v170, v172 offset:0x201f
	s_waitcnt lgkmcnt(1)
	v_add_f32_e32 v171, v171, v251
	s_waitcnt lgkmcnt(0)
	v_add_f32_e32 v172, v172, v170
	ds_swizzle_b32 v251, v171 offset:0x101f
	ds_swizzle_b32 v170, v172 offset:0x101f
	s_waitcnt lgkmcnt(1)
	v_add_f32_e32 v171, v171, v251
	s_waitcnt lgkmcnt(0)
	v_add_f32_e32 v172, v172, v170
	ds_swizzle_b32 v251, v171 offset:0x81f
	ds_swizzle_b32 v170, v172 offset:0x81f
	s_waitcnt lgkmcnt(1)
	v_add_f32_e32 v171, v171, v251
	s_waitcnt lgkmcnt(0)
	v_add_f32_e32 v172, v172, v170
	ds_swizzle_b32 v251, v171 offset:0x41f
	ds_swizzle_b32 v170, v172 offset:0x41f
	s_waitcnt lgkmcnt(1)
	v_add_f32_e32 v171, v171, v251
	s_waitcnt lgkmcnt(0)
	v_add_f32_e32 v172, v172, v170
	v_fmamk_f32 v171, v171, 0x3a800000, v153
	v_fmamk_f32 v172, v172, 0x3a800000, v153
	v_rsq_f32_e32 v171, v171
	v_rsq_f32_e32 v172, v172
	s_nop 0
	s_waitcnt vmcnt(16)
	s_add_u32 s28, s56, 0x4000000
	s_addc_u32 s29, s57, 0
	v_lshlrev_b32_e32 v0, 16, v2
	v_and_b32_e32 v250, 0xffff0000, v2
	v_mul_f32_e32 v0, v171, v0
	v_mul_f32_e32 v250, v171, v250
	v_fmac_f32_e32 v18, v50, v0
	v_fmac_f32_e32 v19, v51, v250
	v_lshlrev_b32_e32 v0, 16, v3
	v_and_b32_e32 v250, 0xffff0000, v3
	v_mul_f32_e32 v0, v171, v0
	v_mul_f32_e32 v250, v171, v250
	v_fmac_f32_e32 v20, v52, v0
	v_fmac_f32_e32 v21, v53, v250
	v_lshlrev_b32_e32 v0, 16, v4
	v_and_b32_e32 v250, 0xffff0000, v4
	v_mul_f32_e32 v0, v171, v0
	v_mul_f32_e32 v250, v171, v250
	v_fmac_f32_e32 v22, v54, v0
	v_fmac_f32_e32 v23, v55, v250
	v_lshlrev_b32_e32 v0, 16, v5
	v_and_b32_e32 v250, 0xffff0000, v5
	v_mul_f32_e32 v0, v171, v0
	v_mul_f32_e32 v250, v171, v250
	v_fmac_f32_e32 v24, v56, v0
	v_fmac_f32_e32 v25, v57, v250
	v_lshlrev_b32_e32 v0, 16, v6
	v_and_b32_e32 v250, 0xffff0000, v6
	v_mul_f32_e32 v0, v171, v0
	v_mul_f32_e32 v250, v171, v250
	v_fmac_f32_e32 v26, v58, v0
	v_fmac_f32_e32 v27, v59, v250
	v_lshlrev_b32_e32 v0, 16, v7
	v_and_b32_e32 v250, 0xffff0000, v7
	v_mul_f32_e32 v0, v171, v0
	v_mul_f32_e32 v250, v171, v250
	v_fmac_f32_e32 v28, v60, v0
	v_fmac_f32_e32 v29, v61, v250
	v_lshlrev_b32_e32 v0, 16, v8
	v_and_b32_e32 v250, 0xffff0000, v8
	v_mul_f32_e32 v0, v171, v0
	v_mul_f32_e32 v250, v171, v250
	v_fmac_f32_e32 v30, v62, v0
	v_fmac_f32_e32 v31, v63, v250
	v_lshlrev_b32_e32 v0, 16, v9
	v_and_b32_e32 v250, 0xffff0000, v9
	v_mul_f32_e32 v0, v171, v0
	v_mul_f32_e32 v250, v171, v250
	v_fmac_f32_e32 v32, v64, v0
	v_fmac_f32_e32 v33, v65, v250
	global_store_dwordx4 v173, v[18:21], s[28:29] offset:0
	global_store_dwordx4 v173, v[22:25], s[28:29] offset:16
	global_store_dwordx4 v173, v[26:29], s[28:29] offset:2048
	global_store_dwordx4 v173, v[30:33], s[28:29] offset:2064
	v_lshlrev_b32_e32 v0, 16, v10
	v_and_b32_e32 v250, 0xffff0000, v10
	v_mul_f32_e32 v0, v172, v0
	v_mul_f32_e32 v250, v172, v250
	v_fmac_f32_e32 v34, v50, v0
	v_fmac_f32_e32 v35, v51, v250
	v_lshlrev_b32_e32 v0, 16, v11
	v_and_b32_e32 v250, 0xffff0000, v11
	v_mul_f32_e32 v0, v172, v0
	v_mul_f32_e32 v250, v172, v250
	v_fmac_f32_e32 v36, v52, v0
	v_fmac_f32_e32 v37, v53, v250
	v_lshlrev_b32_e32 v0, 16, v12
	v_and_b32_e32 v250, 0xffff0000, v12
	v_mul_f32_e32 v0, v172, v0
	v_mul_f32_e32 v250, v172, v250
	v_fmac_f32_e32 v38, v54, v0
	v_fmac_f32_e32 v39, v55, v250
	v_lshlrev_b32_e32 v0, 16, v13
	v_and_b32_e32 v250, 0xffff0000, v13
	v_mul_f32_e32 v0, v172, v0
	v_mul_f32_e32 v250, v172, v250
	v_fmac_f32_e32 v40, v56, v0
	v_fmac_f32_e32 v41, v57, v250
	v_lshlrev_b32_e32 v0, 16, v14
	v_and_b32_e32 v250, 0xffff0000, v14
	v_mul_f32_e32 v0, v172, v0
	v_mul_f32_e32 v250, v172, v250
	v_fmac_f32_e32 v42, v58, v0
	v_fmac_f32_e32 v43, v59, v250
	v_lshlrev_b32_e32 v0, 16, v15
	v_and_b32_e32 v250, 0xffff0000, v15
	v_mul_f32_e32 v0, v172, v0
	v_mul_f32_e32 v250, v172, v250
	v_fmac_f32_e32 v44, v60, v0
	v_fmac_f32_e32 v45, v61, v250
	v_lshlrev_b32_e32 v0, 16, v16
	v_and_b32_e32 v250, 0xffff0000, v16
	v_mul_f32_e32 v0, v172, v0
	v_mul_f32_e32 v250, v172, v250
	v_fmac_f32_e32 v46, v62, v0
	v_fmac_f32_e32 v47, v63, v250
	v_lshlrev_b32_e32 v0, 16, v17
	v_and_b32_e32 v250, 0xffff0000, v17
	v_mul_f32_e32 v0, v172, v0
	v_mul_f32_e32 v250, v172, v250
	v_fmac_f32_e32 v48, v64, v0
	v_fmac_f32_e32 v49, v65, v250
	s_add_u32 s28, s28, 0x1000
	s_addc_u32 s29, s29, 0
	global_store_dwordx4 v173, v[34:37], s[28:29] offset:0
	global_store_dwordx4 v173, v[38:41], s[28:29] offset:16
	global_store_dwordx4 v173, v[42:45], s[28:29] offset:2048
	global_store_dwordx4 v173, v[46:49], s[28:29] offset:2064
	v_mul_f32_e32 v171, v18, v18
	v_fmac_f32_e32 v171, v19, v19
	v_fmac_f32_e32 v171, v20, v20
	v_fmac_f32_e32 v171, v21, v21
	v_fmac_f32_e32 v171, v22, v22
	v_fmac_f32_e32 v171, v23, v23
	v_fmac_f32_e32 v171, v24, v24
	v_fmac_f32_e32 v171, v25, v25
	v_fmac_f32_e32 v171, v26, v26
	v_fmac_f32_e32 v171, v27, v27
	v_fmac_f32_e32 v171, v28, v28
	v_fmac_f32_e32 v171, v29, v29
	v_fmac_f32_e32 v171, v30, v30
	v_fmac_f32_e32 v171, v31, v31
	v_fmac_f32_e32 v171, v32, v32
	v_fmac_f32_e32 v171, v33, v33
	v_mul_f32_e32 v172, v34, v34
	v_fmac_f32_e32 v172, v35, v35
	v_fmac_f32_e32 v172, v36, v36
	v_fmac_f32_e32 v172, v37, v37
	v_fmac_f32_e32 v172, v38, v38
	v_fmac_f32_e32 v172, v39, v39
	v_fmac_f32_e32 v172, v40, v40
	v_fmac_f32_e32 v172, v41, v41
	v_fmac_f32_e32 v172, v42, v42
	v_fmac_f32_e32 v172, v43, v43
	v_fmac_f32_e32 v172, v44, v44
	v_fmac_f32_e32 v172, v45, v45
	v_fmac_f32_e32 v172, v46, v46
	v_fmac_f32_e32 v172, v47, v47
	v_fmac_f32_e32 v172, v48, v48
	v_fmac_f32_e32 v172, v49, v49
	v_mov_b32_e32 v251, v171
	v_mov_b32_e32 v170, v172
	s_nop 1
	v_permlane32_swap_b32_e32 v171, v251
	v_permlane32_swap_b32_e32 v172, v170
	v_add_f32_e32 v171, v171, v251
	v_add_f32_e32 v172, v172, v170
	ds_swizzle_b32 v251, v171 offset:0x401f
	ds_swizzle_b32 v170, v172 offset:0x401f
	s_waitcnt lgkmcnt(1)
	v_add_f32_e32 v171, v171, v251
	s_waitcnt lgkmcnt(0)
	v_add_f32_e32 v172, v172, v170
	ds_swizzle_b32 v251, v171 offset:0x201f
	ds_swizzle_b32 v170, v172 offset:0x201f
	s_waitcnt lgkmcnt(1)
	v_add_f32_e32 v171, v171, v251
	s_waitcnt lgkmcnt(0)
	v_add_f32_e32 v172, v172, v170
	ds_swizzle_b32 v251, v171 offset:0x101f
	ds_swizzle_b32 v170, v172 offset:0x101f
	s_waitcnt lgkmcnt(1)
	v_add_f32_e32 v171, v171, v251
	s_waitcnt lgkmcnt(0)
	v_add_f32_e32 v172, v172, v170
	ds_swizzle_b32 v251, v171 offset:0x81f
	ds_swizzle_b32 v170, v172 offset:0x81f
	s_waitcnt lgkmcnt(1)
	v_add_f32_e32 v171, v171, v251
	s_waitcnt lgkmcnt(0)
	v_add_f32_e32 v172, v172, v170
	ds_swizzle_b32 v251, v171 offset:0x41f
	ds_swizzle_b32 v170, v172 offset:0x41f
	s_waitcnt lgkmcnt(1)
	v_add_f32_e32 v171, v171, v251
	s_waitcnt lgkmcnt(0)
	v_add_f32_e32 v172, v172, v170
	v_fmamk_f32 v171, v171, 0x3a800000, v153
	v_fmamk_f32 v172, v172, 0x3a800000, v153
	v_rsq_f32_e32 v171, v171
	v_rsq_f32_e32 v172, v172
	s_nop 0
	v_add_f32_e32 v218, 1.0, v218
	v_add_f32_e32 v219, 1.0, v219
	v_add_f32_e32 v220, 1.0, v220
	v_add_f32_e32 v221, 1.0, v221
	v_add_f32_e32 v222, 1.0, v222
	v_add_f32_e32 v223, 1.0, v223
	v_add_f32_e32 v224, 1.0, v224
	v_add_f32_e32 v225, 1.0, v225
	v_add_f32_e32 v226, 1.0, v226
	v_add_f32_e32 v227, 1.0, v227
	v_add_f32_e32 v228, 1.0, v228
	v_add_f32_e32 v229, 1.0, v229
	v_add_f32_e32 v230, 1.0, v230
	v_add_f32_e32 v231, 1.0, v231
	v_add_f32_e32 v232, 1.0, v232
	v_add_f32_e32 v233, 1.0, v233
	s_add_u32 s8, s58, 0x2000000
	s_addc_u32 s9, s59, 0
	v_lshrrev_b32_e32 v251, 1, v173
	v_mul_f32_e32 v0, v18, v171
	v_mul_f32_e32 v0, v0, v154
	v_fma_f32 v0, v0, v218, v234
	v_mul_f32_e32 v250, v19, v171
	v_mul_f32_e32 v250, v250, v155
	v_fma_f32 v250, v250, v219, v235
	v_cvt_pk_bf16_f32 v174, v0, v250
	v_mul_f32_e32 v0, v20, v171
	v_mul_f32_e32 v0, v0, v156
	v_fma_f32 v0, v0, v220, v236
	v_mul_f32_e32 v250, v21, v171
	v_mul_f32_e32 v250, v250, v157
	v_fma_f32 v250, v250, v221, v237
	v_cvt_pk_bf16_f32 v175, v0, v250
	v_mul_f32_e32 v0, v22, v171
	v_mul_f32_e32 v0, v0, v158
	v_fma_f32 v0, v0, v222, v238
	v_mul_f32_e32 v250, v23, v171
	v_mul_f32_e32 v250, v250, v159
	v_fma_f32 v250, v250, v223, v239
	v_cvt_pk_bf16_f32 v176, v0, v250
	v_mul_f32_e32 v0, v24, v171
	v_mul_f32_e32 v0, v0, v160
	v_fma_f32 v0, v0, v224, v240
	v_mul_f32_e32 v250, v25, v171
	v_mul_f32_e32 v250, v250, v161
	v_fma_f32 v250, v250, v225, v241
	v_cvt_pk_bf16_f32 v177, v0, v250
	global_store_dwordx4 v251, v[174:177], s[8:9] offset:0
	s_nop 1
	v_mul_f32_e32 v0, v26, v171
	v_mul_f32_e32 v0, v0, v162
	v_fma_f32 v0, v0, v226, v242
	v_mul_f32_e32 v250, v27, v171
	v_mul_f32_e32 v250, v250, v163
	v_fma_f32 v250, v250, v227, v243
	v_cvt_pk_bf16_f32 v174, v0, v250
	v_mul_f32_e32 v0, v28, v171
	v_mul_f32_e32 v0, v0, v164
	v_fma_f32 v0, v0, v228, v244
	v_mul_f32_e32 v250, v29, v171
	v_mul_f32_e32 v250, v250, v165
	v_fma_f32 v250, v250, v229, v245
	v_cvt_pk_bf16_f32 v175, v0, v250
	v_mul_f32_e32 v0, v30, v171
	v_mul_f32_e32 v0, v0, v166
	v_fma_f32 v0, v0, v230, v246
	v_mul_f32_e32 v250, v31, v171
	v_mul_f32_e32 v250, v250, v167
	v_fma_f32 v250, v250, v231, v247
	v_cvt_pk_bf16_f32 v176, v0, v250
	v_mul_f32_e32 v0, v32, v171
	v_mul_f32_e32 v0, v0, v168
	v_fma_f32 v0, v0, v232, v248
	v_mul_f32_e32 v250, v33, v171
	v_mul_f32_e32 v250, v250, v169
	v_fma_f32 v250, v250, v233, v249
	v_cvt_pk_bf16_f32 v177, v0, v250
	global_store_dwordx4 v251, v[174:177], s[8:9] offset:1024
	s_nop 1
	v_mul_f32_e32 v0, v34, v172
	v_mul_f32_e32 v0, v0, v154
	v_fma_f32 v0, v0, v218, v234
	v_mul_f32_e32 v250, v35, v172
	v_mul_f32_e32 v250, v250, v155
	v_fma_f32 v250, v250, v219, v235
	v_cvt_pk_bf16_f32 v174, v0, v250
	v_mul_f32_e32 v0, v36, v172
	v_mul_f32_e32 v0, v0, v156
	v_fma_f32 v0, v0, v220, v236
	v_mul_f32_e32 v250, v37, v172
	v_mul_f32_e32 v250, v250, v157
	v_fma_f32 v250, v250, v221, v237
	v_cvt_pk_bf16_f32 v175, v0, v250
	v_mul_f32_e32 v0, v38, v172
	v_mul_f32_e32 v0, v0, v158
	v_fma_f32 v0, v0, v222, v238
	v_mul_f32_e32 v250, v39, v172
	v_mul_f32_e32 v250, v250, v159
	v_fma_f32 v250, v250, v223, v239
	v_cvt_pk_bf16_f32 v176, v0, v250
	v_mul_f32_e32 v0, v40, v172
	v_mul_f32_e32 v0, v0, v160
	v_fma_f32 v0, v0, v224, v240
	v_mul_f32_e32 v250, v41, v172
	v_mul_f32_e32 v250, v250, v161
	v_fma_f32 v250, v250, v225, v241
	v_cvt_pk_bf16_f32 v177, v0, v250
	global_store_dwordx4 v251, v[174:177], s[8:9] offset:2048
	s_nop 1
	v_mul_f32_e32 v0, v42, v172
	v_mul_f32_e32 v0, v0, v162
	v_fma_f32 v0, v0, v226, v242
	v_mul_f32_e32 v250, v43, v172
	v_mul_f32_e32 v250, v250, v163
	v_fma_f32 v250, v250, v227, v243
	v_cvt_pk_bf16_f32 v174, v0, v250
	v_mul_f32_e32 v0, v44, v172
	v_mul_f32_e32 v0, v0, v164
	v_fma_f32 v0, v0, v228, v244
	v_mul_f32_e32 v250, v45, v172
	v_mul_f32_e32 v250, v250, v165
	v_fma_f32 v250, v250, v229, v245
	v_cvt_pk_bf16_f32 v175, v0, v250
	v_mul_f32_e32 v0, v46, v172
	v_mul_f32_e32 v0, v0, v166
	v_fma_f32 v0, v0, v230, v246
	v_mul_f32_e32 v250, v47, v172
	v_mul_f32_e32 v250, v250, v167
	v_fma_f32 v250, v250, v231, v247
	v_cvt_pk_bf16_f32 v176, v0, v250
	v_mul_f32_e32 v0, v48, v172
	v_mul_f32_e32 v0, v0, v168
	v_fma_f32 v0, v0, v232, v248
	v_mul_f32_e32 v250, v49, v172
	v_mul_f32_e32 v250, v250, v169
	v_fma_f32 v250, v250, v233, v249
	v_cvt_pk_bf16_f32 v177, v0, v250
	global_store_dwordx4 v251, v[174:177], s[8:9] offset:3072
	s_nop 1
	s_add_u32 s0, s60, 0x1b000
	s_addc_u32 s1, s61, 0
	global_load_dwordx4 v[234:237], v173, s[0:1] offset:0
	global_load_dwordx4 v[238:241], v173, s[0:1] offset:16
	global_load_dwordx4 v[242:245], v173, s[0:1] offset:2048
	global_load_dwordx4 v[246:249], v173, s[0:1] offset:2064
	s_add_u32 s0, s0, 0x1000
	s_addc_u32 s1, s1, 0
	global_load_dwordx4 v[218:221], v173, s[0:1] offset:0
	global_load_dwordx4 v[222:225], v173, s[0:1] offset:16
	global_load_dwordx4 v[226:229], v173, s[0:1] offset:2048
	global_load_dwordx4 v[230:233], v173, s[0:1] offset:2064
	s_waitcnt vmcnt(8)
	v_mul_f32_e32 v114, v114, v130
	v_mul_f32_e32 v115, v115, v131
	v_mul_f32_e32 v116, v116, v132
	v_mul_f32_e32 v117, v117, v133
	v_mul_f32_e32 v118, v118, v134
	v_mul_f32_e32 v119, v119, v135
	v_mul_f32_e32 v120, v120, v136
	v_mul_f32_e32 v121, v121, v137
	v_mul_f32_e32 v122, v122, v138
	v_mul_f32_e32 v123, v123, v139
	v_mul_f32_e32 v124, v124, v140
	v_mul_f32_e32 v125, v125, v141
	v_mul_f32_e32 v126, v126, v142
	v_mul_f32_e32 v127, v127, v143
	v_mul_f32_e32 v128, v128, v144
	v_mul_f32_e32 v129, v129, v145
	v_lshlrev_b32_e32 v0, 16, v66
	v_and_b32_e32 v250, 0xffff0000, v66
	v_mul_f32_e32 v171, v0, v0
	v_fmac_f32_e32 v171, v250, v250
	v_lshlrev_b32_e32 v0, 16, v67
	v_and_b32_e32 v250, 0xffff0000, v67
	v_fmac_f32_e32 v171, v0, v0
	v_fmac_f32_e32 v171, v250, v250
	v_lshlrev_b32_e32 v0, 16, v68
	v_and_b32_e32 v250, 0xffff0000, v68
	v_fmac_f32_e32 v171, v0, v0
	v_fmac_f32_e32 v171, v250, v250
	v_lshlrev_b32_e32 v0, 16, v69
	v_and_b32_e32 v250, 0xffff0000, v69
	v_fmac_f32_e32 v171, v0, v0
	v_fmac_f32_e32 v171, v250, v250
	v_lshlrev_b32_e32 v0, 16, v70
	v_and_b32_e32 v250, 0xffff0000, v70
	v_fmac_f32_e32 v171, v0, v0
	v_fmac_f32_e32 v171, v250, v250
	v_lshlrev_b32_e32 v0, 16, v71
	v_and_b32_e32 v250, 0xffff0000, v71
	v_fmac_f32_e32 v171, v0, v0
	v_fmac_f32_e32 v171, v250, v250
	v_lshlrev_b32_e32 v0, 16, v72
	v_and_b32_e32 v250, 0xffff0000, v72
	v_fmac_f32_e32 v171, v0, v0
	v_fmac_f32_e32 v171, v250, v250
	v_lshlrev_b32_e32 v0, 16, v73
	v_and_b32_e32 v250, 0xffff0000, v73
	v_fmac_f32_e32 v171, v0, v0
	v_fmac_f32_e32 v171, v250, v250
	v_lshlrev_b32_e32 v0, 16, v74
	v_and_b32_e32 v250, 0xffff0000, v74
	v_mul_f32_e32 v172, v0, v0
	v_fmac_f32_e32 v172, v250, v250
	v_lshlrev_b32_e32 v0, 16, v75
	v_and_b32_e32 v250, 0xffff0000, v75
	v_fmac_f32_e32 v172, v0, v0
	v_fmac_f32_e32 v172, v250, v250
	v_lshlrev_b32_e32 v0, 16, v76
	v_and_b32_e32 v250, 0xffff0000, v76
	v_fmac_f32_e32 v172, v0, v0
	v_fmac_f32_e32 v172, v250, v250
	v_lshlrev_b32_e32 v0, 16, v77
	v_and_b32_e32 v250, 0xffff0000, v77
	v_fmac_f32_e32 v172, v0, v0
	v_fmac_f32_e32 v172, v250, v250
	v_lshlrev_b32_e32 v0, 16, v78
	v_and_b32_e32 v250, 0xffff0000, v78
	v_fmac_f32_e32 v172, v0, v0
	v_fmac_f32_e32 v172, v250, v250
	v_lshlrev_b32_e32 v0, 16, v79
	v_and_b32_e32 v250, 0xffff0000, v79
	v_fmac_f32_e32 v172, v0, v0
	v_fmac_f32_e32 v172, v250, v250
	v_lshlrev_b32_e32 v0, 16, v80
	v_and_b32_e32 v250, 0xffff0000, v80
	v_fmac_f32_e32 v172, v0, v0
	v_fmac_f32_e32 v172, v250, v250
	v_lshlrev_b32_e32 v0, 16, v81
	v_and_b32_e32 v250, 0xffff0000, v81
	v_fmac_f32_e32 v172, v0, v0
	v_fmac_f32_e32 v172, v250, v250
	v_mov_b32_e32 v251, v171
	v_mov_b32_e32 v170, v172
	s_nop 1
	v_permlane32_swap_b32_e32 v171, v251
	v_permlane32_swap_b32_e32 v172, v170
	v_add_f32_e32 v171, v171, v251
	v_add_f32_e32 v172, v172, v170
	ds_swizzle_b32 v251, v171 offset:0x401f
	ds_swizzle_b32 v170, v172 offset:0x401f
	s_waitcnt lgkmcnt(1)
	v_add_f32_e32 v171, v171, v251
	s_waitcnt lgkmcnt(0)
	v_add_f32_e32 v172, v172, v170
	ds_swizzle_b32 v251, v171 offset:0x201f
	ds_swizzle_b32 v170, v172 offset:0x201f
	s_waitcnt lgkmcnt(1)
	v_add_f32_e32 v171, v171, v251
	s_waitcnt lgkmcnt(0)
	v_add_f32_e32 v172, v172, v170
	ds_swizzle_b32 v251, v171 offset:0x101f
	ds_swizzle_b32 v170, v172 offset:0x101f
	s_waitcnt lgkmcnt(1)
	v_add_f32_e32 v171, v171, v251
	s_waitcnt lgkmcnt(0)
	v_add_f32_e32 v172, v172, v170
	ds_swizzle_b32 v251, v171 offset:0x81f
	ds_swizzle_b32 v170, v172 offset:0x81f
	s_waitcnt lgkmcnt(1)
	v_add_f32_e32 v171, v171, v251
	s_waitcnt lgkmcnt(0)
	v_add_f32_e32 v172, v172, v170
	ds_swizzle_b32 v251, v171 offset:0x41f
	ds_swizzle_b32 v170, v172 offset:0x41f
	s_waitcnt lgkmcnt(1)
	v_add_f32_e32 v171, v171, v251
	s_waitcnt lgkmcnt(0)
	v_add_f32_e32 v172, v172, v170
	v_fmamk_f32 v171, v171, 0x3a800000, v153
	v_fmamk_f32 v172, v172, 0x3a800000, v153
	v_rsq_f32_e32 v171, v171
	v_rsq_f32_e32 v172, v172
	s_nop 0
	s_waitcnt vmcnt(0)
	s_add_u32 s28, s56, 0x5000000
	s_addc_u32 s29, s57, 0
	v_lshlrev_b32_e32 v0, 16, v66
	v_and_b32_e32 v250, 0xffff0000, v66
	v_mul_f32_e32 v0, v171, v0
	v_mul_f32_e32 v250, v171, v250
	v_fmac_f32_e32 v82, v114, v0
	v_fmac_f32_e32 v83, v115, v250
	v_lshlrev_b32_e32 v0, 16, v67
	v_and_b32_e32 v250, 0xffff0000, v67
	v_mul_f32_e32 v0, v171, v0
	v_mul_f32_e32 v250, v171, v250
	v_fmac_f32_e32 v84, v116, v0
	v_fmac_f32_e32 v85, v117, v250
	v_lshlrev_b32_e32 v0, 16, v68
	v_and_b32_e32 v250, 0xffff0000, v68
	v_mul_f32_e32 v0, v171, v0
	v_mul_f32_e32 v250, v171, v250
	v_fmac_f32_e32 v86, v118, v0
	v_fmac_f32_e32 v87, v119, v250
	v_lshlrev_b32_e32 v0, 16, v69
	v_and_b32_e32 v250, 0xffff0000, v69
	v_mul_f32_e32 v0, v171, v0
	v_mul_f32_e32 v250, v171, v250
	v_fmac_f32_e32 v88, v120, v0
	v_fmac_f32_e32 v89, v121, v250
	v_lshlrev_b32_e32 v0, 16, v70
	v_and_b32_e32 v250, 0xffff0000, v70
	v_mul_f32_e32 v0, v171, v0
	v_mul_f32_e32 v250, v171, v250
	v_fmac_f32_e32 v90, v122, v0
	v_fmac_f32_e32 v91, v123, v250
	v_lshlrev_b32_e32 v0, 16, v71
	v_and_b32_e32 v250, 0xffff0000, v71
	v_mul_f32_e32 v0, v171, v0
	v_mul_f32_e32 v250, v171, v250
	v_fmac_f32_e32 v92, v124, v0
	v_fmac_f32_e32 v93, v125, v250
	v_lshlrev_b32_e32 v0, 16, v72
	v_and_b32_e32 v250, 0xffff0000, v72
	v_mul_f32_e32 v0, v171, v0
	v_mul_f32_e32 v250, v171, v250
	v_fmac_f32_e32 v94, v126, v0
	v_fmac_f32_e32 v95, v127, v250
	v_lshlrev_b32_e32 v0, 16, v73
	v_and_b32_e32 v250, 0xffff0000, v73
	v_mul_f32_e32 v0, v171, v0
	v_mul_f32_e32 v250, v171, v250
	v_fmac_f32_e32 v96, v128, v0
	v_fmac_f32_e32 v97, v129, v250
	global_store_dwordx4 v173, v[82:85], s[28:29] offset:0
	global_store_dwordx4 v173, v[86:89], s[28:29] offset:16
	global_store_dwordx4 v173, v[90:93], s[28:29] offset:2048
	global_store_dwordx4 v173, v[94:97], s[28:29] offset:2064
	v_lshlrev_b32_e32 v0, 16, v74
	v_and_b32_e32 v250, 0xffff0000, v74
	v_mul_f32_e32 v0, v172, v0
	v_mul_f32_e32 v250, v172, v250
	v_fmac_f32_e32 v98, v114, v0
	v_fmac_f32_e32 v99, v115, v250
	v_lshlrev_b32_e32 v0, 16, v75
	v_and_b32_e32 v250, 0xffff0000, v75
	v_mul_f32_e32 v0, v172, v0
	v_mul_f32_e32 v250, v172, v250
	v_fmac_f32_e32 v100, v116, v0
	v_fmac_f32_e32 v101, v117, v250
	v_lshlrev_b32_e32 v0, 16, v76
	v_and_b32_e32 v250, 0xffff0000, v76
	v_mul_f32_e32 v0, v172, v0
	v_mul_f32_e32 v250, v172, v250
	v_fmac_f32_e32 v102, v118, v0
	v_fmac_f32_e32 v103, v119, v250
	v_lshlrev_b32_e32 v0, 16, v77
	v_and_b32_e32 v250, 0xffff0000, v77
	v_mul_f32_e32 v0, v172, v0
	v_mul_f32_e32 v250, v172, v250
	v_fmac_f32_e32 v104, v120, v0
	v_fmac_f32_e32 v105, v121, v250
	v_lshlrev_b32_e32 v0, 16, v78
	v_and_b32_e32 v250, 0xffff0000, v78
	v_mul_f32_e32 v0, v172, v0
	v_mul_f32_e32 v250, v172, v250
	v_fmac_f32_e32 v106, v122, v0
	v_fmac_f32_e32 v107, v123, v250
	v_lshlrev_b32_e32 v0, 16, v79
	v_and_b32_e32 v250, 0xffff0000, v79
	v_mul_f32_e32 v0, v172, v0
	v_mul_f32_e32 v250, v172, v250
	v_fmac_f32_e32 v108, v124, v0
	v_fmac_f32_e32 v109, v125, v250
	v_lshlrev_b32_e32 v0, 16, v80
	v_and_b32_e32 v250, 0xffff0000, v80
	v_mul_f32_e32 v0, v172, v0
	v_mul_f32_e32 v250, v172, v250
	v_fmac_f32_e32 v110, v126, v0
	v_fmac_f32_e32 v111, v127, v250
	v_lshlrev_b32_e32 v0, 16, v81
	v_and_b32_e32 v250, 0xffff0000, v81
	v_mul_f32_e32 v0, v172, v0
	v_mul_f32_e32 v250, v172, v250
	v_fmac_f32_e32 v112, v128, v0
	v_fmac_f32_e32 v113, v129, v250
	s_add_u32 s28, s28, 0x1000
	s_addc_u32 s29, s29, 0
	global_store_dwordx4 v173, v[98:101], s[28:29] offset:0
	global_store_dwordx4 v173, v[102:105], s[28:29] offset:16
	global_store_dwordx4 v173, v[106:109], s[28:29] offset:2048
	global_store_dwordx4 v173, v[110:113], s[28:29] offset:2064
	v_mul_f32_e32 v171, v82, v82
	v_fmac_f32_e32 v171, v83, v83
	v_fmac_f32_e32 v171, v84, v84
	v_fmac_f32_e32 v171, v85, v85
	v_fmac_f32_e32 v171, v86, v86
	v_fmac_f32_e32 v171, v87, v87
	v_fmac_f32_e32 v171, v88, v88
	v_fmac_f32_e32 v171, v89, v89
	v_fmac_f32_e32 v171, v90, v90
	v_fmac_f32_e32 v171, v91, v91
	v_fmac_f32_e32 v171, v92, v92
	v_fmac_f32_e32 v171, v93, v93
	v_fmac_f32_e32 v171, v94, v94
	v_fmac_f32_e32 v171, v95, v95
	v_fmac_f32_e32 v171, v96, v96
	v_fmac_f32_e32 v171, v97, v97
	v_mul_f32_e32 v172, v98, v98
	v_fmac_f32_e32 v172, v99, v99
	v_fmac_f32_e32 v172, v100, v100
	v_fmac_f32_e32 v172, v101, v101
	v_fmac_f32_e32 v172, v102, v102
	v_fmac_f32_e32 v172, v103, v103
	v_fmac_f32_e32 v172, v104, v104
	v_fmac_f32_e32 v172, v105, v105
	v_fmac_f32_e32 v172, v106, v106
	v_fmac_f32_e32 v172, v107, v107
	v_fmac_f32_e32 v172, v108, v108
	v_fmac_f32_e32 v172, v109, v109
	v_fmac_f32_e32 v172, v110, v110
	v_fmac_f32_e32 v172, v111, v111
	v_fmac_f32_e32 v172, v112, v112
	v_fmac_f32_e32 v172, v113, v113
	v_mov_b32_e32 v251, v171
	v_mov_b32_e32 v170, v172
	s_nop 1
	v_permlane32_swap_b32_e32 v171, v251
	v_permlane32_swap_b32_e32 v172, v170
	v_add_f32_e32 v171, v171, v251
	v_add_f32_e32 v172, v172, v170
	ds_swizzle_b32 v251, v171 offset:0x401f
	ds_swizzle_b32 v170, v172 offset:0x401f
	s_waitcnt lgkmcnt(1)
	v_add_f32_e32 v171, v171, v251
	s_waitcnt lgkmcnt(0)
	v_add_f32_e32 v172, v172, v170
	ds_swizzle_b32 v251, v171 offset:0x201f
	ds_swizzle_b32 v170, v172 offset:0x201f
	s_waitcnt lgkmcnt(1)
	v_add_f32_e32 v171, v171, v251
	s_waitcnt lgkmcnt(0)
	v_add_f32_e32 v172, v172, v170
	ds_swizzle_b32 v251, v171 offset:0x101f
	ds_swizzle_b32 v170, v172 offset:0x101f
	s_waitcnt lgkmcnt(1)
	v_add_f32_e32 v171, v171, v251
	s_waitcnt lgkmcnt(0)
	v_add_f32_e32 v172, v172, v170
	ds_swizzle_b32 v251, v171 offset:0x81f
	ds_swizzle_b32 v170, v172 offset:0x81f
	s_waitcnt lgkmcnt(1)
	v_add_f32_e32 v171, v171, v251
	s_waitcnt lgkmcnt(0)
	v_add_f32_e32 v172, v172, v170
	ds_swizzle_b32 v251, v171 offset:0x41f
	ds_swizzle_b32 v170, v172 offset:0x41f
	s_waitcnt lgkmcnt(1)
	v_add_f32_e32 v171, v171, v251
	s_waitcnt lgkmcnt(0)
	v_add_f32_e32 v172, v172, v170
	v_fmamk_f32 v171, v171, 0x3a800000, v153
	v_fmamk_f32 v172, v172, 0x3a800000, v153
	v_rsq_f32_e32 v171, v171
	v_rsq_f32_e32 v172, v172
	s_nop 0
	v_add_f32_e32 v218, 1.0, v218
	v_add_f32_e32 v219, 1.0, v219
	v_add_f32_e32 v220, 1.0, v220
	v_add_f32_e32 v221, 1.0, v221
	v_add_f32_e32 v222, 1.0, v222
	v_add_f32_e32 v223, 1.0, v223
	v_add_f32_e32 v224, 1.0, v224
	v_add_f32_e32 v225, 1.0, v225
	v_add_f32_e32 v226, 1.0, v226
	v_add_f32_e32 v227, 1.0, v227
	v_add_f32_e32 v228, 1.0, v228
	v_add_f32_e32 v229, 1.0, v229
	v_add_f32_e32 v230, 1.0, v230
	v_add_f32_e32 v231, 1.0, v231
	v_add_f32_e32 v232, 1.0, v232
	v_add_f32_e32 v233, 1.0, v233
	s_add_u32 s8, s58, 0x2800000
	s_addc_u32 s9, s59, 0
	v_lshrrev_b32_e32 v251, 1, v173
	v_mul_f32_e32 v0, v82, v171
	v_mul_f32_e32 v0, v0, v154
	v_fma_f32 v0, v0, v218, v234
	v_mul_f32_e32 v250, v83, v171
	v_mul_f32_e32 v250, v250, v155
	v_fma_f32 v250, v250, v219, v235
	v_cvt_pk_bf16_f32 v174, v0, v250
	v_mul_f32_e32 v0, v84, v171
	v_mul_f32_e32 v0, v0, v156
	v_fma_f32 v0, v0, v220, v236
	v_mul_f32_e32 v250, v85, v171
	v_mul_f32_e32 v250, v250, v157
	v_fma_f32 v250, v250, v221, v237
	v_cvt_pk_bf16_f32 v175, v0, v250
	v_mul_f32_e32 v0, v86, v171
	v_mul_f32_e32 v0, v0, v158
	v_fma_f32 v0, v0, v222, v238
	v_mul_f32_e32 v250, v87, v171
	v_mul_f32_e32 v250, v250, v159
	v_fma_f32 v250, v250, v223, v239
	v_cvt_pk_bf16_f32 v176, v0, v250
	v_mul_f32_e32 v0, v88, v171
	v_mul_f32_e32 v0, v0, v160
	v_fma_f32 v0, v0, v224, v240
	v_mul_f32_e32 v250, v89, v171
	v_mul_f32_e32 v250, v250, v161
	v_fma_f32 v250, v250, v225, v241
	v_cvt_pk_bf16_f32 v177, v0, v250
	global_store_dwordx4 v251, v[174:177], s[8:9] offset:0
	s_nop 1
	v_mul_f32_e32 v0, v90, v171
	v_mul_f32_e32 v0, v0, v162
	v_fma_f32 v0, v0, v226, v242
	v_mul_f32_e32 v250, v91, v171
	v_mul_f32_e32 v250, v250, v163
	v_fma_f32 v250, v250, v227, v243
	v_cvt_pk_bf16_f32 v174, v0, v250
	v_mul_f32_e32 v0, v92, v171
	v_mul_f32_e32 v0, v0, v164
	v_fma_f32 v0, v0, v228, v244
	v_mul_f32_e32 v250, v93, v171
	v_mul_f32_e32 v250, v250, v165
	v_fma_f32 v250, v250, v229, v245
	v_cvt_pk_bf16_f32 v175, v0, v250
	v_mul_f32_e32 v0, v94, v171
	v_mul_f32_e32 v0, v0, v166
	v_fma_f32 v0, v0, v230, v246
	v_mul_f32_e32 v250, v95, v171
	v_mul_f32_e32 v250, v250, v167
	v_fma_f32 v250, v250, v231, v247
	v_cvt_pk_bf16_f32 v176, v0, v250
	v_mul_f32_e32 v0, v96, v171
	v_mul_f32_e32 v0, v0, v168
	v_fma_f32 v0, v0, v232, v248
	v_mul_f32_e32 v250, v97, v171
	v_mul_f32_e32 v250, v250, v169
	v_fma_f32 v250, v250, v233, v249
	v_cvt_pk_bf16_f32 v177, v0, v250
	global_store_dwordx4 v251, v[174:177], s[8:9] offset:1024
	s_nop 1
	v_mul_f32_e32 v0, v98, v172
	v_mul_f32_e32 v0, v0, v154
	v_fma_f32 v0, v0, v218, v234
	v_mul_f32_e32 v250, v99, v172
	v_mul_f32_e32 v250, v250, v155
	v_fma_f32 v250, v250, v219, v235
	v_cvt_pk_bf16_f32 v174, v0, v250
	v_mul_f32_e32 v0, v100, v172
	v_mul_f32_e32 v0, v0, v156
	v_fma_f32 v0, v0, v220, v236
	v_mul_f32_e32 v250, v101, v172
	v_mul_f32_e32 v250, v250, v157
	v_fma_f32 v250, v250, v221, v237
	v_cvt_pk_bf16_f32 v175, v0, v250
	v_mul_f32_e32 v0, v102, v172
	v_mul_f32_e32 v0, v0, v158
	v_fma_f32 v0, v0, v222, v238
	v_mul_f32_e32 v250, v103, v172
	v_mul_f32_e32 v250, v250, v159
	v_fma_f32 v250, v250, v223, v239
	v_cvt_pk_bf16_f32 v176, v0, v250
	v_mul_f32_e32 v0, v104, v172
	v_mul_f32_e32 v0, v0, v160
	v_fma_f32 v0, v0, v224, v240
	v_mul_f32_e32 v250, v105, v172
	v_mul_f32_e32 v250, v250, v161
	v_fma_f32 v250, v250, v225, v241
	v_cvt_pk_bf16_f32 v177, v0, v250
	global_store_dwordx4 v251, v[174:177], s[8:9] offset:2048
	s_nop 1
	v_mul_f32_e32 v0, v106, v172
	v_mul_f32_e32 v0, v0, v162
	v_fma_f32 v0, v0, v226, v242
	v_mul_f32_e32 v250, v107, v172
	v_mul_f32_e32 v250, v250, v163
	v_fma_f32 v250, v250, v227, v243
	v_cvt_pk_bf16_f32 v174, v0, v250
	v_mul_f32_e32 v0, v108, v172
	v_mul_f32_e32 v0, v0, v164
	v_fma_f32 v0, v0, v228, v244
	v_mul_f32_e32 v250, v109, v172
	v_mul_f32_e32 v250, v250, v165
	v_fma_f32 v250, v250, v229, v245
	v_cvt_pk_bf16_f32 v175, v0, v250
	v_mul_f32_e32 v0, v110, v172
	v_mul_f32_e32 v0, v0, v166
	v_fma_f32 v0, v0, v230, v246
	v_mul_f32_e32 v250, v111, v172
	v_mul_f32_e32 v250, v250, v167
	v_fma_f32 v250, v250, v231, v247
	v_cvt_pk_bf16_f32 v176, v0, v250
	v_mul_f32_e32 v0, v112, v172
	v_mul_f32_e32 v0, v0, v168
	v_fma_f32 v0, v0, v232, v248
	v_mul_f32_e32 v250, v113, v172
	v_mul_f32_e32 v250, v250, v169
	v_fma_f32 v250, v250, v233, v249
	v_cvt_pk_bf16_f32 v177, v0, v250
	global_store_dwordx4 v251, v[174:177], s[8:9] offset:3072
	s_nop 1
	s_branch .LBB0_48
.Lfin_l1:
	v_and_b32_e32 v0, 63, v151
	v_lshlrev_b32_e32 v173, 5, v0
	v_lshrrev_b32_e32 v0, 6, v151
	v_readlane_b32 s5, v252, 0
	s_nop 0
	v_readfirstlane_b32 s6, v0
	s_lshl_b32 s5, s5, 3
	s_lshl_b32 s6, s6, 1
	s_add_i32 s5, s5, s6
	s_lshl_b32 s6, s5, 12
	s_lshl_b32 s7, s5, 11
	s_add_u32 s56, s92, s6
	s_addc_u32 s57, s93, 0
	s_add_u32 s58, s94, s7
	s_addc_u32 s59, s95, 0
	s_add_u32 s60, s94, 0xfc80000
	s_addc_u32 s61, s95, 0
	v_readlane_b32 s62, v252, 35
	v_readlane_b32 s63, v252, 36
	s_add_u32 s62, s62, 0x1000
	s_addc_u32 s63, s63, 0
	global_load_dwordx4 v[130:133], v173, s[62:63] offset:0
	global_load_dwordx4 v[134:137], v173, s[62:63] offset:16
	global_load_dwordx4 v[138:141], v173, s[62:63] offset:2048
	global_load_dwordx4 v[142:145], v173, s[62:63] offset:2064
	s_add_u32 s38, s56, 0x0
	s_addc_u32 s39, s57, 0
	s_add_u32 s40, s58, 0x3000000
	s_addc_u32 s41, s59, 0
	s_add_u32 s42, s60, 0x11000
	s_addc_u32 s43, s61, 0
	v_lshrrev_b32_e32 v0, 1, v173
	global_load_dwordx4 v[2:5], v0, s[40:41] offset:0
	global_load_dwordx4 v[6:9], v0, s[40:41] offset:1024
	global_load_dwordx4 v[10:13], v0, s[40:41] offset:2048
	global_load_dwordx4 v[14:17], v0, s[40:41] offset:3072
	global_load_dwordx4 v[18:21], v173, s[38:39] offset:0
	global_load_dwordx4 v[22:25], v173, s[38:39] offset:16
	global_load_dwordx4 v[26:29], v173, s[38:39] offset:2048
	global_load_dwordx4 v[30:33], v173, s[38:39] offset:2064
	s_add_u32 s38, s38, 0x1000
	s_addc_u32 s39, s39, 0
	global_load_dwordx4 v[34:37], v173, s[38:39] offset:0
	global_load_dwordx4 v[38:41], v173, s[38:39] offset:16
	global_load_dwordx4 v[42:45], v173, s[38:39] offset:2048
	global_load_dwordx4 v[46:49], v173, s[38:39] offset:2064
	global_load_dwordx4 v[50:53], v173, s[42:43] offset:0
	global_load_dwordx4 v[54:57], v173, s[42:43] offset:16
	global_load_dwordx4 v[58:61], v173, s[42:43] offset:2048
	global_load_dwordx4 v[62:65], v173, s[42:43] offset:2064
	s_add_u32 s38, s56, 0x1000000
	s_addc_u32 s39, s57, 0
	s_add_u32 s40, s58, 0x3800000
	s_addc_u32 s41, s59, 0
	s_add_u32 s42, s60, 0x11000
	s_addc_u32 s43, s61, 0
	v_lshrrev_b32_e32 v0, 1, v173
	global_load_dwordx4 v[66:69], v0, s[40:41] offset:0
	global_load_dwordx4 v[70:73], v0, s[40:41] offset:1024
	global_load_dwordx4 v[74:77], v0, s[40:41] offset:2048
	global_load_dwordx4 v[78:81], v0, s[40:41] offset:3072
	global_load_dwordx4 v[82:85], v173, s[38:39] offset:0
	global_load_dwordx4 v[86:89], v173, s[38:39] offset:16
	global_load_dwordx4 v[90:93], v173, s[38:39] offset:2048
	global_load_dwordx4 v[94:97], v173, s[38:39] offset:2064
	s_add_u32 s38, s38, 0x1000
	s_addc_u32 s39, s39, 0
	global_load_dwordx4 v[98:101], v173, s[38:39] offset:0
	global_load_dwordx4 v[102:105], v173, s[38:39] offset:16
	global_load_dwordx4 v[106:109], v173, s[38:39] offset:2048
	global_load_dwordx4 v[110:113], v173, s[38:39] offset:2064
	global_load_dwordx4 v[114:117], v173, s[42:43] offset:0
	global_load_dwordx4 v[118:121], v173, s[42:43] offset:16
	global_load_dwordx4 v[122:125], v173, s[42:43] offset:2048
	global_load_dwordx4 v[126:129], v173, s[42:43] offset:2064
	s_waitcnt vmcnt(16)
	v_mul_f32_e32 v50, v50, v130
	v_mul_f32_e32 v51, v51, v131
	v_mul_f32_e32 v52, v52, v132
	v_mul_f32_e32 v53, v53, v133
	v_mul_f32_e32 v54, v54, v134
	v_mul_f32_e32 v55, v55, v135
	v_mul_f32_e32 v56, v56, v136
	v_mul_f32_e32 v57, v57, v137
	v_mul_f32_e32 v58, v58, v138
	v_mul_f32_e32 v59, v59, v139
	v_mul_f32_e32 v60, v60, v140
	v_mul_f32_e32 v61, v61, v141
	v_mul_f32_e32 v62, v62, v142
	v_mul_f32_e32 v63, v63, v143
	v_mul_f32_e32 v64, v64, v144
	v_mul_f32_e32 v65, v65, v145
	v_lshlrev_b32_e32 v0, 16, v2
	v_and_b32_e32 v250, 0xffff0000, v2
	v_mul_f32_e32 v171, v0, v0
	v_fmac_f32_e32 v171, v250, v250
	v_lshlrev_b32_e32 v0, 16, v3
	v_and_b32_e32 v250, 0xffff0000, v3
	v_fmac_f32_e32 v171, v0, v0
	v_fmac_f32_e32 v171, v250, v250
	v_lshlrev_b32_e32 v0, 16, v4
	v_and_b32_e32 v250, 0xffff0000, v4
	v_fmac_f32_e32 v171, v0, v0
	v_fmac_f32_e32 v171, v250, v250
	v_lshlrev_b32_e32 v0, 16, v5
	v_and_b32_e32 v250, 0xffff0000, v5
	v_fmac_f32_e32 v171, v0, v0
	v_fmac_f32_e32 v171, v250, v250
	v_lshlrev_b32_e32 v0, 16, v6
	v_and_b32_e32 v250, 0xffff0000, v6
	v_fmac_f32_e32 v171, v0, v0
	v_fmac_f32_e32 v171, v250, v250
	v_lshlrev_b32_e32 v0, 16, v7
	v_and_b32_e32 v250, 0xffff0000, v7
	v_fmac_f32_e32 v171, v0, v0
	v_fmac_f32_e32 v171, v250, v250
	v_lshlrev_b32_e32 v0, 16, v8
	v_and_b32_e32 v250, 0xffff0000, v8
	v_fmac_f32_e32 v171, v0, v0
	v_fmac_f32_e32 v171, v250, v250
	v_lshlrev_b32_e32 v0, 16, v9
	v_and_b32_e32 v250, 0xffff0000, v9
	v_fmac_f32_e32 v171, v0, v0
	v_fmac_f32_e32 v171, v250, v250
	v_lshlrev_b32_e32 v0, 16, v10
	v_and_b32_e32 v250, 0xffff0000, v10
	v_mul_f32_e32 v172, v0, v0
	v_fmac_f32_e32 v172, v250, v250
	v_lshlrev_b32_e32 v0, 16, v11
	v_and_b32_e32 v250, 0xffff0000, v11
	v_fmac_f32_e32 v172, v0, v0
	v_fmac_f32_e32 v172, v250, v250
	v_lshlrev_b32_e32 v0, 16, v12
	v_and_b32_e32 v250, 0xffff0000, v12
	v_fmac_f32_e32 v172, v0, v0
	v_fmac_f32_e32 v172, v250, v250
	v_lshlrev_b32_e32 v0, 16, v13
	v_and_b32_e32 v250, 0xffff0000, v13
	v_fmac_f32_e32 v172, v0, v0
	v_fmac_f32_e32 v172, v250, v250
	v_lshlrev_b32_e32 v0, 16, v14
	v_and_b32_e32 v250, 0xffff0000, v14
	v_fmac_f32_e32 v172, v0, v0
	v_fmac_f32_e32 v172, v250, v250
	v_lshlrev_b32_e32 v0, 16, v15
	v_and_b32_e32 v250, 0xffff0000, v15
	v_fmac_f32_e32 v172, v0, v0
	v_fmac_f32_e32 v172, v250, v250
	v_lshlrev_b32_e32 v0, 16, v16
	v_and_b32_e32 v250, 0xffff0000, v16
	v_fmac_f32_e32 v172, v0, v0
	v_fmac_f32_e32 v172, v250, v250
	v_lshlrev_b32_e32 v0, 16, v17
	v_and_b32_e32 v250, 0xffff0000, v17
	v_fmac_f32_e32 v172, v0, v0
	v_fmac_f32_e32 v172, v250, v250
	v_mov_b32_e32 v251, v171
	v_mov_b32_e32 v170, v172
	s_nop 1
	v_permlane32_swap_b32_e32 v171, v251
	v_permlane32_swap_b32_e32 v172, v170
	v_add_f32_e32 v171, v171, v251
	v_add_f32_e32 v172, v172, v170
	ds_swizzle_b32 v251, v171 offset:0x401f
	ds_swizzle_b32 v170, v172 offset:0x401f
	s_waitcnt lgkmcnt(1)
	v_add_f32_e32 v171, v171, v251
	s_waitcnt lgkmcnt(0)
	v_add_f32_e32 v172, v172, v170
	ds_swizzle_b32 v251, v171 offset:0x201f
	ds_swizzle_b32 v170, v172 offset:0x201f
	s_waitcnt lgkmcnt(1)
	v_add_f32_e32 v171, v171, v251
	s_waitcnt lgkmcnt(0)
	v_add_f32_e32 v172, v172, v170
	ds_swizzle_b32 v251, v171 offset:0x101f
	ds_swizzle_b32 v170, v172 offset:0x101f
	s_waitcnt lgkmcnt(1)
	v_add_f32_e32 v171, v171, v251
	s_waitcnt lgkmcnt(0)
	v_add_f32_e32 v172, v172, v170
	ds_swizzle_b32 v251, v171 offset:0x81f
	ds_swizzle_b32 v170, v172 offset:0x81f
	s_waitcnt lgkmcnt(1)
	v_add_f32_e32 v171, v171, v251
	s_waitcnt lgkmcnt(0)
	v_add_f32_e32 v172, v172, v170
	ds_swizzle_b32 v251, v171 offset:0x41f
	ds_swizzle_b32 v170, v172 offset:0x41f
	s_waitcnt lgkmcnt(1)
	v_add_f32_e32 v171, v171, v251
	s_waitcnt lgkmcnt(0)
	v_add_f32_e32 v172, v172, v170
	v_fmamk_f32 v171, v171, 0x3a800000, v153
	v_fmamk_f32 v172, v172, 0x3a800000, v153
	v_rsq_f32_e32 v171, v171
	v_rsq_f32_e32 v172, v172
	s_nop 0
	s_add_u32 s28, s56, 0x0
	s_addc_u32 s29, s57, 0
	v_lshlrev_b32_e32 v0, 16, v2
	v_and_b32_e32 v250, 0xffff0000, v2
	v_mul_f32_e32 v0, v171, v0
	v_mul_f32_e32 v250, v171, v250
	v_fmac_f32_e32 v18, v50, v0
	v_fmac_f32_e32 v19, v51, v250
	v_lshlrev_b32_e32 v0, 16, v3
	v_and_b32_e32 v250, 0xffff0000, v3
	v_mul_f32_e32 v0, v171, v0
	v_mul_f32_e32 v250, v171, v250
	v_fmac_f32_e32 v20, v52, v0
	v_fmac_f32_e32 v21, v53, v250
	v_lshlrev_b32_e32 v0, 16, v4
	v_and_b32_e32 v250, 0xffff0000, v4
	v_mul_f32_e32 v0, v171, v0
	v_mul_f32_e32 v250, v171, v250
	v_fmac_f32_e32 v22, v54, v0
	v_fmac_f32_e32 v23, v55, v250
	v_lshlrev_b32_e32 v0, 16, v5
	v_and_b32_e32 v250, 0xffff0000, v5
	v_mul_f32_e32 v0, v171, v0
	v_mul_f32_e32 v250, v171, v250
	v_fmac_f32_e32 v24, v56, v0
	v_fmac_f32_e32 v25, v57, v250
	v_lshlrev_b32_e32 v0, 16, v6
	v_and_b32_e32 v250, 0xffff0000, v6
	v_mul_f32_e32 v0, v171, v0
	v_mul_f32_e32 v250, v171, v250
	v_fmac_f32_e32 v26, v58, v0
	v_fmac_f32_e32 v27, v59, v250
	v_lshlrev_b32_e32 v0, 16, v7
	v_and_b32_e32 v250, 0xffff0000, v7
	v_mul_f32_e32 v0, v171, v0
	v_mul_f32_e32 v250, v171, v250
	v_fmac_f32_e32 v28, v60, v0
	v_fmac_f32_e32 v29, v61, v250
	v_lshlrev_b32_e32 v0, 16, v8
	v_and_b32_e32 v250, 0xffff0000, v8
	v_mul_f32_e32 v0, v171, v0
	v_mul_f32_e32 v250, v171, v250
	v_fmac_f32_e32 v30, v62, v0
	v_fmac_f32_e32 v31, v63, v250
	v_lshlrev_b32_e32 v0, 16, v9
	v_and_b32_e32 v250, 0xffff0000, v9
	v_mul_f32_e32 v0, v171, v0
	v_mul_f32_e32 v250, v171, v250
	v_fmac_f32_e32 v32, v64, v0
	v_fmac_f32_e32 v33, v65, v250
	global_store_dwordx4 v173, v[18:21], s[28:29] offset:0
	global_store_dwordx4 v173, v[22:25], s[28:29] offset:16
	global_store_dwordx4 v173, v[26:29], s[28:29] offset:2048
	global_store_dwordx4 v173, v[30:33], s[28:29] offset:2064
	v_lshlrev_b32_e32 v0, 16, v10
	v_and_b32_e32 v250, 0xffff0000, v10
	v_mul_f32_e32 v0, v172, v0
	v_mul_f32_e32 v250, v172, v250
	v_fmac_f32_e32 v34, v50, v0
	v_fmac_f32_e32 v35, v51, v250
	v_lshlrev_b32_e32 v0, 16, v11
	v_and_b32_e32 v250, 0xffff0000, v11
	v_mul_f32_e32 v0, v172, v0
	v_mul_f32_e32 v250, v172, v250
	v_fmac_f32_e32 v36, v52, v0
	v_fmac_f32_e32 v37, v53, v250
	v_lshlrev_b32_e32 v0, 16, v12
	v_and_b32_e32 v250, 0xffff0000, v12
	v_mul_f32_e32 v0, v172, v0
	v_mul_f32_e32 v250, v172, v250
	v_fmac_f32_e32 v38, v54, v0
	v_fmac_f32_e32 v39, v55, v250
	v_lshlrev_b32_e32 v0, 16, v13
	v_and_b32_e32 v250, 0xffff0000, v13
	v_mul_f32_e32 v0, v172, v0
	v_mul_f32_e32 v250, v172, v250
	v_fmac_f32_e32 v40, v56, v0
	v_fmac_f32_e32 v41, v57, v250
	v_lshlrev_b32_e32 v0, 16, v14
	v_and_b32_e32 v250, 0xffff0000, v14
	v_mul_f32_e32 v0, v172, v0
	v_mul_f32_e32 v250, v172, v250
	v_fmac_f32_e32 v42, v58, v0
	v_fmac_f32_e32 v43, v59, v250
	v_lshlrev_b32_e32 v0, 16, v15
	v_and_b32_e32 v250, 0xffff0000, v15
	v_mul_f32_e32 v0, v172, v0
	v_mul_f32_e32 v250, v172, v250
	v_fmac_f32_e32 v44, v60, v0
	v_fmac_f32_e32 v45, v61, v250
	v_lshlrev_b32_e32 v0, 16, v16
	v_and_b32_e32 v250, 0xffff0000, v16
	v_mul_f32_e32 v0, v172, v0
	v_mul_f32_e32 v250, v172, v250
	v_fmac_f32_e32 v46, v62, v0
	v_fmac_f32_e32 v47, v63, v250
	v_lshlrev_b32_e32 v0, 16, v17
	v_and_b32_e32 v250, 0xffff0000, v17
	v_mul_f32_e32 v0, v172, v0
	v_mul_f32_e32 v250, v172, v250
	v_fmac_f32_e32 v48, v64, v0
	v_fmac_f32_e32 v49, v65, v250
	s_add_u32 s28, s28, 0x1000
	s_addc_u32 s29, s29, 0
	global_store_dwordx4 v173, v[34:37], s[28:29] offset:0
	global_store_dwordx4 v173, v[38:41], s[28:29] offset:16
	global_store_dwordx4 v173, v[42:45], s[28:29] offset:2048
	global_store_dwordx4 v173, v[46:49], s[28:29] offset:2064
	s_add_u32 s38, s56, 0x2000000
	s_addc_u32 s39, s57, 0
	s_add_u32 s40, s58, 0x4000000
	s_addc_u32 s41, s59, 0
	s_add_u32 s42, s60, 0x14000
	s_addc_u32 s43, s61, 0
	v_lshrrev_b32_e32 v0, 1, v173
	global_load_dwordx4 v[2:5], v0, s[40:41] offset:0
	global_load_dwordx4 v[6:9], v0, s[40:41] offset:1024
	global_load_dwordx4 v[10:13], v0, s[40:41] offset:2048
	global_load_dwordx4 v[14:17], v0, s[40:41] offset:3072
	global_load_dwordx4 v[18:21], v173, s[38:39] offset:0
	global_load_dwordx4 v[22:25], v173, s[38:39] offset:16
	global_load_dwordx4 v[26:29], v173, s[38:39] offset:2048
	global_load_dwordx4 v[30:33], v173, s[38:39] offset:2064
	s_add_u32 s38, s38, 0x1000
	s_addc_u32 s39, s39, 0
	global_load_dwordx4 v[34:37], v173, s[38:39] offset:0
	global_load_dwordx4 v[38:41], v173, s[38:39] offset:16
	global_load_dwordx4 v[42:45], v173, s[38:39] offset:2048
	global_load_dwordx4 v[46:49], v173, s[38:39] offset:2064
	global_load_dwordx4 v[50:53], v173, s[42:43] offset:0
	global_load_dwordx4 v[54:57], v173, s[42:43] offset:16
	global_load_dwordx4 v[58:61], v173, s[42:43] offset:2048
	global_load_dwordx4 v[62:65], v173, s[42:43] offset:2064
	s_waitcnt vmcnt(16)
	v_mul_f32_e32 v114, v114, v130
	v_mul_f32_e32 v115, v115, v131
	v_mul_f32_e32 v116, v116, v132
	v_mul_f32_e32 v117, v117, v133
	v_mul_f32_e32 v118, v118, v134
	v_mul_f32_e32 v119, v119, v135
	v_mul_f32_e32 v120, v120, v136
	v_mul_f32_e32 v121, v121, v137
	v_mul_f32_e32 v122, v122, v138
	v_mul_f32_e32 v123, v123, v139
	v_mul_f32_e32 v124, v124, v140
	v_mul_f32_e32 v125, v125, v141
	v_mul_f32_e32 v126, v126, v142
	v_mul_f32_e32 v127, v127, v143
	v_mul_f32_e32 v128, v128, v144
	v_mul_f32_e32 v129, v129, v145
	v_lshlrev_b32_e32 v0, 16, v66
	v_and_b32_e32 v250, 0xffff0000, v66
	v_mul_f32_e32 v171, v0, v0
	v_fmac_f32_e32 v171, v250, v250
	v_lshlrev_b32_e32 v0, 16, v67
	v_and_b32_e32 v250, 0xffff0000, v67
	v_fmac_f32_e32 v171, v0, v0
	v_fmac_f32_e32 v171, v250, v250
	v_lshlrev_b32_e32 v0, 16, v68
	v_and_b32_e32 v250, 0xffff0000, v68
	v_fmac_f32_e32 v171, v0, v0
	v_fmac_f32_e32 v171, v250, v250
	v_lshlrev_b32_e32 v0, 16, v69
	v_and_b32_e32 v250, 0xffff0000, v69
	v_fmac_f32_e32 v171, v0, v0
	v_fmac_f32_e32 v171, v250, v250
	v_lshlrev_b32_e32 v0, 16, v70
	v_and_b32_e32 v250, 0xffff0000, v70
	v_fmac_f32_e32 v171, v0, v0
	v_fmac_f32_e32 v171, v250, v250
	v_lshlrev_b32_e32 v0, 16, v71
	v_and_b32_e32 v250, 0xffff0000, v71
	v_fmac_f32_e32 v171, v0, v0
	v_fmac_f32_e32 v171, v250, v250
	v_lshlrev_b32_e32 v0, 16, v72
	v_and_b32_e32 v250, 0xffff0000, v72
	v_fmac_f32_e32 v171, v0, v0
	v_fmac_f32_e32 v171, v250, v250
	v_lshlrev_b32_e32 v0, 16, v73
	v_and_b32_e32 v250, 0xffff0000, v73
	v_fmac_f32_e32 v171, v0, v0
	v_fmac_f32_e32 v171, v250, v250
	v_lshlrev_b32_e32 v0, 16, v74
	v_and_b32_e32 v250, 0xffff0000, v74
	v_mul_f32_e32 v172, v0, v0
	v_fmac_f32_e32 v172, v250, v250
	v_lshlrev_b32_e32 v0, 16, v75
	v_and_b32_e32 v250, 0xffff0000, v75
	v_fmac_f32_e32 v172, v0, v0
	v_fmac_f32_e32 v172, v250, v250
	v_lshlrev_b32_e32 v0, 16, v76
	v_and_b32_e32 v250, 0xffff0000, v76
	v_fmac_f32_e32 v172, v0, v0
	v_fmac_f32_e32 v172, v250, v250
	v_lshlrev_b32_e32 v0, 16, v77
	v_and_b32_e32 v250, 0xffff0000, v77
	v_fmac_f32_e32 v172, v0, v0
	v_fmac_f32_e32 v172, v250, v250
	v_lshlrev_b32_e32 v0, 16, v78
	v_and_b32_e32 v250, 0xffff0000, v78
	v_fmac_f32_e32 v172, v0, v0
	v_fmac_f32_e32 v172, v250, v250
	v_lshlrev_b32_e32 v0, 16, v79
	v_and_b32_e32 v250, 0xffff0000, v79
	v_fmac_f32_e32 v172, v0, v0
	v_fmac_f32_e32 v172, v250, v250
	v_lshlrev_b32_e32 v0, 16, v80
	v_and_b32_e32 v250, 0xffff0000, v80
	v_fmac_f32_e32 v172, v0, v0
	v_fmac_f32_e32 v172, v250, v250
	v_lshlrev_b32_e32 v0, 16, v81
	v_and_b32_e32 v250, 0xffff0000, v81
	v_fmac_f32_e32 v172, v0, v0
	v_fmac_f32_e32 v172, v250, v250
	v_mov_b32_e32 v251, v171
	v_mov_b32_e32 v170, v172
	s_nop 1
	v_permlane32_swap_b32_e32 v171, v251
	v_permlane32_swap_b32_e32 v172, v170
	v_add_f32_e32 v171, v171, v251
	v_add_f32_e32 v172, v172, v170
	ds_swizzle_b32 v251, v171 offset:0x401f
	ds_swizzle_b32 v170, v172 offset:0x401f
	s_waitcnt lgkmcnt(1)
	v_add_f32_e32 v171, v171, v251
	s_waitcnt lgkmcnt(0)
	v_add_f32_e32 v172, v172, v170
	ds_swizzle_b32 v251, v171 offset:0x201f
	ds_swizzle_b32 v170, v172 offset:0x201f
	s_waitcnt lgkmcnt(1)
	v_add_f32_e32 v171, v171, v251
	s_waitcnt lgkmcnt(0)
	v_add_f32_e32 v172, v172, v170
	ds_swizzle_b32 v251, v171 offset:0x101f
	ds_swizzle_b32 v170, v172 offset:0x101f
	s_waitcnt lgkmcnt(1)
	v_add_f32_e32 v171, v171, v251
	s_waitcnt lgkmcnt(0)
	v_add_f32_e32 v172, v172, v170
	ds_swizzle_b32 v251, v171 offset:0x81f
	ds_swizzle_b32 v170, v172 offset:0x81f
	s_waitcnt lgkmcnt(1)
	v_add_f32_e32 v171, v171, v251
	s_waitcnt lgkmcnt(0)
	v_add_f32_e32 v172, v172, v170
	ds_swizzle_b32 v251, v171 offset:0x41f
	ds_swizzle_b32 v170, v172 offset:0x41f
	s_waitcnt lgkmcnt(1)
	v_add_f32_e32 v171, v171, v251
	s_waitcnt lgkmcnt(0)
	v_add_f32_e32 v172, v172, v170
	v_fmamk_f32 v171, v171, 0x3a800000, v153
	v_fmamk_f32 v172, v172, 0x3a800000, v153
	v_rsq_f32_e32 v171, v171
	v_rsq_f32_e32 v172, v172
	s_nop 0
	s_add_u32 s28, s56, 0x1000000
	s_addc_u32 s29, s57, 0
	v_lshlrev_b32_e32 v0, 16, v66
	v_and_b32_e32 v250, 0xffff0000, v66
	v_mul_f32_e32 v0, v171, v0
	v_mul_f32_e32 v250, v171, v250
	v_fmac_f32_e32 v82, v114, v0
	v_fmac_f32_e32 v83, v115, v250
	v_lshlrev_b32_e32 v0, 16, v67
	v_and_b32_e32 v250, 0xffff0000, v67
	v_mul_f32_e32 v0, v171, v0
	v_mul_f32_e32 v250, v171, v250
	v_fmac_f32_e32 v84, v116, v0
	v_fmac_f32_e32 v85, v117, v250
	v_lshlrev_b32_e32 v0, 16, v68
	v_and_b32_e32 v250, 0xffff0000, v68
	v_mul_f32_e32 v0, v171, v0
	v_mul_f32_e32 v250, v171, v250
	v_fmac_f32_e32 v86, v118, v0
	v_fmac_f32_e32 v87, v119, v250
	v_lshlrev_b32_e32 v0, 16, v69
	v_and_b32_e32 v250, 0xffff0000, v69
	v_mul_f32_e32 v0, v171, v0
	v_mul_f32_e32 v250, v171, v250
	v_fmac_f32_e32 v88, v120, v0
	v_fmac_f32_e32 v89, v121, v250
	v_lshlrev_b32_e32 v0, 16, v70
	v_and_b32_e32 v250, 0xffff0000, v70
	v_mul_f32_e32 v0, v171, v0
	v_mul_f32_e32 v250, v171, v250
	v_fmac_f32_e32 v90, v122, v0
	v_fmac_f32_e32 v91, v123, v250
	v_lshlrev_b32_e32 v0, 16, v71
	v_and_b32_e32 v250, 0xffff0000, v71
	v_mul_f32_e32 v0, v171, v0
	v_mul_f32_e32 v250, v171, v250
	v_fmac_f32_e32 v92, v124, v0
	v_fmac_f32_e32 v93, v125, v250
	v_lshlrev_b32_e32 v0, 16, v72
	v_and_b32_e32 v250, 0xffff0000, v72
	v_mul_f32_e32 v0, v171, v0
	v_mul_f32_e32 v250, v171, v250
	v_fmac_f32_e32 v94, v126, v0
	v_fmac_f32_e32 v95, v127, v250
	v_lshlrev_b32_e32 v0, 16, v73
	v_and_b32_e32 v250, 0xffff0000, v73
	v_mul_f32_e32 v0, v171, v0
	v_mul_f32_e32 v250, v171, v250
	v_fmac_f32_e32 v96, v128, v0
	v_fmac_f32_e32 v97, v129, v250
	global_store_dwordx4 v173, v[82:85], s[28:29] offset:0
	global_store_dwordx4 v173, v[86:89], s[28:29] offset:16
	global_store_dwordx4 v173, v[90:93], s[28:29] offset:2048
	global_store_dwordx4 v173, v[94:97], s[28:29] offset:2064
	v_lshlrev_b32_e32 v0, 16, v74
	v_and_b32_e32 v250, 0xffff0000, v74
	v_mul_f32_e32 v0, v172, v0
	v_mul_f32_e32 v250, v172, v250
	v_fmac_f32_e32 v98, v114, v0
	v_fmac_f32_e32 v99, v115, v250
	v_lshlrev_b32_e32 v0, 16, v75
	v_and_b32_e32 v250, 0xffff0000, v75
	v_mul_f32_e32 v0, v172, v0
	v_mul_f32_e32 v250, v172, v250
	v_fmac_f32_e32 v100, v116, v0
	v_fmac_f32_e32 v101, v117, v250
	v_lshlrev_b32_e32 v0, 16, v76
	v_and_b32_e32 v250, 0xffff0000, v76
	v_mul_f32_e32 v0, v172, v0
	v_mul_f32_e32 v250, v172, v250
	v_fmac_f32_e32 v102, v118, v0
	v_fmac_f32_e32 v103, v119, v250
	v_lshlrev_b32_e32 v0, 16, v77
	v_and_b32_e32 v250, 0xffff0000, v77
	v_mul_f32_e32 v0, v172, v0
	v_mul_f32_e32 v250, v172, v250
	v_fmac_f32_e32 v104, v120, v0
	v_fmac_f32_e32 v105, v121, v250
	v_lshlrev_b32_e32 v0, 16, v78
	v_and_b32_e32 v250, 0xffff0000, v78
	v_mul_f32_e32 v0, v172, v0
	v_mul_f32_e32 v250, v172, v250
	v_fmac_f32_e32 v106, v122, v0
	v_fmac_f32_e32 v107, v123, v250
	v_lshlrev_b32_e32 v0, 16, v79
	v_and_b32_e32 v250, 0xffff0000, v79
	v_mul_f32_e32 v0, v172, v0
	v_mul_f32_e32 v250, v172, v250
	v_fmac_f32_e32 v108, v124, v0
	v_fmac_f32_e32 v109, v125, v250
	v_lshlrev_b32_e32 v0, 16, v80
	v_and_b32_e32 v250, 0xffff0000, v80
	v_mul_f32_e32 v0, v172, v0
	v_mul_f32_e32 v250, v172, v250
	v_fmac_f32_e32 v110, v126, v0
	v_fmac_f32_e32 v111, v127, v250
	v_lshlrev_b32_e32 v0, 16, v81
	v_and_b32_e32 v250, 0xffff0000, v81
	v_mul_f32_e32 v0, v172, v0
	v_mul_f32_e32 v250, v172, v250
	v_fmac_f32_e32 v112, v128, v0
	v_fmac_f32_e32 v113, v129, v250
	s_add_u32 s28, s28, 0x1000
	s_addc_u32 s29, s29, 0
	global_store_dwordx4 v173, v[98:101], s[28:29] offset:0
	global_store_dwordx4 v173, v[102:105], s[28:29] offset:16
	global_store_dwordx4 v173, v[106:109], s[28:29] offset:2048
	global_store_dwordx4 v173, v[110:113], s[28:29] offset:2064
	s_add_u32 s38, s56, 0x3000000
	s_addc_u32 s39, s57, 0
	s_add_u32 s40, s58, 0x4800000
	s_addc_u32 s41, s59, 0
	s_add_u32 s42, s60, 0x17000
	s_addc_u32 s43, s61, 0
	v_lshrrev_b32_e32 v0, 1, v173
	global_load_dwordx4 v[66:69], v0, s[40:41] offset:0
	global_load_dwordx4 v[70:73], v0, s[40:41] offset:1024
	global_load_dwordx4 v[74:77], v0, s[40:41] offset:2048
	global_load_dwordx4 v[78:81], v0, s[40:41] offset:3072
	global_load_dwordx4 v[82:85], v173, s[38:39] offset:0
	global_load_dwordx4 v[86:89], v173, s[38:39] offset:16
	global_load_dwordx4 v[90:93], v173, s[38:39] offset:2048
	global_load_dwordx4 v[94:97], v173, s[38:39] offset:2064
	s_add_u32 s38, s38, 0x1000
	s_addc_u32 s39, s39, 0
	global_load_dwordx4 v[98:101], v173, s[38:39] offset:0
	global_load_dwordx4 v[102:105], v173, s[38:39] offset:16
	global_load_dwordx4 v[106:109], v173, s[38:39] offset:2048
	global_load_dwordx4 v[110:113], v173, s[38:39] offset:2064
	global_load_dwordx4 v[114:117], v173, s[42:43] offset:0
	global_load_dwordx4 v[118:121], v173, s[42:43] offset:16
	global_load_dwordx4 v[122:125], v173, s[42:43] offset:2048
	global_load_dwordx4 v[126:129], v173, s[42:43] offset:2064
	s_waitcnt vmcnt(16)
	v_mul_f32_e32 v50, v50, v130
	v_mul_f32_e32 v51, v51, v131
	v_mul_f32_e32 v52, v52, v132
	v_mul_f32_e32 v53, v53, v133
	v_mul_f32_e32 v54, v54, v134
	v_mul_f32_e32 v55, v55, v135
	v_mul_f32_e32 v56, v56, v136
	v_mul_f32_e32 v57, v57, v137
	v_mul_f32_e32 v58, v58, v138
	v_mul_f32_e32 v59, v59, v139
	v_mul_f32_e32 v60, v60, v140
	v_mul_f32_e32 v61, v61, v141
	v_mul_f32_e32 v62, v62, v142
	v_mul_f32_e32 v63, v63, v143
	v_mul_f32_e32 v64, v64, v144
	v_mul_f32_e32 v65, v65, v145
	v_lshlrev_b32_e32 v0, 16, v2
	v_and_b32_e32 v250, 0xffff0000, v2
	v_mul_f32_e32 v171, v0, v0
	v_fmac_f32_e32 v171, v250, v250
	v_lshlrev_b32_e32 v0, 16, v3
	v_and_b32_e32 v250, 0xffff0000, v3
	v_fmac_f32_e32 v171, v0, v0
	v_fmac_f32_e32 v171, v250, v250
	v_lshlrev_b32_e32 v0, 16, v4
	v_and_b32_e32 v250, 0xffff0000, v4
	v_fmac_f32_e32 v171, v0, v0
	v_fmac_f32_e32 v171, v250, v250
	v_lshlrev_b32_e32 v0, 16, v5
	v_and_b32_e32 v250, 0xffff0000, v5
	v_fmac_f32_e32 v171, v0, v0
	v_fmac_f32_e32 v171, v250, v250
	v_lshlrev_b32_e32 v0, 16, v6
	v_and_b32_e32 v250, 0xffff0000, v6
	v_fmac_f32_e32 v171, v0, v0
	v_fmac_f32_e32 v171, v250, v250
	v_lshlrev_b32_e32 v0, 16, v7
	v_and_b32_e32 v250, 0xffff0000, v7
	v_fmac_f32_e32 v171, v0, v0
	v_fmac_f32_e32 v171, v250, v250
	v_lshlrev_b32_e32 v0, 16, v8
	v_and_b32_e32 v250, 0xffff0000, v8
	v_fmac_f32_e32 v171, v0, v0
	v_fmac_f32_e32 v171, v250, v250
	v_lshlrev_b32_e32 v0, 16, v9
	v_and_b32_e32 v250, 0xffff0000, v9
	v_fmac_f32_e32 v171, v0, v0
	v_fmac_f32_e32 v171, v250, v250
	v_lshlrev_b32_e32 v0, 16, v10
	v_and_b32_e32 v250, 0xffff0000, v10
	v_mul_f32_e32 v172, v0, v0
	v_fmac_f32_e32 v172, v250, v250
	v_lshlrev_b32_e32 v0, 16, v11
	v_and_b32_e32 v250, 0xffff0000, v11
	v_fmac_f32_e32 v172, v0, v0
	v_fmac_f32_e32 v172, v250, v250
	v_lshlrev_b32_e32 v0, 16, v12
	v_and_b32_e32 v250, 0xffff0000, v12
	v_fmac_f32_e32 v172, v0, v0
	v_fmac_f32_e32 v172, v250, v250
	v_lshlrev_b32_e32 v0, 16, v13
	v_and_b32_e32 v250, 0xffff0000, v13
	v_fmac_f32_e32 v172, v0, v0
	v_fmac_f32_e32 v172, v250, v250
	v_lshlrev_b32_e32 v0, 16, v14
	v_and_b32_e32 v250, 0xffff0000, v14
	v_fmac_f32_e32 v172, v0, v0
	v_fmac_f32_e32 v172, v250, v250
	v_lshlrev_b32_e32 v0, 16, v15
	v_and_b32_e32 v250, 0xffff0000, v15
	v_fmac_f32_e32 v172, v0, v0
	v_fmac_f32_e32 v172, v250, v250
	v_lshlrev_b32_e32 v0, 16, v16
	v_and_b32_e32 v250, 0xffff0000, v16
	v_fmac_f32_e32 v172, v0, v0
	v_fmac_f32_e32 v172, v250, v250
	v_lshlrev_b32_e32 v0, 16, v17
	v_and_b32_e32 v250, 0xffff0000, v17
	v_fmac_f32_e32 v172, v0, v0
	v_fmac_f32_e32 v172, v250, v250
	v_mov_b32_e32 v251, v171
	v_mov_b32_e32 v170, v172
	s_nop 1
	v_permlane32_swap_b32_e32 v171, v251
	v_permlane32_swap_b32_e32 v172, v170
	v_add_f32_e32 v171, v171, v251
	v_add_f32_e32 v172, v172, v170
	ds_swizzle_b32 v251, v171 offset:0x401f
	ds_swizzle_b32 v170, v172 offset:0x401f
	s_waitcnt lgkmcnt(1)
	v_add_f32_e32 v171, v171, v251
	s_waitcnt lgkmcnt(0)
	v_add_f32_e32 v172, v172, v170
	ds_swizzle_b32 v251, v171 offset:0x201f
	ds_swizzle_b32 v170, v172 offset:0x201f
	s_waitcnt lgkmcnt(1)
	v_add_f32_e32 v171, v171, v251
	s_waitcnt lgkmcnt(0)
	v_add_f32_e32 v172, v172, v170
	ds_swizzle_b32 v251, v171 offset:0x101f
	ds_swizzle_b32 v170, v172 offset:0x101f
	s_waitcnt lgkmcnt(1)
	v_add_f32_e32 v171, v171, v251
	s_waitcnt lgkmcnt(0)
	v_add_f32_e32 v172, v172, v170
	ds_swizzle_b32 v251, v171 offset:0x81f
	ds_swizzle_b32 v170, v172 offset:0x81f
	s_waitcnt lgkmcnt(1)
	v_add_f32_e32 v171, v171, v251
	s_waitcnt lgkmcnt(0)
	v_add_f32_e32 v172, v172, v170
	ds_swizzle_b32 v251, v171 offset:0x41f
	ds_swizzle_b32 v170, v172 offset:0x41f
	s_waitcnt lgkmcnt(1)
	v_add_f32_e32 v171, v171, v251
	s_waitcnt lgkmcnt(0)
	v_add_f32_e32 v172, v172, v170
	v_fmamk_f32 v171, v171, 0x3a800000, v153
	v_fmamk_f32 v172, v172, 0x3a800000, v153
	v_rsq_f32_e32 v171, v171
	v_rsq_f32_e32 v172, v172
	s_nop 0
	s_add_u32 s28, s56, 0x2000000
	s_addc_u32 s29, s57, 0
	v_lshlrev_b32_e32 v0, 16, v2
	v_and_b32_e32 v250, 0xffff0000, v2
	v_mul_f32_e32 v0, v171, v0
	v_mul_f32_e32 v250, v171, v250
	v_fmac_f32_e32 v18, v50, v0
	v_fmac_f32_e32 v19, v51, v250
	v_lshlrev_b32_e32 v0, 16, v3
	v_and_b32_e32 v250, 0xffff0000, v3
	v_mul_f32_e32 v0, v171, v0
	v_mul_f32_e32 v250, v171, v250
	v_fmac_f32_e32 v20, v52, v0
	v_fmac_f32_e32 v21, v53, v250
	v_lshlrev_b32_e32 v0, 16, v4
	v_and_b32_e32 v250, 0xffff0000, v4
	v_mul_f32_e32 v0, v171, v0
	v_mul_f32_e32 v250, v171, v250
	v_fmac_f32_e32 v22, v54, v0
	v_fmac_f32_e32 v23, v55, v250
	v_lshlrev_b32_e32 v0, 16, v5
	v_and_b32_e32 v250, 0xffff0000, v5
	v_mul_f32_e32 v0, v171, v0
	v_mul_f32_e32 v250, v171, v250
	v_fmac_f32_e32 v24, v56, v0
	v_fmac_f32_e32 v25, v57, v250
	v_lshlrev_b32_e32 v0, 16, v6
	v_and_b32_e32 v250, 0xffff0000, v6
	v_mul_f32_e32 v0, v171, v0
	v_mul_f32_e32 v250, v171, v250
	v_fmac_f32_e32 v26, v58, v0
	v_fmac_f32_e32 v27, v59, v250
	v_lshlrev_b32_e32 v0, 16, v7
	v_and_b32_e32 v250, 0xffff0000, v7
	v_mul_f32_e32 v0, v171, v0
	v_mul_f32_e32 v250, v171, v250
	v_fmac_f32_e32 v28, v60, v0
	v_fmac_f32_e32 v29, v61, v250
	v_lshlrev_b32_e32 v0, 16, v8
	v_and_b32_e32 v250, 0xffff0000, v8
	v_mul_f32_e32 v0, v171, v0
	v_mul_f32_e32 v250, v171, v250
	v_fmac_f32_e32 v30, v62, v0
	v_fmac_f32_e32 v31, v63, v250
	v_lshlrev_b32_e32 v0, 16, v9
	v_and_b32_e32 v250, 0xffff0000, v9
	v_mul_f32_e32 v0, v171, v0
	v_mul_f32_e32 v250, v171, v250
	v_fmac_f32_e32 v32, v64, v0
	v_fmac_f32_e32 v33, v65, v250
	global_store_dwordx4 v173, v[18:21], s[28:29] offset:0
	global_store_dwordx4 v173, v[22:25], s[28:29] offset:16
	global_store_dwordx4 v173, v[26:29], s[28:29] offset:2048
	global_store_dwordx4 v173, v[30:33], s[28:29] offset:2064
	v_lshlrev_b32_e32 v0, 16, v10
	v_and_b32_e32 v250, 0xffff0000, v10
	v_mul_f32_e32 v0, v172, v0
	v_mul_f32_e32 v250, v172, v250
	v_fmac_f32_e32 v34, v50, v0
	v_fmac_f32_e32 v35, v51, v250
	v_lshlrev_b32_e32 v0, 16, v11
	v_and_b32_e32 v250, 0xffff0000, v11
	v_mul_f32_e32 v0, v172, v0
	v_mul_f32_e32 v250, v172, v250
	v_fmac_f32_e32 v36, v52, v0
	v_fmac_f32_e32 v37, v53, v250
	v_lshlrev_b32_e32 v0, 16, v12
	v_and_b32_e32 v250, 0xffff0000, v12
	v_mul_f32_e32 v0, v172, v0
	v_mul_f32_e32 v250, v172, v250
	v_fmac_f32_e32 v38, v54, v0
	v_fmac_f32_e32 v39, v55, v250
	v_lshlrev_b32_e32 v0, 16, v13
	v_and_b32_e32 v250, 0xffff0000, v13
	v_mul_f32_e32 v0, v172, v0
	v_mul_f32_e32 v250, v172, v250
	v_fmac_f32_e32 v40, v56, v0
	v_fmac_f32_e32 v41, v57, v250
	v_lshlrev_b32_e32 v0, 16, v14
	v_and_b32_e32 v250, 0xffff0000, v14
	v_mul_f32_e32 v0, v172, v0
	v_mul_f32_e32 v250, v172, v250
	v_fmac_f32_e32 v42, v58, v0
	v_fmac_f32_e32 v43, v59, v250
	v_lshlrev_b32_e32 v0, 16, v15
	v_and_b32_e32 v250, 0xffff0000, v15
	v_mul_f32_e32 v0, v172, v0
	v_mul_f32_e32 v250, v172, v250
	v_fmac_f32_e32 v44, v60, v0
	v_fmac_f32_e32 v45, v61, v250
	v_lshlrev_b32_e32 v0, 16, v16
	v_and_b32_e32 v250, 0xffff0000, v16
	v_mul_f32_e32 v0, v172, v0
	v_mul_f32_e32 v250, v172, v250
	v_fmac_f32_e32 v46, v62, v0
	v_fmac_f32_e32 v47, v63, v250
	v_lshlrev_b32_e32 v0, 16, v17
	v_and_b32_e32 v250, 0xffff0000, v17
	v_mul_f32_e32 v0, v172, v0
	v_mul_f32_e32 v250, v172, v250
	v_fmac_f32_e32 v48, v64, v0
	v_fmac_f32_e32 v49, v65, v250
	s_add_u32 s28, s28, 0x1000
	s_addc_u32 s29, s29, 0
	global_store_dwordx4 v173, v[34:37], s[28:29] offset:0
	global_store_dwordx4 v173, v[38:41], s[28:29] offset:16
	global_store_dwordx4 v173, v[42:45], s[28:29] offset:2048
	global_store_dwordx4 v173, v[46:49], s[28:29] offset:2064
	s_add_u32 s38, s56, 0x4000000
	s_addc_u32 s39, s57, 0
	s_add_u32 s40, s58, 0x5000000
	s_addc_u32 s41, s59, 0
	s_add_u32 s42, s60, 0x1a000
	s_addc_u32 s43, s61, 0
	v_lshrrev_b32_e32 v0, 1, v173
	global_load_dwordx4 v[2:5], v0, s[40:41] offset:0
	global_load_dwordx4 v[6:9], v0, s[40:41] offset:1024
	global_load_dwordx4 v[10:13], v0, s[40:41] offset:2048
	global_load_dwordx4 v[14:17], v0, s[40:41] offset:3072
	global_load_dwordx4 v[18:21], v173, s[38:39] offset:0
	global_load_dwordx4 v[22:25], v173, s[38:39] offset:16
	global_load_dwordx4 v[26:29], v173, s[38:39] offset:2048
	global_load_dwordx4 v[30:33], v173, s[38:39] offset:2064
	s_add_u32 s38, s38, 0x1000
	s_addc_u32 s39, s39, 0
	global_load_dwordx4 v[34:37], v173, s[38:39] offset:0
	global_load_dwordx4 v[38:41], v173, s[38:39] offset:16
	global_load_dwordx4 v[42:45], v173, s[38:39] offset:2048
	global_load_dwordx4 v[46:49], v173, s[38:39] offset:2064
	global_load_dwordx4 v[50:53], v173, s[42:43] offset:0
	global_load_dwordx4 v[54:57], v173, s[42:43] offset:16
	global_load_dwordx4 v[58:61], v173, s[42:43] offset:2048
	global_load_dwordx4 v[62:65], v173, s[42:43] offset:2064
	s_waitcnt vmcnt(16)
	v_mul_f32_e32 v114, v114, v130
	v_mul_f32_e32 v115, v115, v131
	v_mul_f32_e32 v116, v116, v132
	v_mul_f32_e32 v117, v117, v133
	v_mul_f32_e32 v118, v118, v134
	v_mul_f32_e32 v119, v119, v135
	v_mul_f32_e32 v120, v120, v136
	v_mul_f32_e32 v121, v121, v137
	v_mul_f32_e32 v122, v122, v138
	v_mul_f32_e32 v123, v123, v139
	v_mul_f32_e32 v124, v124, v140
	v_mul_f32_e32 v125, v125, v141
	v_mul_f32_e32 v126, v126, v142
	v_mul_f32_e32 v127, v127, v143
	v_mul_f32_e32 v128, v128, v144
	v_mul_f32_e32 v129, v129, v145
	v_lshlrev_b32_e32 v0, 16, v66
	v_and_b32_e32 v250, 0xffff0000, v66
	v_mul_f32_e32 v171, v0, v0
	v_fmac_f32_e32 v171, v250, v250
	v_lshlrev_b32_e32 v0, 16, v67
	v_and_b32_e32 v250, 0xffff0000, v67
	v_fmac_f32_e32 v171, v0, v0
	v_fmac_f32_e32 v171, v250, v250
	v_lshlrev_b32_e32 v0, 16, v68
	v_and_b32_e32 v250, 0xffff0000, v68
	v_fmac_f32_e32 v171, v0, v0
	v_fmac_f32_e32 v171, v250, v250
	v_lshlrev_b32_e32 v0, 16, v69
	v_and_b32_e32 v250, 0xffff0000, v69
	v_fmac_f32_e32 v171, v0, v0
	v_fmac_f32_e32 v171, v250, v250
	v_lshlrev_b32_e32 v0, 16, v70
	v_and_b32_e32 v250, 0xffff0000, v70
	v_fmac_f32_e32 v171, v0, v0
	v_fmac_f32_e32 v171, v250, v250
	v_lshlrev_b32_e32 v0, 16, v71
	v_and_b32_e32 v250, 0xffff0000, v71
	v_fmac_f32_e32 v171, v0, v0
	v_fmac_f32_e32 v171, v250, v250
	v_lshlrev_b32_e32 v0, 16, v72
	v_and_b32_e32 v250, 0xffff0000, v72
	v_fmac_f32_e32 v171, v0, v0
	v_fmac_f32_e32 v171, v250, v250
	v_lshlrev_b32_e32 v0, 16, v73
	v_and_b32_e32 v250, 0xffff0000, v73
	v_fmac_f32_e32 v171, v0, v0
	v_fmac_f32_e32 v171, v250, v250
	v_lshlrev_b32_e32 v0, 16, v74
	v_and_b32_e32 v250, 0xffff0000, v74
	v_mul_f32_e32 v172, v0, v0
	v_fmac_f32_e32 v172, v250, v250
	v_lshlrev_b32_e32 v0, 16, v75
	v_and_b32_e32 v250, 0xffff0000, v75
	v_fmac_f32_e32 v172, v0, v0
	v_fmac_f32_e32 v172, v250, v250
	v_lshlrev_b32_e32 v0, 16, v76
	v_and_b32_e32 v250, 0xffff0000, v76
	v_fmac_f32_e32 v172, v0, v0
	v_fmac_f32_e32 v172, v250, v250
	v_lshlrev_b32_e32 v0, 16, v77
	v_and_b32_e32 v250, 0xffff0000, v77
	v_fmac_f32_e32 v172, v0, v0
	v_fmac_f32_e32 v172, v250, v250
	v_lshlrev_b32_e32 v0, 16, v78
	v_and_b32_e32 v250, 0xffff0000, v78
	v_fmac_f32_e32 v172, v0, v0
	v_fmac_f32_e32 v172, v250, v250
	v_lshlrev_b32_e32 v0, 16, v79
	v_and_b32_e32 v250, 0xffff0000, v79
	v_fmac_f32_e32 v172, v0, v0
	v_fmac_f32_e32 v172, v250, v250
	v_lshlrev_b32_e32 v0, 16, v80
	v_and_b32_e32 v250, 0xffff0000, v80
	v_fmac_f32_e32 v172, v0, v0
	v_fmac_f32_e32 v172, v250, v250
	v_lshlrev_b32_e32 v0, 16, v81
	v_and_b32_e32 v250, 0xffff0000, v81
	v_fmac_f32_e32 v172, v0, v0
	v_fmac_f32_e32 v172, v250, v250
	v_mov_b32_e32 v251, v171
	v_mov_b32_e32 v170, v172
	s_nop 1
	v_permlane32_swap_b32_e32 v171, v251
	v_permlane32_swap_b32_e32 v172, v170
	v_add_f32_e32 v171, v171, v251
	v_add_f32_e32 v172, v172, v170
	ds_swizzle_b32 v251, v171 offset:0x401f
	ds_swizzle_b32 v170, v172 offset:0x401f
	s_waitcnt lgkmcnt(1)
	v_add_f32_e32 v171, v171, v251
	s_waitcnt lgkmcnt(0)
	v_add_f32_e32 v172, v172, v170
	ds_swizzle_b32 v251, v171 offset:0x201f
	ds_swizzle_b32 v170, v172 offset:0x201f
	s_waitcnt lgkmcnt(1)
	v_add_f32_e32 v171, v171, v251
	s_waitcnt lgkmcnt(0)
	v_add_f32_e32 v172, v172, v170
	ds_swizzle_b32 v251, v171 offset:0x101f
	ds_swizzle_b32 v170, v172 offset:0x101f
	s_waitcnt lgkmcnt(1)
	v_add_f32_e32 v171, v171, v251
	s_waitcnt lgkmcnt(0)
	v_add_f32_e32 v172, v172, v170
	ds_swizzle_b32 v251, v171 offset:0x81f
	ds_swizzle_b32 v170, v172 offset:0x81f
	s_waitcnt lgkmcnt(1)
	v_add_f32_e32 v171, v171, v251
	s_waitcnt lgkmcnt(0)
	v_add_f32_e32 v172, v172, v170
	ds_swizzle_b32 v251, v171 offset:0x41f
	ds_swizzle_b32 v170, v172 offset:0x41f
	s_waitcnt lgkmcnt(1)
	v_add_f32_e32 v171, v171, v251
	s_waitcnt lgkmcnt(0)
	v_add_f32_e32 v172, v172, v170
	v_fmamk_f32 v171, v171, 0x3a800000, v153
	v_fmamk_f32 v172, v172, 0x3a800000, v153
	v_rsq_f32_e32 v171, v171
	v_rsq_f32_e32 v172, v172
	s_nop 0
	s_add_u32 s28, s56, 0x3000000
	s_addc_u32 s29, s57, 0
	v_lshlrev_b32_e32 v0, 16, v66
	v_and_b32_e32 v250, 0xffff0000, v66
	v_mul_f32_e32 v0, v171, v0
	v_mul_f32_e32 v250, v171, v250
	v_fmac_f32_e32 v82, v114, v0
	v_fmac_f32_e32 v83, v115, v250
	v_lshlrev_b32_e32 v0, 16, v67
	v_and_b32_e32 v250, 0xffff0000, v67
	v_mul_f32_e32 v0, v171, v0
	v_mul_f32_e32 v250, v171, v250
	v_fmac_f32_e32 v84, v116, v0
	v_fmac_f32_e32 v85, v117, v250
	v_lshlrev_b32_e32 v0, 16, v68
	v_and_b32_e32 v250, 0xffff0000, v68
	v_mul_f32_e32 v0, v171, v0
	v_mul_f32_e32 v250, v171, v250
	v_fmac_f32_e32 v86, v118, v0
	v_fmac_f32_e32 v87, v119, v250
	v_lshlrev_b32_e32 v0, 16, v69
	v_and_b32_e32 v250, 0xffff0000, v69
	v_mul_f32_e32 v0, v171, v0
	v_mul_f32_e32 v250, v171, v250
	v_fmac_f32_e32 v88, v120, v0
	v_fmac_f32_e32 v89, v121, v250
	v_lshlrev_b32_e32 v0, 16, v70
	v_and_b32_e32 v250, 0xffff0000, v70
	v_mul_f32_e32 v0, v171, v0
	v_mul_f32_e32 v250, v171, v250
	v_fmac_f32_e32 v90, v122, v0
	v_fmac_f32_e32 v91, v123, v250
	v_lshlrev_b32_e32 v0, 16, v71
	v_and_b32_e32 v250, 0xffff0000, v71
	v_mul_f32_e32 v0, v171, v0
	v_mul_f32_e32 v250, v171, v250
	v_fmac_f32_e32 v92, v124, v0
	v_fmac_f32_e32 v93, v125, v250
	v_lshlrev_b32_e32 v0, 16, v72
	v_and_b32_e32 v250, 0xffff0000, v72
	v_mul_f32_e32 v0, v171, v0
	v_mul_f32_e32 v250, v171, v250
	v_fmac_f32_e32 v94, v126, v0
	v_fmac_f32_e32 v95, v127, v250
	v_lshlrev_b32_e32 v0, 16, v73
	v_and_b32_e32 v250, 0xffff0000, v73
	v_mul_f32_e32 v0, v171, v0
	v_mul_f32_e32 v250, v171, v250
	v_fmac_f32_e32 v96, v128, v0
	v_fmac_f32_e32 v97, v129, v250
	global_store_dwordx4 v173, v[82:85], s[28:29] offset:0
	global_store_dwordx4 v173, v[86:89], s[28:29] offset:16
	global_store_dwordx4 v173, v[90:93], s[28:29] offset:2048
	global_store_dwordx4 v173, v[94:97], s[28:29] offset:2064
	v_lshlrev_b32_e32 v0, 16, v74
	v_and_b32_e32 v250, 0xffff0000, v74
	v_mul_f32_e32 v0, v172, v0
	v_mul_f32_e32 v250, v172, v250
	v_fmac_f32_e32 v98, v114, v0
	v_fmac_f32_e32 v99, v115, v250
	v_lshlrev_b32_e32 v0, 16, v75
	v_and_b32_e32 v250, 0xffff0000, v75
	v_mul_f32_e32 v0, v172, v0
	v_mul_f32_e32 v250, v172, v250
	v_fmac_f32_e32 v100, v116, v0
	v_fmac_f32_e32 v101, v117, v250
	v_lshlrev_b32_e32 v0, 16, v76
	v_and_b32_e32 v250, 0xffff0000, v76
	v_mul_f32_e32 v0, v172, v0
	v_mul_f32_e32 v250, v172, v250
	v_fmac_f32_e32 v102, v118, v0
	v_fmac_f32_e32 v103, v119, v250
	v_lshlrev_b32_e32 v0, 16, v77
	v_and_b32_e32 v250, 0xffff0000, v77
	v_mul_f32_e32 v0, v172, v0
	v_mul_f32_e32 v250, v172, v250
	v_fmac_f32_e32 v104, v120, v0
	v_fmac_f32_e32 v105, v121, v250
	v_lshlrev_b32_e32 v0, 16, v78
	v_and_b32_e32 v250, 0xffff0000, v78
	v_mul_f32_e32 v0, v172, v0
	v_mul_f32_e32 v250, v172, v250
	v_fmac_f32_e32 v106, v122, v0
	v_fmac_f32_e32 v107, v123, v250
	v_lshlrev_b32_e32 v0, 16, v79
	v_and_b32_e32 v250, 0xffff0000, v79
	v_mul_f32_e32 v0, v172, v0
	v_mul_f32_e32 v250, v172, v250
	v_fmac_f32_e32 v108, v124, v0
	v_fmac_f32_e32 v109, v125, v250
	v_lshlrev_b32_e32 v0, 16, v80
	v_and_b32_e32 v250, 0xffff0000, v80
	v_mul_f32_e32 v0, v172, v0
	v_mul_f32_e32 v250, v172, v250
	v_fmac_f32_e32 v110, v126, v0
	v_fmac_f32_e32 v111, v127, v250
	v_lshlrev_b32_e32 v0, 16, v81
	v_and_b32_e32 v250, 0xffff0000, v81
	v_mul_f32_e32 v0, v172, v0
	v_mul_f32_e32 v250, v172, v250
	v_fmac_f32_e32 v112, v128, v0
	v_fmac_f32_e32 v113, v129, v250
	s_add_u32 s28, s28, 0x1000
	s_addc_u32 s29, s29, 0
	global_store_dwordx4 v173, v[98:101], s[28:29] offset:0
	global_store_dwordx4 v173, v[102:105], s[28:29] offset:16
	global_store_dwordx4 v173, v[106:109], s[28:29] offset:2048
	global_store_dwordx4 v173, v[110:113], s[28:29] offset:2064
	s_add_u32 s38, s56, 0x5000000
	s_addc_u32 s39, s57, 0
	s_add_u32 s40, s58, 0x5800000
	s_addc_u32 s41, s59, 0
	s_add_u32 s42, s60, 0x1d000
	s_addc_u32 s43, s61, 0
	v_lshrrev_b32_e32 v0, 1, v173
	global_load_dwordx4 v[66:69], v0, s[40:41] offset:0
	global_load_dwordx4 v[70:73], v0, s[40:41] offset:1024
	global_load_dwordx4 v[74:77], v0, s[40:41] offset:2048
	global_load_dwordx4 v[78:81], v0, s[40:41] offset:3072
	global_load_dwordx4 v[82:85], v173, s[38:39] offset:0
	global_load_dwordx4 v[86:89], v173, s[38:39] offset:16
	global_load_dwordx4 v[90:93], v173, s[38:39] offset:2048
	global_load_dwordx4 v[94:97], v173, s[38:39] offset:2064
	s_add_u32 s38, s38, 0x1000
	s_addc_u32 s39, s39, 0
	global_load_dwordx4 v[98:101], v173, s[38:39] offset:0
	global_load_dwordx4 v[102:105], v173, s[38:39] offset:16
	global_load_dwordx4 v[106:109], v173, s[38:39] offset:2048
	global_load_dwordx4 v[110:113], v173, s[38:39] offset:2064
	global_load_dwordx4 v[114:117], v173, s[42:43] offset:0
	global_load_dwordx4 v[118:121], v173, s[42:43] offset:16
	global_load_dwordx4 v[122:125], v173, s[42:43] offset:2048
	global_load_dwordx4 v[126:129], v173, s[42:43] offset:2064
	s_waitcnt vmcnt(16)
	v_mul_f32_e32 v50, v50, v130
	v_mul_f32_e32 v51, v51, v131
	v_mul_f32_e32 v52, v52, v132
	v_mul_f32_e32 v53, v53, v133
	v_mul_f32_e32 v54, v54, v134
	v_mul_f32_e32 v55, v55, v135
	v_mul_f32_e32 v56, v56, v136
	v_mul_f32_e32 v57, v57, v137
	v_mul_f32_e32 v58, v58, v138
	v_mul_f32_e32 v59, v59, v139
	v_mul_f32_e32 v60, v60, v140
	v_mul_f32_e32 v61, v61, v141
	v_mul_f32_e32 v62, v62, v142
	v_mul_f32_e32 v63, v63, v143
	v_mul_f32_e32 v64, v64, v144
	v_mul_f32_e32 v65, v65, v145
	v_lshlrev_b32_e32 v0, 16, v2
	v_and_b32_e32 v250, 0xffff0000, v2
	v_mul_f32_e32 v171, v0, v0
	v_fmac_f32_e32 v171, v250, v250
	v_lshlrev_b32_e32 v0, 16, v3
	v_and_b32_e32 v250, 0xffff0000, v3
	v_fmac_f32_e32 v171, v0, v0
	v_fmac_f32_e32 v171, v250, v250
	v_lshlrev_b32_e32 v0, 16, v4
	v_and_b32_e32 v250, 0xffff0000, v4
	v_fmac_f32_e32 v171, v0, v0
	v_fmac_f32_e32 v171, v250, v250
	v_lshlrev_b32_e32 v0, 16, v5
	v_and_b32_e32 v250, 0xffff0000, v5
	v_fmac_f32_e32 v171, v0, v0
	v_fmac_f32_e32 v171, v250, v250
	v_lshlrev_b32_e32 v0, 16, v6
	v_and_b32_e32 v250, 0xffff0000, v6
	v_fmac_f32_e32 v171, v0, v0
	v_fmac_f32_e32 v171, v250, v250
	v_lshlrev_b32_e32 v0, 16, v7
	v_and_b32_e32 v250, 0xffff0000, v7
	v_fmac_f32_e32 v171, v0, v0
	v_fmac_f32_e32 v171, v250, v250
	v_lshlrev_b32_e32 v0, 16, v8
	v_and_b32_e32 v250, 0xffff0000, v8
	v_fmac_f32_e32 v171, v0, v0
	v_fmac_f32_e32 v171, v250, v250
	v_lshlrev_b32_e32 v0, 16, v9
	v_and_b32_e32 v250, 0xffff0000, v9
	v_fmac_f32_e32 v171, v0, v0
	v_fmac_f32_e32 v171, v250, v250
	v_lshlrev_b32_e32 v0, 16, v10
	v_and_b32_e32 v250, 0xffff0000, v10
	v_mul_f32_e32 v172, v0, v0
	v_fmac_f32_e32 v172, v250, v250
	v_lshlrev_b32_e32 v0, 16, v11
	v_and_b32_e32 v250, 0xffff0000, v11
	v_fmac_f32_e32 v172, v0, v0
	v_fmac_f32_e32 v172, v250, v250
	v_lshlrev_b32_e32 v0, 16, v12
	v_and_b32_e32 v250, 0xffff0000, v12
	v_fmac_f32_e32 v172, v0, v0
	v_fmac_f32_e32 v172, v250, v250
	v_lshlrev_b32_e32 v0, 16, v13
	v_and_b32_e32 v250, 0xffff0000, v13
	v_fmac_f32_e32 v172, v0, v0
	v_fmac_f32_e32 v172, v250, v250
	v_lshlrev_b32_e32 v0, 16, v14
	v_and_b32_e32 v250, 0xffff0000, v14
	v_fmac_f32_e32 v172, v0, v0
	v_fmac_f32_e32 v172, v250, v250
	v_lshlrev_b32_e32 v0, 16, v15
	v_and_b32_e32 v250, 0xffff0000, v15
	v_fmac_f32_e32 v172, v0, v0
	v_fmac_f32_e32 v172, v250, v250
	v_lshlrev_b32_e32 v0, 16, v16
	v_and_b32_e32 v250, 0xffff0000, v16
	v_fmac_f32_e32 v172, v0, v0
	v_fmac_f32_e32 v172, v250, v250
	v_lshlrev_b32_e32 v0, 16, v17
	v_and_b32_e32 v250, 0xffff0000, v17
	v_fmac_f32_e32 v172, v0, v0
	v_fmac_f32_e32 v172, v250, v250
	v_mov_b32_e32 v251, v171
	v_mov_b32_e32 v170, v172
	s_nop 1
	v_permlane32_swap_b32_e32 v171, v251
	v_permlane32_swap_b32_e32 v172, v170
	v_add_f32_e32 v171, v171, v251
	v_add_f32_e32 v172, v172, v170
	ds_swizzle_b32 v251, v171 offset:0x401f
	ds_swizzle_b32 v170, v172 offset:0x401f
	s_waitcnt lgkmcnt(1)
	v_add_f32_e32 v171, v171, v251
	s_waitcnt lgkmcnt(0)
	v_add_f32_e32 v172, v172, v170
	ds_swizzle_b32 v251, v171 offset:0x201f
	ds_swizzle_b32 v170, v172 offset:0x201f
	s_waitcnt lgkmcnt(1)
	v_add_f32_e32 v171, v171, v251
	s_waitcnt lgkmcnt(0)
	v_add_f32_e32 v172, v172, v170
	ds_swizzle_b32 v251, v171 offset:0x101f
	ds_swizzle_b32 v170, v172 offset:0x101f
	s_waitcnt lgkmcnt(1)
	v_add_f32_e32 v171, v171, v251
	s_waitcnt lgkmcnt(0)
	v_add_f32_e32 v172, v172, v170
	ds_swizzle_b32 v251, v171 offset:0x81f
	ds_swizzle_b32 v170, v172 offset:0x81f
	s_waitcnt lgkmcnt(1)
	v_add_f32_e32 v171, v171, v251
	s_waitcnt lgkmcnt(0)
	v_add_f32_e32 v172, v172, v170
	ds_swizzle_b32 v251, v171 offset:0x41f
	ds_swizzle_b32 v170, v172 offset:0x41f
	s_waitcnt lgkmcnt(1)
	v_add_f32_e32 v171, v171, v251
	s_waitcnt lgkmcnt(0)
	v_add_f32_e32 v172, v172, v170
	v_fmamk_f32 v171, v171, 0x3a800000, v153
	v_fmamk_f32 v172, v172, 0x3a800000, v153
	v_rsq_f32_e32 v171, v171
	v_rsq_f32_e32 v172, v172
	s_nop 0
	s_add_u32 s28, s56, 0x4000000
	s_addc_u32 s29, s57, 0
	v_lshlrev_b32_e32 v0, 16, v2
	v_and_b32_e32 v250, 0xffff0000, v2
	v_mul_f32_e32 v0, v171, v0
	v_mul_f32_e32 v250, v171, v250
	v_fmac_f32_e32 v18, v50, v0
	v_fmac_f32_e32 v19, v51, v250
	v_lshlrev_b32_e32 v0, 16, v3
	v_and_b32_e32 v250, 0xffff0000, v3
	v_mul_f32_e32 v0, v171, v0
	v_mul_f32_e32 v250, v171, v250
	v_fmac_f32_e32 v20, v52, v0
	v_fmac_f32_e32 v21, v53, v250
	v_lshlrev_b32_e32 v0, 16, v4
	v_and_b32_e32 v250, 0xffff0000, v4
	v_mul_f32_e32 v0, v171, v0
	v_mul_f32_e32 v250, v171, v250
	v_fmac_f32_e32 v22, v54, v0
	v_fmac_f32_e32 v23, v55, v250
	v_lshlrev_b32_e32 v0, 16, v5
	v_and_b32_e32 v250, 0xffff0000, v5
	v_mul_f32_e32 v0, v171, v0
	v_mul_f32_e32 v250, v171, v250
	v_fmac_f32_e32 v24, v56, v0
	v_fmac_f32_e32 v25, v57, v250
	v_lshlrev_b32_e32 v0, 16, v6
	v_and_b32_e32 v250, 0xffff0000, v6
	v_mul_f32_e32 v0, v171, v0
	v_mul_f32_e32 v250, v171, v250
	v_fmac_f32_e32 v26, v58, v0
	v_fmac_f32_e32 v27, v59, v250
	v_lshlrev_b32_e32 v0, 16, v7
	v_and_b32_e32 v250, 0xffff0000, v7
	v_mul_f32_e32 v0, v171, v0
	v_mul_f32_e32 v250, v171, v250
	v_fmac_f32_e32 v28, v60, v0
	v_fmac_f32_e32 v29, v61, v250
	v_lshlrev_b32_e32 v0, 16, v8
	v_and_b32_e32 v250, 0xffff0000, v8
	v_mul_f32_e32 v0, v171, v0
	v_mul_f32_e32 v250, v171, v250
	v_fmac_f32_e32 v30, v62, v0
	v_fmac_f32_e32 v31, v63, v250
	v_lshlrev_b32_e32 v0, 16, v9
	v_and_b32_e32 v250, 0xffff0000, v9
	v_mul_f32_e32 v0, v171, v0
	v_mul_f32_e32 v250, v171, v250
	v_fmac_f32_e32 v32, v64, v0
	v_fmac_f32_e32 v33, v65, v250
	global_store_dwordx4 v173, v[18:21], s[28:29] offset:0
	global_store_dwordx4 v173, v[22:25], s[28:29] offset:16
	global_store_dwordx4 v173, v[26:29], s[28:29] offset:2048
	global_store_dwordx4 v173, v[30:33], s[28:29] offset:2064
	v_lshlrev_b32_e32 v0, 16, v10
	v_and_b32_e32 v250, 0xffff0000, v10
	v_mul_f32_e32 v0, v172, v0
	v_mul_f32_e32 v250, v172, v250
	v_fmac_f32_e32 v34, v50, v0
	v_fmac_f32_e32 v35, v51, v250
	v_lshlrev_b32_e32 v0, 16, v11
	v_and_b32_e32 v250, 0xffff0000, v11
	v_mul_f32_e32 v0, v172, v0
	v_mul_f32_e32 v250, v172, v250
	v_fmac_f32_e32 v36, v52, v0
	v_fmac_f32_e32 v37, v53, v250
	v_lshlrev_b32_e32 v0, 16, v12
	v_and_b32_e32 v250, 0xffff0000, v12
	v_mul_f32_e32 v0, v172, v0
	v_mul_f32_e32 v250, v172, v250
	v_fmac_f32_e32 v38, v54, v0
	v_fmac_f32_e32 v39, v55, v250
	v_lshlrev_b32_e32 v0, 16, v13
	v_and_b32_e32 v250, 0xffff0000, v13
	v_mul_f32_e32 v0, v172, v0
	v_mul_f32_e32 v250, v172, v250
	v_fmac_f32_e32 v40, v56, v0
	v_fmac_f32_e32 v41, v57, v250
	v_lshlrev_b32_e32 v0, 16, v14
	v_and_b32_e32 v250, 0xffff0000, v14
	v_mul_f32_e32 v0, v172, v0
	v_mul_f32_e32 v250, v172, v250
	v_fmac_f32_e32 v42, v58, v0
	v_fmac_f32_e32 v43, v59, v250
	v_lshlrev_b32_e32 v0, 16, v15
	v_and_b32_e32 v250, 0xffff0000, v15
	v_mul_f32_e32 v0, v172, v0
	v_mul_f32_e32 v250, v172, v250
	v_fmac_f32_e32 v44, v60, v0
	v_fmac_f32_e32 v45, v61, v250
	v_lshlrev_b32_e32 v0, 16, v16
	v_and_b32_e32 v250, 0xffff0000, v16
	v_mul_f32_e32 v0, v172, v0
	v_mul_f32_e32 v250, v172, v250
	v_fmac_f32_e32 v46, v62, v0
	v_fmac_f32_e32 v47, v63, v250
	v_lshlrev_b32_e32 v0, 16, v17
	v_and_b32_e32 v250, 0xffff0000, v17
	v_mul_f32_e32 v0, v172, v0
	v_mul_f32_e32 v250, v172, v250
	v_fmac_f32_e32 v48, v64, v0
	v_fmac_f32_e32 v49, v65, v250
	s_add_u32 s28, s28, 0x1000
	s_addc_u32 s29, s29, 0
	global_store_dwordx4 v173, v[34:37], s[28:29] offset:0
	global_store_dwordx4 v173, v[38:41], s[28:29] offset:16
	global_store_dwordx4 v173, v[42:45], s[28:29] offset:2048
	global_store_dwordx4 v173, v[46:49], s[28:29] offset:2064
	s_waitcnt vmcnt(0)
	v_mul_f32_e32 v114, v114, v130
	v_mul_f32_e32 v115, v115, v131
	v_mul_f32_e32 v116, v116, v132
	v_mul_f32_e32 v117, v117, v133
	v_mul_f32_e32 v118, v118, v134
	v_mul_f32_e32 v119, v119, v135
	v_mul_f32_e32 v120, v120, v136
	v_mul_f32_e32 v121, v121, v137
	v_mul_f32_e32 v122, v122, v138
	v_mul_f32_e32 v123, v123, v139
	v_mul_f32_e32 v124, v124, v140
	v_mul_f32_e32 v125, v125, v141
	v_mul_f32_e32 v126, v126, v142
	v_mul_f32_e32 v127, v127, v143
	v_mul_f32_e32 v128, v128, v144
	v_mul_f32_e32 v129, v129, v145
	v_lshlrev_b32_e32 v0, 16, v66
	v_and_b32_e32 v250, 0xffff0000, v66
	v_mul_f32_e32 v171, v0, v0
	v_fmac_f32_e32 v171, v250, v250
	v_lshlrev_b32_e32 v0, 16, v67
	v_and_b32_e32 v250, 0xffff0000, v67
	v_fmac_f32_e32 v171, v0, v0
	v_fmac_f32_e32 v171, v250, v250
	v_lshlrev_b32_e32 v0, 16, v68
	v_and_b32_e32 v250, 0xffff0000, v68
	v_fmac_f32_e32 v171, v0, v0
	v_fmac_f32_e32 v171, v250, v250
	v_lshlrev_b32_e32 v0, 16, v69
	v_and_b32_e32 v250, 0xffff0000, v69
	v_fmac_f32_e32 v171, v0, v0
	v_fmac_f32_e32 v171, v250, v250
	v_lshlrev_b32_e32 v0, 16, v70
	v_and_b32_e32 v250, 0xffff0000, v70
	v_fmac_f32_e32 v171, v0, v0
	v_fmac_f32_e32 v171, v250, v250
	v_lshlrev_b32_e32 v0, 16, v71
	v_and_b32_e32 v250, 0xffff0000, v71
	v_fmac_f32_e32 v171, v0, v0
	v_fmac_f32_e32 v171, v250, v250
	v_lshlrev_b32_e32 v0, 16, v72
	v_and_b32_e32 v250, 0xffff0000, v72
	v_fmac_f32_e32 v171, v0, v0
	v_fmac_f32_e32 v171, v250, v250
	v_lshlrev_b32_e32 v0, 16, v73
	v_and_b32_e32 v250, 0xffff0000, v73
	v_fmac_f32_e32 v171, v0, v0
	v_fmac_f32_e32 v171, v250, v250
	v_lshlrev_b32_e32 v0, 16, v74
	v_and_b32_e32 v250, 0xffff0000, v74
	v_mul_f32_e32 v172, v0, v0
	v_fmac_f32_e32 v172, v250, v250
	v_lshlrev_b32_e32 v0, 16, v75
	v_and_b32_e32 v250, 0xffff0000, v75
	v_fmac_f32_e32 v172, v0, v0
	v_fmac_f32_e32 v172, v250, v250
	v_lshlrev_b32_e32 v0, 16, v76
	v_and_b32_e32 v250, 0xffff0000, v76
	v_fmac_f32_e32 v172, v0, v0
	v_fmac_f32_e32 v172, v250, v250
	v_lshlrev_b32_e32 v0, 16, v77
	v_and_b32_e32 v250, 0xffff0000, v77
	v_fmac_f32_e32 v172, v0, v0
	v_fmac_f32_e32 v172, v250, v250
	v_lshlrev_b32_e32 v0, 16, v78
	v_and_b32_e32 v250, 0xffff0000, v78
	v_fmac_f32_e32 v172, v0, v0
	v_fmac_f32_e32 v172, v250, v250
	v_lshlrev_b32_e32 v0, 16, v79
	v_and_b32_e32 v250, 0xffff0000, v79
	v_fmac_f32_e32 v172, v0, v0
	v_fmac_f32_e32 v172, v250, v250
	v_lshlrev_b32_e32 v0, 16, v80
	v_and_b32_e32 v250, 0xffff0000, v80
	v_fmac_f32_e32 v172, v0, v0
	v_fmac_f32_e32 v172, v250, v250
	v_lshlrev_b32_e32 v0, 16, v81
	v_and_b32_e32 v250, 0xffff0000, v81
	v_fmac_f32_e32 v172, v0, v0
	v_fmac_f32_e32 v172, v250, v250
	v_mov_b32_e32 v251, v171
	v_mov_b32_e32 v170, v172
	s_nop 1
	v_permlane32_swap_b32_e32 v171, v251
	v_permlane32_swap_b32_e32 v172, v170
	v_add_f32_e32 v171, v171, v251
	v_add_f32_e32 v172, v172, v170
	ds_swizzle_b32 v251, v171 offset:0x401f
	ds_swizzle_b32 v170, v172 offset:0x401f
	s_waitcnt lgkmcnt(1)
	v_add_f32_e32 v171, v171, v251
	s_waitcnt lgkmcnt(0)
	v_add_f32_e32 v172, v172, v170
	ds_swizzle_b32 v251, v171 offset:0x201f
	ds_swizzle_b32 v170, v172 offset:0x201f
	s_waitcnt lgkmcnt(1)
	v_add_f32_e32 v171, v171, v251
	s_waitcnt lgkmcnt(0)
	v_add_f32_e32 v172, v172, v170
	ds_swizzle_b32 v251, v171 offset:0x101f
	ds_swizzle_b32 v170, v172 offset:0x101f
	s_waitcnt lgkmcnt(1)
	v_add_f32_e32 v171, v171, v251
	s_waitcnt lgkmcnt(0)
	v_add_f32_e32 v172, v172, v170
	ds_swizzle_b32 v251, v171 offset:0x81f
	ds_swizzle_b32 v170, v172 offset:0x81f
	s_waitcnt lgkmcnt(1)
	v_add_f32_e32 v171, v171, v251
	s_waitcnt lgkmcnt(0)
	v_add_f32_e32 v172, v172, v170
	ds_swizzle_b32 v251, v171 offset:0x41f
	ds_swizzle_b32 v170, v172 offset:0x41f
	s_waitcnt lgkmcnt(1)
	v_add_f32_e32 v171, v171, v251
	s_waitcnt lgkmcnt(0)
	v_add_f32_e32 v172, v172, v170
	v_fmamk_f32 v171, v171, 0x3a800000, v153
	v_fmamk_f32 v172, v172, 0x3a800000, v153
	v_rsq_f32_e32 v171, v171
	v_rsq_f32_e32 v172, v172
	s_nop 0
	s_add_u32 s28, s56, 0x5000000
	s_addc_u32 s29, s57, 0
	v_lshlrev_b32_e32 v0, 16, v66
	v_and_b32_e32 v250, 0xffff0000, v66
	v_mul_f32_e32 v0, v171, v0
	v_mul_f32_e32 v250, v171, v250
	v_fmac_f32_e32 v82, v114, v0
	v_fmac_f32_e32 v83, v115, v250
	v_lshlrev_b32_e32 v0, 16, v67
	v_and_b32_e32 v250, 0xffff0000, v67
	v_mul_f32_e32 v0, v171, v0
	v_mul_f32_e32 v250, v171, v250
	v_fmac_f32_e32 v84, v116, v0
	v_fmac_f32_e32 v85, v117, v250
	v_lshlrev_b32_e32 v0, 16, v68
	v_and_b32_e32 v250, 0xffff0000, v68
	v_mul_f32_e32 v0, v171, v0
	v_mul_f32_e32 v250, v171, v250
	v_fmac_f32_e32 v86, v118, v0
	v_fmac_f32_e32 v87, v119, v250
	v_lshlrev_b32_e32 v0, 16, v69
	v_and_b32_e32 v250, 0xffff0000, v69
	v_mul_f32_e32 v0, v171, v0
	v_mul_f32_e32 v250, v171, v250
	v_fmac_f32_e32 v88, v120, v0
	v_fmac_f32_e32 v89, v121, v250
	v_lshlrev_b32_e32 v0, 16, v70
	v_and_b32_e32 v250, 0xffff0000, v70
	v_mul_f32_e32 v0, v171, v0
	v_mul_f32_e32 v250, v171, v250
	v_fmac_f32_e32 v90, v122, v0
	v_fmac_f32_e32 v91, v123, v250
	v_lshlrev_b32_e32 v0, 16, v71
	v_and_b32_e32 v250, 0xffff0000, v71
	v_mul_f32_e32 v0, v171, v0
	v_mul_f32_e32 v250, v171, v250
	v_fmac_f32_e32 v92, v124, v0
	v_fmac_f32_e32 v93, v125, v250
	v_lshlrev_b32_e32 v0, 16, v72
	v_and_b32_e32 v250, 0xffff0000, v72
	v_mul_f32_e32 v0, v171, v0
	v_mul_f32_e32 v250, v171, v250
	v_fmac_f32_e32 v94, v126, v0
	v_fmac_f32_e32 v95, v127, v250
	v_lshlrev_b32_e32 v0, 16, v73
	v_and_b32_e32 v250, 0xffff0000, v73
	v_mul_f32_e32 v0, v171, v0
	v_mul_f32_e32 v250, v171, v250
	v_fmac_f32_e32 v96, v128, v0
	v_fmac_f32_e32 v97, v129, v250
	global_store_dwordx4 v173, v[82:85], s[28:29] offset:0
	global_store_dwordx4 v173, v[86:89], s[28:29] offset:16
	global_store_dwordx4 v173, v[90:93], s[28:29] offset:2048
	global_store_dwordx4 v173, v[94:97], s[28:29] offset:2064
	v_lshlrev_b32_e32 v0, 16, v74
	v_and_b32_e32 v250, 0xffff0000, v74
	v_mul_f32_e32 v0, v172, v0
	v_mul_f32_e32 v250, v172, v250
	v_fmac_f32_e32 v98, v114, v0
	v_fmac_f32_e32 v99, v115, v250
	v_lshlrev_b32_e32 v0, 16, v75
	v_and_b32_e32 v250, 0xffff0000, v75
	v_mul_f32_e32 v0, v172, v0
	v_mul_f32_e32 v250, v172, v250
	v_fmac_f32_e32 v100, v116, v0
	v_fmac_f32_e32 v101, v117, v250
	v_lshlrev_b32_e32 v0, 16, v76
	v_and_b32_e32 v250, 0xffff0000, v76
	v_mul_f32_e32 v0, v172, v0
	v_mul_f32_e32 v250, v172, v250
	v_fmac_f32_e32 v102, v118, v0
	v_fmac_f32_e32 v103, v119, v250
	v_lshlrev_b32_e32 v0, 16, v77
	v_and_b32_e32 v250, 0xffff0000, v77
	v_mul_f32_e32 v0, v172, v0
	v_mul_f32_e32 v250, v172, v250
	v_fmac_f32_e32 v104, v120, v0
	v_fmac_f32_e32 v105, v121, v250
	v_lshlrev_b32_e32 v0, 16, v78
	v_and_b32_e32 v250, 0xffff0000, v78
	v_mul_f32_e32 v0, v172, v0
	v_mul_f32_e32 v250, v172, v250
	v_fmac_f32_e32 v106, v122, v0
	v_fmac_f32_e32 v107, v123, v250
	v_lshlrev_b32_e32 v0, 16, v79
	v_and_b32_e32 v250, 0xffff0000, v79
	v_mul_f32_e32 v0, v172, v0
	v_mul_f32_e32 v250, v172, v250
	v_fmac_f32_e32 v108, v124, v0
	v_fmac_f32_e32 v109, v125, v250
	v_lshlrev_b32_e32 v0, 16, v80
	v_and_b32_e32 v250, 0xffff0000, v80
	v_mul_f32_e32 v0, v172, v0
	v_mul_f32_e32 v250, v172, v250
	v_fmac_f32_e32 v110, v126, v0
	v_fmac_f32_e32 v111, v127, v250
	v_lshlrev_b32_e32 v0, 16, v81
	v_and_b32_e32 v250, 0xffff0000, v81
	v_mul_f32_e32 v0, v172, v0
	v_mul_f32_e32 v250, v172, v250
	v_fmac_f32_e32 v112, v128, v0
	v_fmac_f32_e32 v113, v129, v250
	s_add_u32 s28, s28, 0x1000
	s_addc_u32 s29, s29, 0
	global_store_dwordx4 v173, v[98:101], s[28:29] offset:0
	global_store_dwordx4 v173, v[102:105], s[28:29] offset:16
	global_store_dwordx4 v173, v[106:109], s[28:29] offset:2048
	global_store_dwordx4 v173, v[110:113], s[28:29] offset:2064
	s_branch .LBB0_48
	s_cmp_lt_u32 s82, 4
	s_cselect_b64 s[40:41], -1, 0
	s_cmp_gt_u32 s82, 3
	s_cselect_b64 s[0:1], -1, 0
	s_lshl_b32 s28, s80, 10
	s_ashr_i32 s29, s28, 31
	v_readlane_b32 s5, v253, 2
	v_readlane_b32 s6, v252, 0
	s_branch .LBB0_40
